# hg_scan prefetch at loop top + GEMM K-step: double-buffered LDS fragment reads with counted lgkmcnt, LDS-DMA pieces interleaved between MFMAs
# speedup vs baseline: 1.6764x; 1.6764x over previous
; #define MFMA(a, b, c) __builtin_amdgcn_mfma_f32_32x32x16_bf16((a), (b), (c), 0, 0, 0)
; DI f32x16 zero16() { f32x16 z; for (int i = 0; i < 16; ++i) z[i] = 0.f; return z; }
;     ...
;   const int fP = r * 128, fsw = (r >> 1) & 7;
;   const int fA = wm * 8192 + fP, fB = 32768 + wn * 16384 + fP;
;   f32x16 acc[2][4];
; #pragma unroll
;   for (int i = 0; i < 2; ++i)
; #pragma unroll
;     for (int j = 0; j < 4; ++j) acc[i][j] = zero16();
;   __syncthreads();
;   G_DMA(0, 0);
;   asm volatile("s_waitcnt vmcnt(0)" ::: "memory");
;   asm volatile("s_waitcnt lgkmcnt(0)" ::: "memory"); __builtin_amdgcn_s_barrier(); asm volatile("" ::: "memory");
;   int cur = 0;
;   for (int s = 0; s < S; ++s) {
;     G_DMA(s + 1, cur ^ BUFB);
;     {
;       const char* Ab = smem + cur + fA;
;       const char* Bb = smem + cur + fB;
;       __builtin_amdgcn_sched_barrier(0);
; #pragma unroll
;       for (int kk = 0; kk < 4; ++kk) {
;         const int ko = (((kk * 2 + hh) ^ fsw) << 4);
;         bf16x8 af[2], wf[4];
;         af[0] = *(const bf16x8*)(Ab + ko); af[1] = *(const bf16x8*)(Ab + 4096 + ko);
; #pragma unroll
;         for (int ni = 0; ni < 4; ++ni) wf[ni] = *(const bf16x8*)(Bb + ni * 4096 + ko);
; #pragma unroll
;         for (int mi = 0; mi < 2; ++mi)
; #pragma unroll
;           for (int ni = 0; ni < 4; ++ni) acc[mi][ni] = MFMA(wf[ni], af[mi], acc[mi][ni]);
;         if (kk == 1) __builtin_amdgcn_sched_barrier(0);
;       }
;       __builtin_amdgcn_sched_barrier(0);
;     }
;     asm volatile("s_waitcnt vmcnt(0)" ::: "memory");
.LBB0_211:
	s_lshl_b32 s9, s7, 16
	s_and_b32 s9, s9, 0x200000
	s_add_i32 s9, s93, s9
	s_lshl_b32 s9, s9, 1
	s_and_b32 s28, s9, 0x700000
	s_xor_b32 s9, s8, 0x10000
	v_add_u32_e32 v128, s9, v150
	v_lshl_add_u64 v[160:161], v[136:137], 0, s[40:41]
	v_readfirstlane_b32 s22, v128
	v_add_u32_e32 v164, 0x2000, v128
	v_lshl_add_u64 v[162:163], v[160:161], 0, s[24:25]
	s_mov_b32 m0, s22
	v_readfirstlane_b32 s22, v164
	v_add_u32_e32 v164, 0x4000, v128
	global_load_lds_dwordx4 v[162:163], off
	v_add3_u32 v244, s8, v144, v147
	v_add3_u32 v245, s8, v149, v147
	v_add_u32_e32 v187, v245, v148
	v_add_u32_e32 v208, v244, v148
	ds_read_b128 v[188:191], v187 offset:32768
	ds_read_b128 v[204:207], v208
	ds_read_b128 v[192:195], v187 offset:36864
	ds_read_b128 v[196:199], v187 offset:40960
	ds_read_b128 v[200:203], v187 offset:45056
	ds_read_b128 v[216:219], v208 offset:4096
	v_add_u32_e32 v209, v245, v145
	v_add_u32_e32 v215, v244, v145
	ds_read_b128 v[220:223], v209 offset:32768
	ds_read_b128 v[236:239], v215
	ds_read_b128 v[224:227], v209 offset:36864
	ds_read_b128 v[228:231], v209 offset:40960
	ds_read_b128 v[232:235], v209 offset:45056
	ds_read_b128 v[240:243], v215 offset:4096
	s_waitcnt lgkmcnt(10)
	v_mfma_f32_32x32x16_bf16 v[112:127], v[188:191], v[204:207], v[112:127]
	s_waitcnt lgkmcnt(9)
	v_mfma_f32_32x32x16_bf16 v[96:111], v[192:195], v[204:207], v[96:111]
	v_lshl_add_u64 v[162:163], v[160:161], 0, s[42:43]
	s_mov_b32 m0, s22
	v_readfirstlane_b32 s22, v164
	global_load_lds_dwordx4 v[162:163], off
	s_waitcnt lgkmcnt(8)
	v_mfma_f32_32x32x16_bf16 v[80:95], v[196:199], v[204:207], v[80:95]
	s_waitcnt lgkmcnt(7)
	v_mfma_f32_32x32x16_bf16 v[64:79], v[200:203], v[204:207], v[64:79]
	v_lshl_add_u64 v[162:163], v[160:161], 0, s[44:45]
	s_mov_b32 m0, s22
	v_lshl_add_u64 v[158:159], v[138:139], 0, s[28:29]
	global_load_lds_dwordx4 v[162:163], off
	s_waitcnt lgkmcnt(6)
	v_mfma_f32_32x32x16_bf16 v[48:63], v[188:191], v[216:219], v[48:63]
	v_mfma_f32_32x32x16_bf16 v[32:47], v[192:195], v[216:219], v[32:47]
	v_add_u32_e32 v162, 0x6000, v128
	v_lshl_add_u64 v[160:161], v[160:161], 0, s[46:47]
	v_readfirstlane_b32 s22, v162
	v_add_u32_e32 v162, 0x8000, v128
	s_mov_b32 m0, s22
	v_lshl_add_u64 v[158:159], v[158:159], 0, s[40:41]
	v_readfirstlane_b32 s22, v162
	v_add_u32_e32 v162, 0xa000, v128
	global_load_lds_dwordx4 v[160:161], off
	v_mfma_f32_32x32x16_bf16 v[16:31], v[196:199], v[216:219], v[16:31]
	v_mfma_f32_32x32x16_bf16 v[0:15], v[200:203], v[216:219], v[0:15]
	v_lshl_add_u64 v[160:161], v[158:159], 0, s[48:49]
	s_mov_b32 m0, s22
	v_readfirstlane_b32 s22, v162
	v_add_u32_e32 v162, 0xc000, v128
	global_load_lds_dwordx4 v[160:161], off
	v_add_u32_e32 v187, v245, v141
	v_add_u32_e32 v208, v244, v141
	ds_read_b128 v[188:191], v187 offset:32768
	ds_read_b128 v[204:207], v208
	ds_read_b128 v[192:195], v187 offset:36864
	ds_read_b128 v[196:199], v187 offset:40960
	ds_read_b128 v[200:203], v187 offset:45056
	ds_read_b128 v[216:219], v208 offset:4096
	s_waitcnt lgkmcnt(10)
	v_mfma_f32_32x32x16_bf16 v[112:127], v[220:223], v[236:239], v[112:127]
	s_waitcnt lgkmcnt(9)
	v_mfma_f32_32x32x16_bf16 v[96:111], v[224:227], v[236:239], v[96:111]
	v_lshl_add_u64 v[160:161], v[158:159], 0, s[50:51]
	s_mov_b32 m0, s22
	v_readfirstlane_b32 s22, v162
	v_add_u32_e32 v128, 0xe000, v128
	global_load_lds_dwordx4 v[160:161], off
	s_waitcnt lgkmcnt(8)
	v_mfma_f32_32x32x16_bf16 v[80:95], v[228:231], v[236:239], v[80:95]
	s_waitcnt lgkmcnt(7)
	v_mfma_f32_32x32x16_bf16 v[64:79], v[232:235], v[236:239], v[64:79]
	v_lshl_add_u64 v[160:161], v[158:159], 0, s[52:53]
	s_mov_b32 m0, s22
	v_readfirstlane_b32 s22, v128
	global_load_lds_dwordx4 v[160:161], off
	s_waitcnt lgkmcnt(6)
	v_mfma_f32_32x32x16_bf16 v[48:63], v[220:223], v[240:243], v[48:63]
	v_mfma_f32_32x32x16_bf16 v[32:47], v[224:227], v[240:243], v[32:47]
	v_lshl_add_u64 v[158:159], v[158:159], 0, s[54:55]
	s_mov_b32 m0, s22
	s_add_i32 s8, s8, 0
	global_load_lds_dwordx4 v[158:159], off
	v_mfma_f32_32x32x16_bf16 v[16:31], v[228:231], v[240:243], v[16:31]
	v_mfma_f32_32x32x16_bf16 v[0:15], v[232:235], v[240:243], v[0:15]
	v_add_u32_e32 v209, v245, v140
	v_add_u32_e32 v215, v244, v140
	ds_read_b128 v[220:223], v209 offset:32768
	ds_read_b128 v[236:239], v215
	ds_read_b128 v[224:227], v209 offset:36864
	ds_read_b128 v[228:231], v209 offset:40960
	ds_read_b128 v[232:235], v209 offset:45056
	ds_read_b128 v[240:243], v215 offset:4096
	s_waitcnt lgkmcnt(10)
	v_mfma_f32_32x32x16_bf16 v[112:127], v[188:191], v[204:207], v[112:127]
	s_waitcnt lgkmcnt(9)
	v_mfma_f32_32x32x16_bf16 v[96:111], v[192:195], v[204:207], v[96:111]
	s_waitcnt lgkmcnt(8)
	v_mfma_f32_32x32x16_bf16 v[80:95], v[196:199], v[204:207], v[80:95]
	s_waitcnt lgkmcnt(7)
	v_mfma_f32_32x32x16_bf16 v[64:79], v[200:203], v[204:207], v[64:79]
	s_waitcnt lgkmcnt(6)
	v_mfma_f32_32x32x16_bf16 v[48:63], v[188:191], v[216:219], v[48:63]
	v_mfma_f32_32x32x16_bf16 v[32:47], v[192:195], v[216:219], v[32:47]
	v_mfma_f32_32x32x16_bf16 v[16:31], v[196:199], v[216:219], v[16:31]
	v_mfma_f32_32x32x16_bf16 v[0:15], v[200:203], v[216:219], v[0:15]
	s_waitcnt lgkmcnt(4)
	v_mfma_f32_32x32x16_bf16 v[112:127], v[220:223], v[236:239], v[112:127]
	s_waitcnt lgkmcnt(3)
	v_mfma_f32_32x32x16_bf16 v[96:111], v[224:227], v[236:239], v[96:111]
	s_waitcnt lgkmcnt(2)
	v_mfma_f32_32x32x16_bf16 v[80:95], v[228:231], v[236:239], v[80:95]
	s_waitcnt lgkmcnt(1)
	v_mfma_f32_32x32x16_bf16 v[64:79], v[232:235], v[236:239], v[64:79]
	s_waitcnt lgkmcnt(0)
	v_mfma_f32_32x32x16_bf16 v[48:63], v[220:223], v[240:243], v[48:63]
	v_mfma_f32_32x32x16_bf16 v[32:47], v[224:227], v[240:243], v[32:47]
	v_mfma_f32_32x32x16_bf16 v[16:31], v[228:231], v[240:243], v[16:31]
	v_mfma_f32_32x32x16_bf16 v[0:15], v[232:235], v[240:243], v[0:15]
	s_waitcnt vmcnt(0)
	s_waitcnt lgkmcnt(0)
	s_barrier
; #define MFMA(a, b, c) __builtin_amdgcn_mfma_f32_32x32x16_bf16((a), (b), (c), 0, 0, 0)
;     ...
;   for (int s = 0; s < S; ++s) {
;     G_DMA(s + 1, cur ^ BUFB);
;     {
;       const char* Ab = smem + cur + fA;
;       const char* Bb = smem + cur + fB;
;       __builtin_amdgcn_sched_barrier(0);
; #pragma unroll
;       for (int kk = 0; kk < 4; ++kk) {
;         const int ko = (((kk * 2 + hh) ^ fsw) << 4);
;         bf16x8 af[2], wf[4];
;         af[0] = *(const bf16x8*)(Ab + ko); af[1] = *(const bf16x8*)(Ab + 4096 + ko);
; #pragma unroll
;         for (int ni = 0; ni < 4; ++ni) wf[ni] = *(const bf16x8*)(Bb + ni * 4096 + ko);
; #pragma unroll
;         for (int mi = 0; mi < 2; ++mi)
; #pragma unroll
;           for (int ni = 0; ni < 4; ++ni) acc[mi][ni] = MFMA(wf[ni], af[mi], acc[mi][ni]);
;         if (kk == 1) __builtin_amdgcn_sched_barrier(0);
;       }
;       __builtin_amdgcn_sched_barrier(0);
;     }
;     asm volatile("s_waitcnt vmcnt(0)" ::: "memory");
;     if ((s & (nk - 1)) == nk - 1) {
;       const int q = slot + (s >> lnk) * nslots;
	s_add_u32 s40, s40, 0x80
	s_addc_u32 s41, s41, 0
	s_add_i32 s7, s7, 1
	s_cmpk_eq_i32 s40, 0xf80
	s_mov_b32 s8, s9
	s_cbranch_scc0 .LBB0_211
	s_mov_b64 s[8:9], 0xf80
	v_readfirstlane_b32 s7, v150
	v_lshl_add_u64 v[136:137], v[132:133], 0, s[8:9]
	s_mov_b32 m0, s7
	s_mov_b64 s[22:23], 0x40f80
	v_readfirstlane_b32 s7, v151
	global_load_lds_dwordx4 v[136:137], off
	v_lshl_add_u64 v[136:137], v[132:133], 0, s[22:23]
	s_mov_b32 m0, s7
	s_mov_b64 s[24:25], 0x80f80
	v_readfirstlane_b32 s7, v152
	global_load_lds_dwordx4 v[136:137], off
	v_lshl_add_u64 v[136:137], v[132:133], 0, s[24:25]
	s_mov_b32 m0, s7
	s_mov_b64 s[40:41], 0xc0f80
	v_readfirstlane_b32 s7, v153
	global_load_lds_dwordx4 v[136:137], off
	v_lshl_add_u64 v[132:133], v[132:133], 0, s[40:41]
	s_mov_b32 m0, s7
	v_readfirstlane_b32 s7, v154
	global_load_lds_dwordx4 v[132:133], off
	v_lshl_add_u64 v[132:133], v[134:135], 0, s[8:9]
	s_mov_b32 m0, s7
	v_readfirstlane_b32 s7, v155
	global_load_lds_dwordx4 v[132:133], off
	v_lshl_add_u64 v[132:133], v[134:135], 0, s[22:23]
	s_mov_b32 m0, s7
	v_readfirstlane_b32 s7, v156
	global_load_lds_dwordx4 v[132:133], off
	v_lshl_add_u64 v[132:133], v[134:135], 0, s[24:25]
	s_mov_b32 m0, s7
	v_readfirstlane_b32 s7, v157
	global_load_lds_dwordx4 v[132:133], off
	v_lshl_add_u64 v[132:133], v[134:135], 0, s[40:41]
	s_mov_b32 m0, s7
	s_add_i32 s28, s6, -1
	global_load_lds_dwordx4 v[132:133], off
	s_lshl_b64 s[8:9], s[28:29], 25
	v_readlane_b32 s22, v253, 39
	v_readlane_b32 s23, v253, 40
	s_add_u32 s40, s22, s8
	v_lshlrev_b32_e32 v132, 6, v146
	s_addc_u32 s41, s23, s9
	v_readlane_b32 s8, v253, 27
	v_ashrrev_i32_e32 v133, 31, v132
	v_readlane_b32 s9, v253, 28
	s_add_i32 s7, 0, 0x10000
	v_lshlrev_b32_e32 v128, 3, v142
	v_lshl_add_u64 v[162:163], v[132:133], 0, s[8:9]
	v_lshlrev_b32_e32 v132, 4, v142
	v_mov_b32_e32 v133, v129
	v_or_b32_e32 v162, v162, v143
	v_lshl_add_u64 v[132:133], s[40:41], 0, v[132:133]
	v_add3_u32 v138, s7, v144, v147
	v_add3_u32 v139, s7, v149, v147
	v_add_u32_e32 v187, v139, v148
	v_add_u32_e32 v208, v138, v148
	ds_read_b128 v[134:137], v187 offset:32768
	ds_read_b128 v[146:149], v208
	ds_read_b128 v[150:153], v187 offset:36864
	ds_read_b128 v[154:157], v187 offset:40960
	ds_read_b128 v[158:161], v187 offset:45056
	ds_read_b128 v[188:191], v208 offset:4096
	v_add_u32_e32 v209, v139, v145
	v_add_u32_e32 v215, v138, v145
	ds_read_b128 v[192:195], v209 offset:32768
	ds_read_b128 v[216:219], v215
	ds_read_b128 v[196:199], v209 offset:36864
	ds_read_b128 v[200:203], v209 offset:40960
	ds_read_b128 v[204:207], v209 offset:45056
	ds_read_b128 v[220:223], v215 offset:4096
	s_waitcnt lgkmcnt(10)
	v_mfma_f32_32x32x16_bf16 v[112:127], v[134:137], v[146:149], v[112:127]
	s_waitcnt lgkmcnt(9)
	v_mfma_f32_32x32x16_bf16 v[96:111], v[150:153], v[146:149], v[96:111]
	s_waitcnt lgkmcnt(8)
	v_mfma_f32_32x32x16_bf16 v[80:95], v[154:157], v[146:149], v[80:95]
	s_waitcnt lgkmcnt(7)
	v_mfma_f32_32x32x16_bf16 v[64:79], v[158:161], v[146:149], v[64:79]
	s_waitcnt lgkmcnt(6)
	v_mfma_f32_32x32x16_bf16 v[48:63], v[134:137], v[188:191], v[48:63]
	v_mfma_f32_32x32x16_bf16 v[32:47], v[150:153], v[188:191], v[32:47]
	v_mfma_f32_32x32x16_bf16 v[16:31], v[154:157], v[188:191], v[16:31]
	v_mfma_f32_32x32x16_bf16 v[0:15], v[158:161], v[188:191], v[0:15]
	v_add_u32_e32 v187, v139, v141
	v_add_u32_e32 v208, v138, v141
	ds_read_b128 v[134:137], v187 offset:32768
	ds_read_b128 v[146:149], v208
	ds_read_b128 v[150:153], v187 offset:36864
	ds_read_b128 v[154:157], v187 offset:40960
	ds_read_b128 v[158:161], v187 offset:45056
	ds_read_b128 v[188:191], v208 offset:4096
	s_waitcnt lgkmcnt(10)
	v_mfma_f32_32x32x16_bf16 v[112:127], v[192:195], v[216:219], v[112:127]
	s_waitcnt lgkmcnt(9)
	v_mfma_f32_32x32x16_bf16 v[96:111], v[196:199], v[216:219], v[96:111]
	s_waitcnt lgkmcnt(8)
	v_mfma_f32_32x32x16_bf16 v[80:95], v[200:203], v[216:219], v[80:95]
	s_waitcnt lgkmcnt(7)
	v_mfma_f32_32x32x16_bf16 v[64:79], v[204:207], v[216:219], v[64:79]
	s_waitcnt lgkmcnt(6)
	v_mfma_f32_32x32x16_bf16 v[48:63], v[192:195], v[220:223], v[48:63]
	v_mfma_f32_32x32x16_bf16 v[32:47], v[196:199], v[220:223], v[32:47]
	v_mfma_f32_32x32x16_bf16 v[16:31], v[200:203], v[220:223], v[16:31]
	v_mfma_f32_32x32x16_bf16 v[0:15], v[204:207], v[220:223], v[0:15]
	v_add_u32_e32 v209, v139, v140
	v_add_u32_e32 v215, v138, v140
	ds_read_b128 v[192:195], v209 offset:32768
	ds_read_b128 v[216:219], v215
	ds_read_b128 v[196:199], v209 offset:36864
	ds_read_b128 v[200:203], v209 offset:40960
	ds_read_b128 v[204:207], v209 offset:45056
	ds_read_b128 v[220:223], v215 offset:4096
	s_waitcnt lgkmcnt(10)
	v_mfma_f32_32x32x16_bf16 v[112:127], v[134:137], v[146:149], v[112:127]
	s_waitcnt lgkmcnt(9)
	v_mfma_f32_32x32x16_bf16 v[96:111], v[150:153], v[146:149], v[96:111]
	s_waitcnt lgkmcnt(8)
	v_mfma_f32_32x32x16_bf16 v[80:95], v[154:157], v[146:149], v[80:95]
	s_waitcnt lgkmcnt(7)
	v_mfma_f32_32x32x16_bf16 v[64:79], v[158:161], v[146:149], v[64:79]
	s_waitcnt lgkmcnt(6)
	v_mfma_f32_32x32x16_bf16 v[48:63], v[134:137], v[188:191], v[48:63]
	v_mfma_f32_32x32x16_bf16 v[32:47], v[150:153], v[188:191], v[32:47]
	v_mfma_f32_32x32x16_bf16 v[16:31], v[154:157], v[188:191], v[16:31]
	v_mfma_f32_32x32x16_bf16 v[0:15], v[158:161], v[188:191], v[0:15]
	s_waitcnt lgkmcnt(4)
	v_mfma_f32_32x32x16_bf16 v[112:127], v[192:195], v[216:219], v[112:127]
	s_waitcnt lgkmcnt(3)
	v_mfma_f32_32x32x16_bf16 v[96:111], v[196:199], v[216:219], v[96:111]
	s_waitcnt lgkmcnt(2)
	v_mfma_f32_32x32x16_bf16 v[80:95], v[200:203], v[216:219], v[80:95]
	s_waitcnt lgkmcnt(1)
	v_mfma_f32_32x32x16_bf16 v[64:79], v[204:207], v[216:219], v[64:79]
	s_waitcnt lgkmcnt(0)
;     ...
;     asm volatile("s_waitcnt vmcnt(0)" ::: "memory");
;     if ((s & (nk - 1)) == nk - 1) {
;       const int q = slot + (s >> lnk) * nslots;
;       int mt, nt; G_TILEMAP(q, mt, nt);
;       if (dostore) {
; #pragma unroll
;         for (int mi = 0; mi < 2; ++mi) {
;           const size_t m = (size_t)mt * 256 + wm * 64 + mi * 32 + r;
; #pragma unroll
;           for (int ni = 0; ni < 4; ++ni) {
;             __builtin_amdgcn_sched_barrier(0);
;             if (MODE == 0) {
; #pragma unroll
;               for (int gp = 0; gp < 2; ++gp) {
;                 const int g0 = 2 * gp;
;                 uint2 pa, pb;
;                 pa.x = pack2(acc[mi][ni][4 * g0], acc[mi][ni][4 * g0 + 1]); pa.y = pack2(acc[mi][ni][4 * g0 + 2], acc[mi][ni][4 * g0 + 3]);
;                 pb.x = pack2(acc[mi][ni][4 * g0 + 4], acc[mi][ni][4 * g0 + 5]); pb.y = pack2(acc[mi][ni][4 * g0 + 6], acc[mi][ni][4 * g0 + 7]);
;                 { auto rx = __builtin_amdgcn_permlane32_swap(pa.x, pb.x, false, false); pa.x = rx[0]; pb.x = rx[1]; }
;                 { auto ry = __builtin_amdgcn_permlane32_swap(pa.y, pb.y, false, false); pa.y = ry[0]; pb.y = ry[1]; }
;                 const int col = nt * 256 + wn * 128 + ni * 32 + 8 * g0 + 8 * hh;
;                 const uint4 v4 = make_uint4(pa.x, pa.y, pb.x, pb.y);
;                 if (outp != nullptr && nt >= 32) *(uint4*)(outp + m * 2048 + (col - 8192)) = v4;
;                 else if (col < nvalid) *(uint4*)(C + m * ldc + col) = v4;
;               }
;             } else if (MODE == 1) {
; #pragma unroll
;               for (int gp = 0; gp < 2; ++gp) {
;                 const int g0 = 2 * gp;
;                 const int nb_ = nt * 256 + wn * 128 + ni * 32 + 8 * g0;
;                 const uint2 ra = *(const uint2*)(res + m * 1024 + nb_ + 4 * hh), rb = *(const uint2*)(res + m * 1024 + nb_ + 8 + 4 * hh);
;                 uint2 pa, pb;
;                 pa.x = pack2(alpha * lo2f(ra.x) + acc[mi][ni][4 * g0], alpha * hi2f(ra.x) + acc[mi][ni][4 * g0 + 1]);
;                 pa.y = pack2(alpha * lo2f(ra.y) + acc[mi][ni][4 * g0 + 2], alpha * hi2f(ra.y) + acc[mi][ni][4 * g0 + 3]);
;                 pb.x = pack2(alpha * lo2f(rb.x) + acc[mi][ni][4 * g0 + 4], alpha * hi2f(rb.x) + acc[mi][ni][4 * g0 + 5]);
;                 pb.y = pack2(alpha * lo2f(rb.y) + acc[mi][ni][4 * g0 + 6], alpha * hi2f(rb.y) + acc[mi][ni][4 * g0 + 7]);
	v_mfma_f32_32x32x16_bf16 v[48:63], v[192:195], v[220:223], v[48:63]
	v_mfma_f32_32x32x16_bf16 v[32:47], v[196:199], v[220:223], v[32:47]
	v_mfma_f32_32x32x16_bf16 v[16:31], v[200:203], v[220:223], v[16:31]
	v_mfma_f32_32x32x16_bf16 v[0:15], v[204:207], v[220:223], v[0:15]
	s_waitcnt vmcnt(0)
	v_lshlrev_b64 v[136:137], 11, v[162:163]
	v_lshl_add_u64 v[138:139], s[40:41], 0, v[136:137]
	v_lshl_add_u64 v[144:145], v[132:133], 0, v[136:137]
	v_readlane_b32 s7, v251, 32
	s_lshl_b32 s7, s7, 1
	v_mov_b32_e32 v135, v129
	v_lshl_or_b32 v134, v131, 8, s7
	v_lshl_add_u64 v[138:139], v[138:139], 0, v[134:135]
	v_lshl_add_u64 v[138:139], v[138:139], 0, v[128:129]
	global_load_dwordx2 v[140:141], v[138:139], off
	global_load_dwordx2 v[142:143], v[138:139], off offset:16
	s_mov_b32 s8, 0x3fd744fd
	s_waitcnt vmcnt(0)
	v_lshlrev_b32_e32 v146, 16, v140
	v_and_b32_e32 v147, 0xffff0000, v140
	v_pk_fma_f32 v[112:113], v[146:147], s[8:9], v[112:113] op_sel_hi:[1,0,1]
	s_nop 0
	v_cvt_pk_bf16_f32 v140, v112, v113
	v_lshlrev_b32_e32 v112, 16, v141
	v_and_b32_e32 v113, 0xffff0000, v141
	v_pk_fma_f32 v[112:113], v[112:113], s[8:9], v[114:115] op_sel_hi:[1,0,1]
	s_nop 0
	v_cvt_pk_bf16_f32 v141, v112, v113
	v_lshlrev_b32_e32 v112, 16, v142
	v_and_b32_e32 v113, 0xffff0000, v142
	v_pk_fma_f32 v[112:113], v[112:113], s[8:9], v[116:117] op_sel_hi:[1,0,1]
	s_nop 0
	v_cvt_pk_bf16_f32 v142, v112, v113
	v_lshlrev_b32_e32 v112, 16, v143
	v_and_b32_e32 v113, 0xffff0000, v143
	v_pk_fma_f32 v[112:113], v[112:113], s[8:9], v[118:119] op_sel_hi:[1,0,1]
	v_permlane32_swap_b32_e32 v140, v142
	v_cvt_pk_bf16_f32 v143, v112, v113
	s_nop 1
	v_permlane32_swap_b32_e32 v141, v143
	v_lshl_add_u64 v[112:113], v[144:145], 0, v[134:135]
	global_store_dwordx4 v[112:113], v[140:143], off
	global_load_dwordx2 v[114:115], v[138:139], off offset:32
	global_load_dwordx2 v[116:117], v[138:139], off offset:48
	s_waitcnt vmcnt(1)
	v_lshlrev_b32_e32 v118, 16, v114
	v_and_b32_e32 v119, 0xffff0000, v114
	v_pk_fma_f32 v[118:119], v[118:119], s[8:9], v[120:121] op_sel_hi:[1,0,1]
	s_nop 0
	v_cvt_pk_bf16_f32 v114, v118, v119
	v_lshlrev_b32_e32 v118, 16, v115
	v_and_b32_e32 v119, 0xffff0000, v115
	v_pk_fma_f32 v[118:119], v[118:119], s[8:9], v[122:123] op_sel_hi:[1,0,1]
	s_nop 0
	v_cvt_pk_bf16_f32 v115, v118, v119
	s_waitcnt vmcnt(0)
	v_lshlrev_b32_e32 v118, 16, v116
	v_and_b32_e32 v119, 0xffff0000, v116
	v_pk_fma_f32 v[118:119], v[118:119], s[8:9], v[124:125] op_sel_hi:[1,0,1]
	s_nop 0
	v_cvt_pk_bf16_f32 v116, v118, v119
	v_lshlrev_b32_e32 v118, 16, v117
	v_and_b32_e32 v119, 0xffff0000, v117
	v_pk_fma_f32 v[118:119], v[118:119], s[8:9], v[126:127] op_sel_hi:[1,0,1]
	v_permlane32_swap_b32_e32 v114, v116
	v_cvt_pk_bf16_f32 v117, v118, v119
	s_nop 1
	v_permlane32_swap_b32_e32 v115, v117
	global_store_dwordx4 v[112:113], v[114:117], off offset:32
	global_load_dwordx2 v[114:115], v[138:139], off offset:64
	s_nop 0
	global_load_dwordx2 v[116:117], v[138:139], off offset:80
	s_waitcnt vmcnt(1)
	v_lshlrev_b32_e32 v118, 16, v114
	v_and_b32_e32 v119, 0xffff0000, v114
	v_lshlrev_b32_e32 v114, 16, v115
	v_and_b32_e32 v115, 0xffff0000, v115
	v_pk_fma_f32 v[96:97], v[118:119], s[8:9], v[96:97] op_sel_hi:[1,0,1]
	v_pk_fma_f32 v[98:99], v[114:115], s[8:9], v[98:99] op_sel_hi:[1,0,1]
	v_cvt_pk_bf16_f32 v96, v96, v97
	v_cvt_pk_bf16_f32 v97, v98, v99
	s_waitcnt vmcnt(0)
	v_lshlrev_b32_e32 v98, 16, v116
	v_and_b32_e32 v99, 0xffff0000, v116
	v_pk_fma_f32 v[98:99], v[98:99], s[8:9], v[100:101] op_sel_hi:[1,0,1]
	v_lshlrev_b32_e32 v100, 16, v117
	v_and_b32_e32 v101, 0xffff0000, v117
	v_pk_fma_f32 v[100:101], v[100:101], s[8:9], v[102:103] op_sel_hi:[1,0,1]
	v_cvt_pk_bf16_f32 v98, v98, v99
	v_cvt_pk_bf16_f32 v99, v100, v101
	s_nop 0
	v_permlane32_swap_b32_e32 v96, v98
	v_permlane32_swap_b32_e32 v97, v99
	global_store_dwordx4 v[112:113], v[96:99], off offset:64
	global_load_dwordx2 v[96:97], v[138:139], off offset:96
	s_nop 0
	global_load_dwordx2 v[98:99], v[138:139], off offset:112
	s_waitcnt vmcnt(1)
	v_lshlrev_b32_e32 v100, 16, v96
	v_and_b32_e32 v101, 0xffff0000, v96
	v_pk_fma_f32 v[100:101], v[100:101], s[8:9], v[104:105] op_sel_hi:[1,0,1]
	s_nop 0
	v_cvt_pk_bf16_f32 v96, v100, v101
	v_lshlrev_b32_e32 v100, 16, v97
	v_and_b32_e32 v101, 0xffff0000, v97
	v_pk_fma_f32 v[100:101], v[100:101], s[8:9], v[106:107] op_sel_hi:[1,0,1]
	s_nop 0
	v_cvt_pk_bf16_f32 v97, v100, v101
	s_waitcnt vmcnt(0)
	v_lshlrev_b32_e32 v100, 16, v98
	v_and_b32_e32 v101, 0xffff0000, v98
	v_pk_fma_f32 v[100:101], v[100:101], s[8:9], v[108:109] op_sel_hi:[1,0,1]
	s_nop 0
	v_cvt_pk_bf16_f32 v98, v100, v101
	v_lshlrev_b32_e32 v100, 16, v99
	v_and_b32_e32 v101, 0xffff0000, v99
	v_pk_fma_f32 v[100:101], v[100:101], s[8:9], v[110:111] op_sel_hi:[1,0,1]
	v_permlane32_swap_b32_e32 v96, v98
	v_cvt_pk_bf16_f32 v99, v100, v101
	s_nop 1
	v_permlane32_swap_b32_e32 v97, v99
	global_store_dwordx4 v[112:113], v[96:99], off offset:96
	global_load_dwordx2 v[96:97], v[138:139], off offset:128
	s_nop 0
	global_load_dwordx2 v[98:99], v[138:139], off offset:144
	s_waitcnt vmcnt(1)
	v_lshlrev_b32_e32 v100, 16, v96
	v_and_b32_e32 v101, 0xffff0000, v96
	v_lshlrev_b32_e32 v96, 16, v97
	v_and_b32_e32 v97, 0xffff0000, v97
	v_pk_fma_f32 v[80:81], v[100:101], s[8:9], v[80:81] op_sel_hi:[1,0,1]
	v_pk_fma_f32 v[82:83], v[96:97], s[8:9], v[82:83] op_sel_hi:[1,0,1]
	v_cvt_pk_bf16_f32 v80, v80, v81
	v_cvt_pk_bf16_f32 v81, v82, v83
	s_waitcnt vmcnt(0)
; DI unsigned pack2(float a, float b) { f32x2_t v = {a, b}; return __builtin_bit_cast(unsigned, __builtin_convertvector(v, bf16x2_t)); }
; DI float lo2f(unsigned v) { return __uint_as_float(v << 16); }
; DI float hi2f(unsigned v) { return __uint_as_float(v & 0xffff0000u); }
;     ...
;             } else if (MODE == 1) {
; #pragma unroll
;               for (int gp = 0; gp < 2; ++gp) {
;                 const int g0 = 2 * gp;
;                 const int nb_ = nt * 256 + wn * 128 + ni * 32 + 8 * g0;
;                 const uint2 ra = *(const uint2*)(res + m * 1024 + nb_ + 4 * hh), rb = *(const uint2*)(res + m * 1024 + nb_ + 8 + 4 * hh);
;                 uint2 pa, pb;
;                 pa.x = pack2(alpha * lo2f(ra.x) + acc[mi][ni][4 * g0], alpha * hi2f(ra.x) + acc[mi][ni][4 * g0 + 1]);
;                 pa.y = pack2(alpha * lo2f(ra.y) + acc[mi][ni][4 * g0 + 2], alpha * hi2f(ra.y) + acc[mi][ni][4 * g0 + 3]);
;                 pb.x = pack2(alpha * lo2f(rb.x) + acc[mi][ni][4 * g0 + 4], alpha * hi2f(rb.x) + acc[mi][ni][4 * g0 + 5]);
;                 pb.y = pack2(alpha * lo2f(rb.y) + acc[mi][ni][4 * g0 + 6], alpha * hi2f(rb.y) + acc[mi][ni][4 * g0 + 7]);
;                 { auto rx = __builtin_amdgcn_permlane32_swap(pa.x, pb.x, false, false); pa.x = rx[0]; pb.x = rx[1]; }
;                 { auto ry = __builtin_amdgcn_permlane32_swap(pa.y, pb.y, false, false); pa.y = ry[0]; pb.y = ry[1]; }
;                 *(uint4*)(outp + m * 1024 + nb_ + 8 * hh) = make_uint4(pa.x, pa.y, pb.x, pb.y);
;               }
	v_lshlrev_b32_e32 v82, 16, v98
	v_and_b32_e32 v83, 0xffff0000, v98
	v_pk_fma_f32 v[82:83], v[82:83], s[8:9], v[84:85] op_sel_hi:[1,0,1]
	v_lshlrev_b32_e32 v84, 16, v99
	v_and_b32_e32 v85, 0xffff0000, v99
	v_pk_fma_f32 v[84:85], v[84:85], s[8:9], v[86:87] op_sel_hi:[1,0,1]
	v_cvt_pk_bf16_f32 v82, v82, v83
	v_cvt_pk_bf16_f32 v83, v84, v85
	s_nop 0
	v_permlane32_swap_b32_e32 v80, v82
	v_permlane32_swap_b32_e32 v81, v83
	global_store_dwordx4 v[112:113], v[80:83], off offset:128
	global_load_dwordx2 v[80:81], v[138:139], off offset:160
	s_nop 0
	global_load_dwordx2 v[82:83], v[138:139], off offset:176
	s_waitcnt vmcnt(1)
	v_lshlrev_b32_e32 v84, 16, v80
	v_and_b32_e32 v85, 0xffff0000, v80
	v_pk_fma_f32 v[84:85], v[84:85], s[8:9], v[88:89] op_sel_hi:[1,0,1]
	s_nop 0
	v_cvt_pk_bf16_f32 v80, v84, v85
	v_lshlrev_b32_e32 v84, 16, v81
	v_and_b32_e32 v85, 0xffff0000, v81
	v_pk_fma_f32 v[84:85], v[84:85], s[8:9], v[90:91] op_sel_hi:[1,0,1]
	s_nop 0
	v_cvt_pk_bf16_f32 v81, v84, v85
	s_waitcnt vmcnt(0)
	v_lshlrev_b32_e32 v84, 16, v82
	v_and_b32_e32 v85, 0xffff0000, v82
	v_pk_fma_f32 v[84:85], v[84:85], s[8:9], v[92:93] op_sel_hi:[1,0,1]
	s_nop 0
	v_cvt_pk_bf16_f32 v82, v84, v85
	v_lshlrev_b32_e32 v84, 16, v83
	v_and_b32_e32 v85, 0xffff0000, v83
	v_pk_fma_f32 v[84:85], v[84:85], s[8:9], v[94:95] op_sel_hi:[1,0,1]
	v_permlane32_swap_b32_e32 v80, v82
	v_cvt_pk_bf16_f32 v83, v84, v85
	s_nop 1
	v_permlane32_swap_b32_e32 v81, v83
	global_store_dwordx4 v[112:113], v[80:83], off offset:160
	global_load_dwordx2 v[80:81], v[138:139], off offset:192
	s_nop 0
	global_load_dwordx2 v[82:83], v[138:139], off offset:208
	v_or_b32_e32 v136, 0x10000, v136
	s_waitcnt vmcnt(1)
	v_lshlrev_b32_e32 v84, 16, v80
	v_and_b32_e32 v85, 0xffff0000, v80
	v_lshlrev_b32_e32 v80, 16, v81
	v_and_b32_e32 v81, 0xffff0000, v81
	v_pk_fma_f32 v[64:65], v[84:85], s[8:9], v[64:65] op_sel_hi:[1,0,1]
	v_pk_fma_f32 v[66:67], v[80:81], s[8:9], v[66:67] op_sel_hi:[1,0,1]
	v_cvt_pk_bf16_f32 v64, v64, v65
	v_cvt_pk_bf16_f32 v65, v66, v67
	s_waitcnt vmcnt(0)
	v_lshlrev_b32_e32 v66, 16, v82
	v_and_b32_e32 v67, 0xffff0000, v82
	v_pk_fma_f32 v[66:67], v[66:67], s[8:9], v[68:69] op_sel_hi:[1,0,1]
	v_lshlrev_b32_e32 v68, 16, v83
	v_and_b32_e32 v69, 0xffff0000, v83
	v_pk_fma_f32 v[68:69], v[68:69], s[8:9], v[70:71] op_sel_hi:[1,0,1]
	v_cvt_pk_bf16_f32 v66, v66, v67
	v_cvt_pk_bf16_f32 v67, v68, v69
	s_nop 0
	v_permlane32_swap_b32_e32 v64, v66
	v_permlane32_swap_b32_e32 v65, v67
	global_store_dwordx4 v[112:113], v[64:67], off offset:192
	global_load_dwordx2 v[64:65], v[138:139], off offset:224
	s_nop 0
	global_load_dwordx2 v[66:67], v[138:139], off offset:240
	v_lshl_add_u64 v[70:71], v[132:133], 0, v[136:137]
	s_waitcnt vmcnt(1)
	v_lshlrev_b32_e32 v68, 16, v64
	v_and_b32_e32 v69, 0xffff0000, v64
	v_pk_fma_f32 v[68:69], v[68:69], s[8:9], v[72:73] op_sel_hi:[1,0,1]
	s_nop 0
	v_cvt_pk_bf16_f32 v64, v68, v69
	v_lshlrev_b32_e32 v68, 16, v65
	v_and_b32_e32 v69, 0xffff0000, v65
	v_pk_fma_f32 v[68:69], v[68:69], s[8:9], v[74:75] op_sel_hi:[1,0,1]
	s_nop 0
	v_cvt_pk_bf16_f32 v65, v68, v69
	s_waitcnt vmcnt(0)
	v_lshlrev_b32_e32 v68, 16, v66
	v_and_b32_e32 v69, 0xffff0000, v66
	v_pk_fma_f32 v[68:69], v[68:69], s[8:9], v[76:77] op_sel_hi:[1,0,1]
	s_nop 0
	v_cvt_pk_bf16_f32 v66, v68, v69
	v_lshlrev_b32_e32 v68, 16, v67
	v_and_b32_e32 v69, 0xffff0000, v67
	v_pk_fma_f32 v[68:69], v[68:69], s[8:9], v[78:79] op_sel_hi:[1,0,1]
	v_permlane32_swap_b32_e32 v64, v66
	v_cvt_pk_bf16_f32 v67, v68, v69
	s_nop 1
	v_permlane32_swap_b32_e32 v65, v67
	global_store_dwordx4 v[112:113], v[64:67], off offset:224
	s_nop 1
	v_lshl_add_u64 v[64:65], s[40:41], 0, v[136:137]
	v_lshl_add_u64 v[64:65], v[64:65], 0, v[134:135]
	v_lshl_add_u64 v[64:65], v[64:65], 0, v[128:129]
	global_load_dwordx2 v[66:67], v[64:65], off
	global_load_dwordx2 v[68:69], v[64:65], off offset:16
	s_waitcnt vmcnt(1)
	v_lshlrev_b32_e32 v72, 16, v66
	v_and_b32_e32 v73, 0xffff0000, v66
	v_pk_fma_f32 v[48:49], v[72:73], s[8:9], v[48:49] op_sel_hi:[1,0,1]
	s_nop 0
	v_cvt_pk_bf16_f32 v66, v48, v49
	v_lshlrev_b32_e32 v48, 16, v67
	v_and_b32_e32 v49, 0xffff0000, v67
	v_pk_fma_f32 v[48:49], v[48:49], s[8:9], v[50:51] op_sel_hi:[1,0,1]
	s_nop 0
	v_cvt_pk_bf16_f32 v67, v48, v49
	s_waitcnt vmcnt(0)
	v_lshlrev_b32_e32 v48, 16, v68
	v_and_b32_e32 v49, 0xffff0000, v68
	v_pk_fma_f32 v[48:49], v[48:49], s[8:9], v[52:53] op_sel_hi:[1,0,1]
	s_nop 0
	v_cvt_pk_bf16_f32 v68, v48, v49
	v_lshlrev_b32_e32 v48, 16, v69
	v_and_b32_e32 v49, 0xffff0000, v69
	v_pk_fma_f32 v[48:49], v[48:49], s[8:9], v[54:55] op_sel_hi:[1,0,1]
	v_permlane32_swap_b32_e32 v66, v68
	v_cvt_pk_bf16_f32 v69, v48, v49
	s_nop 1
	v_permlane32_swap_b32_e32 v67, v69
	v_lshl_add_u64 v[48:49], v[70:71], 0, v[134:135]
	global_store_dwordx4 v[48:49], v[66:69], off
	global_load_dwordx2 v[50:51], v[64:65], off offset:32
	global_load_dwordx2 v[52:53], v[64:65], off offset:48
	s_waitcnt vmcnt(1)
	v_lshlrev_b32_e32 v54, 16, v50
	v_and_b32_e32 v55, 0xffff0000, v50
	v_pk_fma_f32 v[54:55], v[54:55], s[8:9], v[56:57] op_sel_hi:[1,0,1]
	s_nop 0
	v_cvt_pk_bf16_f32 v50, v54, v55
	v_lshlrev_b32_e32 v54, 16, v51
	v_and_b32_e32 v55, 0xffff0000, v51
	v_pk_fma_f32 v[54:55], v[54:55], s[8:9], v[58:59] op_sel_hi:[1,0,1]
	s_nop 0
	v_cvt_pk_bf16_f32 v51, v54, v55
	s_waitcnt vmcnt(0)
	v_lshlrev_b32_e32 v54, 16, v52
	v_and_b32_e32 v55, 0xffff0000, v52
	v_pk_fma_f32 v[54:55], v[54:55], s[8:9], v[60:61] op_sel_hi:[1,0,1]
	s_nop 0
	v_cvt_pk_bf16_f32 v52, v54, v55
	v_lshlrev_b32_e32 v54, 16, v53
	v_and_b32_e32 v55, 0xffff0000, v53
	v_pk_fma_f32 v[54:55], v[54:55], s[8:9], v[62:63] op_sel_hi:[1,0,1]
	v_permlane32_swap_b32_e32 v50, v52
	v_cvt_pk_bf16_f32 v53, v54, v55
	s_nop 1
	v_permlane32_swap_b32_e32 v51, v53
	global_store_dwordx4 v[48:49], v[50:53], off offset:32
	global_load_dwordx2 v[50:51], v[64:65], off offset:64
	s_nop 0
	global_load_dwordx2 v[52:53], v[64:65], off offset:80
	s_waitcnt vmcnt(1)
; DI unsigned pack2(float a, float b) { f32x2_t v = {a, b}; return __builtin_bit_cast(unsigned, __builtin_convertvector(v, bf16x2_t)); }
; DI float lo2f(unsigned v) { return __uint_as_float(v << 16); }
; DI float hi2f(unsigned v) { return __uint_as_float(v & 0xffff0000u); }
;     ...
;             } else if (MODE == 1) {
; #pragma unroll
;               for (int gp = 0; gp < 2; ++gp) {
;                 const int g0 = 2 * gp;
;                 const int nb_ = nt * 256 + wn * 128 + ni * 32 + 8 * g0;
;                 const uint2 ra = *(const uint2*)(res + m * 1024 + nb_ + 4 * hh), rb = *(const uint2*)(res + m * 1024 + nb_ + 8 + 4 * hh);
;                 uint2 pa, pb;
;                 pa.x = pack2(alpha * lo2f(ra.x) + acc[mi][ni][4 * g0], alpha * hi2f(ra.x) + acc[mi][ni][4 * g0 + 1]);
;                 pa.y = pack2(alpha * lo2f(ra.y) + acc[mi][ni][4 * g0 + 2], alpha * hi2f(ra.y) + acc[mi][ni][4 * g0 + 3]);
;                 pb.x = pack2(alpha * lo2f(rb.x) + acc[mi][ni][4 * g0 + 4], alpha * hi2f(rb.x) + acc[mi][ni][4 * g0 + 5]);
;                 pb.y = pack2(alpha * lo2f(rb.y) + acc[mi][ni][4 * g0 + 6], alpha * hi2f(rb.y) + acc[mi][ni][4 * g0 + 7]);
;                 { auto rx = __builtin_amdgcn_permlane32_swap(pa.x, pb.x, false, false); pa.x = rx[0]; pb.x = rx[1]; }
;                 { auto ry = __builtin_amdgcn_permlane32_swap(pa.y, pb.y, false, false); pa.y = ry[0]; pb.y = ry[1]; }
;                 *(uint4*)(outp + m * 1024 + nb_ + 8 * hh) = make_uint4(pa.x, pa.y, pb.x, pb.y);
;               }
;     ...
;     asm volatile("s_waitcnt lgkmcnt(0)" ::: "memory"); __builtin_amdgcn_s_barrier(); asm volatile("" ::: "memory");
;     cur ^= BUFB;
;   }
;   asm volatile("s_waitcnt vmcnt(0)" ::: "memory");
;   __syncthreads();
	v_lshlrev_b32_e32 v54, 16, v50
	v_and_b32_e32 v55, 0xffff0000, v50
	v_lshlrev_b32_e32 v50, 16, v51
	v_and_b32_e32 v51, 0xffff0000, v51
	v_pk_fma_f32 v[32:33], v[54:55], s[8:9], v[32:33] op_sel_hi:[1,0,1]
	v_pk_fma_f32 v[34:35], v[50:51], s[8:9], v[34:35] op_sel_hi:[1,0,1]
	v_cvt_pk_bf16_f32 v32, v32, v33
	v_cvt_pk_bf16_f32 v33, v34, v35
	s_waitcnt vmcnt(0)
	v_lshlrev_b32_e32 v34, 16, v52
	v_and_b32_e32 v35, 0xffff0000, v52
	v_pk_fma_f32 v[34:35], v[34:35], s[8:9], v[36:37] op_sel_hi:[1,0,1]
	v_lshlrev_b32_e32 v36, 16, v53
	v_and_b32_e32 v37, 0xffff0000, v53
	v_pk_fma_f32 v[36:37], v[36:37], s[8:9], v[38:39] op_sel_hi:[1,0,1]
	v_cvt_pk_bf16_f32 v34, v34, v35
	v_cvt_pk_bf16_f32 v35, v36, v37
	s_nop 0
	v_permlane32_swap_b32_e32 v32, v34
	v_permlane32_swap_b32_e32 v33, v35
	global_store_dwordx4 v[48:49], v[32:35], off offset:64
	global_load_dwordx2 v[32:33], v[64:65], off offset:96
	s_nop 0
	global_load_dwordx2 v[34:35], v[64:65], off offset:112
	s_waitcnt vmcnt(1)
	v_lshlrev_b32_e32 v36, 16, v32
	v_and_b32_e32 v37, 0xffff0000, v32
	v_pk_fma_f32 v[36:37], v[36:37], s[8:9], v[40:41] op_sel_hi:[1,0,1]
	s_nop 0
	v_cvt_pk_bf16_f32 v32, v36, v37
	v_lshlrev_b32_e32 v36, 16, v33
	v_and_b32_e32 v37, 0xffff0000, v33
	v_pk_fma_f32 v[36:37], v[36:37], s[8:9], v[42:43] op_sel_hi:[1,0,1]
	s_nop 0
	v_cvt_pk_bf16_f32 v33, v36, v37
	s_waitcnt vmcnt(0)
	v_lshlrev_b32_e32 v36, 16, v34
	v_and_b32_e32 v37, 0xffff0000, v34
	v_pk_fma_f32 v[36:37], v[36:37], s[8:9], v[44:45] op_sel_hi:[1,0,1]
	s_nop 0
	v_cvt_pk_bf16_f32 v34, v36, v37
	v_lshlrev_b32_e32 v36, 16, v35
	v_and_b32_e32 v37, 0xffff0000, v35
	v_pk_fma_f32 v[36:37], v[36:37], s[8:9], v[46:47] op_sel_hi:[1,0,1]
	v_permlane32_swap_b32_e32 v32, v34
	v_cvt_pk_bf16_f32 v35, v36, v37
	s_nop 1
	v_permlane32_swap_b32_e32 v33, v35
	global_store_dwordx4 v[48:49], v[32:35], off offset:96
	global_load_dwordx2 v[32:33], v[64:65], off offset:128
	s_nop 0
	global_load_dwordx2 v[34:35], v[64:65], off offset:144
	s_waitcnt vmcnt(1)
	v_lshlrev_b32_e32 v36, 16, v32
	v_and_b32_e32 v37, 0xffff0000, v32
	v_lshlrev_b32_e32 v32, 16, v33
	v_and_b32_e32 v33, 0xffff0000, v33
	v_pk_fma_f32 v[16:17], v[36:37], s[8:9], v[16:17] op_sel_hi:[1,0,1]
	v_pk_fma_f32 v[18:19], v[32:33], s[8:9], v[18:19] op_sel_hi:[1,0,1]
	v_cvt_pk_bf16_f32 v16, v16, v17
	v_cvt_pk_bf16_f32 v17, v18, v19
	s_waitcnt vmcnt(0)
	v_lshlrev_b32_e32 v18, 16, v34
	v_and_b32_e32 v19, 0xffff0000, v34
	v_pk_fma_f32 v[18:19], v[18:19], s[8:9], v[20:21] op_sel_hi:[1,0,1]
	v_lshlrev_b32_e32 v20, 16, v35
	v_and_b32_e32 v21, 0xffff0000, v35
	v_pk_fma_f32 v[20:21], v[20:21], s[8:9], v[22:23] op_sel_hi:[1,0,1]
	v_cvt_pk_bf16_f32 v18, v18, v19
	v_cvt_pk_bf16_f32 v19, v20, v21
	s_nop 0
	v_permlane32_swap_b32_e32 v16, v18
	v_permlane32_swap_b32_e32 v17, v19
	global_store_dwordx4 v[48:49], v[16:19], off offset:128
	global_load_dwordx2 v[16:17], v[64:65], off offset:160
	s_nop 0
	global_load_dwordx2 v[18:19], v[64:65], off offset:176
	s_waitcnt vmcnt(1)
	v_lshlrev_b32_e32 v20, 16, v16
	v_and_b32_e32 v21, 0xffff0000, v16
	v_pk_fma_f32 v[20:21], v[20:21], s[8:9], v[24:25] op_sel_hi:[1,0,1]
	s_nop 0
	v_cvt_pk_bf16_f32 v16, v20, v21
	v_lshlrev_b32_e32 v20, 16, v17
	v_and_b32_e32 v21, 0xffff0000, v17
	v_pk_fma_f32 v[20:21], v[20:21], s[8:9], v[26:27] op_sel_hi:[1,0,1]
	s_nop 0
	v_cvt_pk_bf16_f32 v17, v20, v21
	s_waitcnt vmcnt(0)
	v_lshlrev_b32_e32 v20, 16, v18
	v_and_b32_e32 v21, 0xffff0000, v18
	v_pk_fma_f32 v[20:21], v[20:21], s[8:9], v[28:29] op_sel_hi:[1,0,1]
	s_nop 0
	v_cvt_pk_bf16_f32 v18, v20, v21
	v_lshlrev_b32_e32 v20, 16, v19
	v_and_b32_e32 v21, 0xffff0000, v19
	v_pk_fma_f32 v[20:21], v[20:21], s[8:9], v[30:31] op_sel_hi:[1,0,1]
	v_permlane32_swap_b32_e32 v16, v18
	v_cvt_pk_bf16_f32 v19, v20, v21
	s_nop 1
	v_permlane32_swap_b32_e32 v17, v19
	global_store_dwordx4 v[48:49], v[16:19], off offset:160
	global_load_dwordx2 v[16:17], v[64:65], off offset:192
	s_nop 0
	global_load_dwordx2 v[18:19], v[64:65], off offset:208
	s_waitcnt vmcnt(1)
	v_lshlrev_b32_e32 v20, 16, v16
	v_and_b32_e32 v21, 0xffff0000, v16
	v_lshlrev_b32_e32 v16, 16, v17
	v_and_b32_e32 v17, 0xffff0000, v17
	v_pk_fma_f32 v[0:1], v[20:21], s[8:9], v[0:1] op_sel_hi:[1,0,1]
	v_pk_fma_f32 v[2:3], v[16:17], s[8:9], v[2:3] op_sel_hi:[1,0,1]
	v_cvt_pk_bf16_f32 v0, v0, v1
	v_cvt_pk_bf16_f32 v1, v2, v3
	s_waitcnt vmcnt(0)
	v_lshlrev_b32_e32 v2, 16, v18
	v_and_b32_e32 v3, 0xffff0000, v18
	v_pk_fma_f32 v[2:3], v[2:3], s[8:9], v[4:5] op_sel_hi:[1,0,1]
	v_lshlrev_b32_e32 v4, 16, v19
	v_and_b32_e32 v5, 0xffff0000, v19
	v_pk_fma_f32 v[4:5], v[4:5], s[8:9], v[6:7] op_sel_hi:[1,0,1]
	v_cvt_pk_bf16_f32 v2, v2, v3
	v_cvt_pk_bf16_f32 v3, v4, v5
	s_nop 0
	v_permlane32_swap_b32_e32 v0, v2
	v_permlane32_swap_b32_e32 v1, v3
	global_store_dwordx4 v[48:49], v[0:3], off offset:192
	global_load_dwordx2 v[0:1], v[64:65], off offset:224
	s_nop 0
	global_load_dwordx2 v[2:3], v[64:65], off offset:240
	s_waitcnt vmcnt(1)
	v_lshlrev_b32_e32 v4, 16, v0
	v_and_b32_e32 v5, 0xffff0000, v0
	v_pk_fma_f32 v[4:5], v[4:5], s[8:9], v[8:9] op_sel_hi:[1,0,1]
	s_nop 0
	v_cvt_pk_bf16_f32 v0, v4, v5
	v_lshlrev_b32_e32 v4, 16, v1
	v_and_b32_e32 v5, 0xffff0000, v1
	v_pk_fma_f32 v[4:5], v[4:5], s[8:9], v[10:11] op_sel_hi:[1,0,1]
	s_nop 0
	v_cvt_pk_bf16_f32 v1, v4, v5
	s_waitcnt vmcnt(0)
	v_lshlrev_b32_e32 v4, 16, v2
	v_and_b32_e32 v5, 0xffff0000, v2
	v_pk_fma_f32 v[4:5], v[4:5], s[8:9], v[12:13] op_sel_hi:[1,0,1]
	s_nop 0
	v_cvt_pk_bf16_f32 v2, v4, v5
	v_lshlrev_b32_e32 v4, 16, v3
	v_and_b32_e32 v5, 0xffff0000, v3
	v_pk_fma_f32 v[4:5], v[4:5], s[8:9], v[14:15] op_sel_hi:[1,0,1]
	v_permlane32_swap_b32_e32 v0, v2
	v_cvt_pk_bf16_f32 v3, v4, v5
	s_nop 1
	v_permlane32_swap_b32_e32 v1, v3
	global_store_dwordx4 v[48:49], v[0:3], off offset:224
	s_waitcnt lgkmcnt(0)
	s_barrier
	s_waitcnt vmcnt(0)
	s_barrier

; #define MFMA(a, b, c) __builtin_amdgcn_mfma_f32_32x32x16_bf16((a), (b), (c), 0, 0, 0)
; DI f32x16 zero16() { f32x16 z; for (int i = 0; i < 16; ++i) z[i] = 0.f; return z; }
;     ...
;   const int drr = lane >> 3, dch = (lane & 7) ^ (((w & 1) * 4 + (drr >> 1)) & 7);
;   const int drow = w * 8 + drr, dcol = dch * 8;
;   const unsigned dA = (unsigned)(drow * lda + dcol), dB = (unsigned)(drow * K + dcol);
;     ...
;   const int fP = r * 128, fsw = (r >> 1) & 7;
;   const int fA = wm * 8192 + fP, fB = 32768 + wn * 16384 + fP;
;   f32x16 acc[2][4];
; #pragma unroll
;   for (int i = 0; i < 2; ++i)
; #pragma unroll
;     for (int j = 0; j < 4; ++j) acc[i][j] = zero16();
;   __syncthreads();
;   G_DMA(0, 0);
;   asm volatile("s_waitcnt vmcnt(0)" ::: "memory");
;   asm volatile("s_waitcnt lgkmcnt(0)" ::: "memory"); __builtin_amdgcn_s_barrier(); asm volatile("" ::: "memory");
;   int cur = 0;
;   for (int s = 0; s < S; ++s) {
;     G_DMA(s + 1, cur ^ BUFB);
;     {
;       const char* Ab = smem + cur + fA;
;       const char* Bb = smem + cur + fB;
;       __builtin_amdgcn_sched_barrier(0);
; #pragma unroll
;       for (int kk = 0; kk < 4; ++kk) {
;         const int ko = (((kk * 2 + hh) ^ fsw) << 4);
;         bf16x8 af[2], wf[4];
;         af[0] = *(const bf16x8*)(Ab + ko); af[1] = *(const bf16x8*)(Ab + 4096 + ko);
; #pragma unroll
;         for (int ni = 0; ni < 4; ++ni) wf[ni] = *(const bf16x8*)(Bb + ni * 4096 + ko);
; #pragma unroll
;         for (int mi = 0; mi < 2; ++mi)
; #pragma unroll
;           for (int ni = 0; ni < 4; ++ni) acc[mi][ni] = MFMA(wf[ni], af[mi], acc[mi][ni]);
;         if (kk == 1) __builtin_amdgcn_sched_barrier(0);
;       }
;       __builtin_amdgcn_sched_barrier(0);
;     }
;     asm volatile("s_waitcnt vmcnt(0)" ::: "memory");
.LBB0_218:
	s_add_i32 s46, s8, 1
	s_cmp_lt_u32 s46, s58
	s_cselect_b32 s22, s46, s59
	s_lshl_b32 s23, s22, 1
	s_andn2_b32 s23, s23, 31
	s_add_i32 s23, s23, s33
	s_lshr_b32 s23, s23, 3
	s_mov_b32 s9, s25
	s_and_b32 s25, s23, 4
	s_or_b32 s25, s25, s45
	s_and_b32 s23, s23, 0xfffff8
	s_or_b32 s28, s23, s74
	s_lshl_b32 s23, s25, 19
	s_add_u32 s23, s7, s23
	s_addc_u32 s25, s24, 0
	s_lshl_b32 s22, s22, 7
	s_and_b32 s44, s22, 0x780
	s_add_u32 s22, s23, s44
	s_addc_u32 s23, s25, 0
	s_lshl_b32 s40, s28, 8
	s_ashr_i32 s41, s40, 31
	s_lshl_b64 s[40:41], s[40:41], 11
	s_add_u32 s28, s62, s40
	s_addc_u32 s40, s63, s41
	s_xor_b32 s25, s9, 0x10000
	v_add_u32_e32 v128, s25, v142
	v_lshl_add_u64 v[136:137], s[22:23], 0, v[132:133]
	v_readfirstlane_b32 s22, v128
	v_add_u32_e32 v148, 0x2000, v128
	s_mov_b32 m0, s22
	s_mov_b64 s[50:51], 0x20000
	v_readfirstlane_b32 s22, v148
	v_add_u32_e32 v148, 0x4000, v128
	global_load_lds_dwordx4 v[136:137], off
	v_add3_u32 v244, s9, v131, v140
	v_add3_u32 v245, s9, v141, v140
	v_add_u32_e32 v187, v245, v144
	v_add_u32_e32 v208, v244, v144
	ds_read_b128 v[188:191], v187 offset:32768
	ds_read_b128 v[204:207], v208
	ds_read_b128 v[192:195], v187 offset:36864
	ds_read_b128 v[196:199], v187 offset:40960
	ds_read_b128 v[200:203], v187 offset:45056
	ds_read_b128 v[216:219], v208 offset:4096
	v_add_u32_e32 v209, v245, v145
	v_add_u32_e32 v215, v244, v145
	ds_read_b128 v[220:223], v209 offset:32768
	ds_read_b128 v[236:239], v215
	ds_read_b128 v[224:227], v209 offset:36864
	ds_read_b128 v[228:231], v209 offset:40960
	ds_read_b128 v[232:235], v209 offset:45056
	ds_read_b128 v[240:243], v215 offset:4096
	s_waitcnt lgkmcnt(10)
	v_mfma_f32_32x32x16_bf16 v[112:127], v[188:191], v[204:207], v[112:127]
	s_waitcnt lgkmcnt(9)
	v_mfma_f32_32x32x16_bf16 v[96:111], v[192:195], v[204:207], v[96:111]
	v_lshl_add_u64 v[138:139], v[136:137], 0, s[50:51]
	s_mov_b32 m0, s22
	s_mov_b64 s[48:49], 0x40000
	v_readfirstlane_b32 s22, v148
	global_load_lds_dwordx4 v[138:139], off
	s_waitcnt lgkmcnt(8)
	v_mfma_f32_32x32x16_bf16 v[80:95], v[196:199], v[204:207], v[80:95]
	s_waitcnt lgkmcnt(7)
	v_mfma_f32_32x32x16_bf16 v[64:79], v[200:203], v[204:207], v[64:79]
	v_lshl_add_u64 v[138:139], v[136:137], 0, s[48:49]
	s_mov_b32 m0, s22
	s_mov_b64 s[52:53], 0x60000
	global_load_lds_dwordx4 v[138:139], off
	s_waitcnt lgkmcnt(6)
	v_mfma_f32_32x32x16_bf16 v[48:63], v[188:191], v[216:219], v[48:63]
	v_mfma_f32_32x32x16_bf16 v[32:47], v[192:195], v[216:219], v[32:47]
	v_add_u32_e32 v138, 0x6000, v128
	v_lshl_add_u64 v[136:137], v[136:137], 0, s[52:53]
	v_readfirstlane_b32 s22, v138
	s_mov_b32 m0, s22
	s_add_u32 s22, s28, s44
	s_addc_u32 s23, s40, 0
	v_add_u32_e32 v138, 0x8000, v128
	global_load_lds_dwordx4 v[136:137], off
	v_mfma_f32_32x32x16_bf16 v[16:31], v[196:199], v[216:219], v[16:31]
	v_mfma_f32_32x32x16_bf16 v[0:15], v[200:203], v[216:219], v[0:15]
	v_lshl_add_u64 v[136:137], s[22:23], 0, v[132:133]
	v_readfirstlane_b32 s22, v138
	v_add_u32_e32 v148, 0xa000, v128
	s_mov_b32 m0, s22
	v_readfirstlane_b32 s22, v148
	v_add_u32_e32 v148, 0xc000, v128
	global_load_lds_dwordx4 v[136:137], off
	v_add_u32_e32 v187, v245, v146
	v_add_u32_e32 v208, v244, v146
	ds_read_b128 v[188:191], v187 offset:32768
	ds_read_b128 v[204:207], v208
	ds_read_b128 v[192:195], v187 offset:36864
	ds_read_b128 v[196:199], v187 offset:40960
	ds_read_b128 v[200:203], v187 offset:45056
	ds_read_b128 v[216:219], v208 offset:4096
	s_waitcnt lgkmcnt(10)
	v_mfma_f32_32x32x16_bf16 v[112:127], v[220:223], v[236:239], v[112:127]
	s_waitcnt lgkmcnt(9)
	v_mfma_f32_32x32x16_bf16 v[96:111], v[224:227], v[236:239], v[96:111]
	v_lshl_add_u64 v[138:139], v[136:137], 0, s[50:51]
	s_mov_b32 m0, s22
	v_readfirstlane_b32 s22, v148
	v_add_u32_e32 v128, 0xe000, v128
	global_load_lds_dwordx4 v[138:139], off
	s_waitcnt lgkmcnt(8)
	v_mfma_f32_32x32x16_bf16 v[80:95], v[228:231], v[236:239], v[80:95]
	s_waitcnt lgkmcnt(7)
	v_mfma_f32_32x32x16_bf16 v[64:79], v[232:235], v[236:239], v[64:79]
	v_lshl_add_u64 v[138:139], v[136:137], 0, s[48:49]
	s_mov_b32 m0, s22
	v_readfirstlane_b32 s22, v128
	global_load_lds_dwordx4 v[138:139], off
	s_waitcnt lgkmcnt(6)
	v_mfma_f32_32x32x16_bf16 v[48:63], v[220:223], v[240:243], v[48:63]
	v_mfma_f32_32x32x16_bf16 v[32:47], v[224:227], v[240:243], v[32:47]
	v_lshl_add_u64 v[136:137], v[136:137], 0, s[52:53]
	s_mov_b32 m0, s22
	s_add_i32 s9, s9, 0
	global_load_lds_dwordx4 v[136:137], off
	v_mfma_f32_32x32x16_bf16 v[16:31], v[228:231], v[240:243], v[16:31]
	v_mfma_f32_32x32x16_bf16 v[0:15], v[232:235], v[240:243], v[0:15]
	v_add_u32_e32 v209, v245, v147
	v_add_u32_e32 v215, v244, v147
	ds_read_b128 v[220:223], v209 offset:32768
	ds_read_b128 v[236:239], v215
	ds_read_b128 v[224:227], v209 offset:36864
	ds_read_b128 v[228:231], v209 offset:40960
	ds_read_b128 v[232:235], v209 offset:45056
	ds_read_b128 v[240:243], v215 offset:4096
	s_waitcnt lgkmcnt(10)
	v_mfma_f32_32x32x16_bf16 v[112:127], v[188:191], v[204:207], v[112:127]
	s_waitcnt lgkmcnt(9)
	v_mfma_f32_32x32x16_bf16 v[96:111], v[192:195], v[204:207], v[96:111]
	s_waitcnt lgkmcnt(8)
	v_mfma_f32_32x32x16_bf16 v[80:95], v[196:199], v[204:207], v[80:95]
	s_waitcnt lgkmcnt(7)
	v_mfma_f32_32x32x16_bf16 v[64:79], v[200:203], v[204:207], v[64:79]
	s_waitcnt lgkmcnt(6)
	v_mfma_f32_32x32x16_bf16 v[48:63], v[188:191], v[216:219], v[48:63]
	v_mfma_f32_32x32x16_bf16 v[32:47], v[192:195], v[216:219], v[32:47]
	v_mfma_f32_32x32x16_bf16 v[16:31], v[196:199], v[216:219], v[16:31]
	v_mfma_f32_32x32x16_bf16 v[0:15], v[200:203], v[216:219], v[0:15]
	s_waitcnt lgkmcnt(4)
	v_mfma_f32_32x32x16_bf16 v[112:127], v[220:223], v[236:239], v[112:127]
	s_waitcnt lgkmcnt(3)
	v_mfma_f32_32x32x16_bf16 v[96:111], v[224:227], v[236:239], v[96:111]
	s_waitcnt lgkmcnt(2)
	v_mfma_f32_32x32x16_bf16 v[80:95], v[228:231], v[236:239], v[80:95]
	s_waitcnt lgkmcnt(1)
	v_mfma_f32_32x32x16_bf16 v[64:79], v[232:235], v[236:239], v[64:79]
	s_waitcnt lgkmcnt(0)
	v_mfma_f32_32x32x16_bf16 v[48:63], v[220:223], v[240:243], v[48:63]
	v_mfma_f32_32x32x16_bf16 v[32:47], v[224:227], v[240:243], v[32:47]
	v_mfma_f32_32x32x16_bf16 v[16:31], v[228:231], v[240:243], v[16:31]
	v_mfma_f32_32x32x16_bf16 v[0:15], v[232:235], v[240:243], v[0:15]
	s_waitcnt vmcnt(0)
	s_and_b32 s9, s8, 15
	s_cmp_lg_u32 s9, 15
	s_cbranch_scc1 .LBB0_217
; DI unsigned pack2(float a, float b) { f32x2_t v = {a, b}; return __builtin_bit_cast(unsigned, __builtin_convertvector(v, bf16x2_t)); }
; #define G_TILEMAP(q, MT, NT) do { if (sq) { const int grp_ = (q) >> 5, i_ = (q) & 31; \
;       MT = xcd * mpx + (grp_ & (mpx / 4 - 1)) * 4 + (i_ & 3); NT = (grp_ >> (LMPX - 2)) * 8 + (i_ >> 2); } \
;     else { MT = xcd * mpx + ((q) & (mpx - 1)); NT = (q) >> LMPX; } } while (0)
;     ...
;     if ((s & (nk - 1)) == nk - 1) {
;       const int q = slot + (s >> lnk) * nslots;
;       int mt, nt; G_TILEMAP(q, mt, nt);
;       if (dostore) {
; #pragma unroll
;         for (int mi = 0; mi < 2; ++mi) {
;           const size_t m = (size_t)mt * 256 + wm * 64 + mi * 32 + r;
; #pragma unroll
;           for (int ni = 0; ni < 4; ++ni) {
;             __builtin_amdgcn_sched_barrier(0);
;             if (MODE == 0) {
; #pragma unroll
;               for (int gp = 0; gp < 2; ++gp) {
;                 const int g0 = 2 * gp;
;                 uint2 pa, pb;
;                 pa.x = pack2(acc[mi][ni][4 * g0], acc[mi][ni][4 * g0 + 1]); pa.y = pack2(acc[mi][ni][4 * g0 + 2], acc[mi][ni][4 * g0 + 3]);
;                 pb.x = pack2(acc[mi][ni][4 * g0 + 4], acc[mi][ni][4 * g0 + 5]); pb.y = pack2(acc[mi][ni][4 * g0 + 6], acc[mi][ni][4 * g0 + 7]);
;                 { auto rx = __builtin_amdgcn_permlane32_swap(pa.x, pb.x, false, false); pa.x = rx[0]; pb.x = rx[1]; }
;                 { auto ry = __builtin_amdgcn_permlane32_swap(pa.y, pb.y, false, false); pa.y = ry[0]; pb.y = ry[1]; }
;                 const int col = nt * 256 + wn * 128 + ni * 32 + 8 * g0 + 8 * hh;
;                 const uint4 v4 = make_uint4(pa.x, pa.y, pb.x, pb.y);
;                 if (outp != nullptr && nt >= 32) *(uint4*)(outp + m * 2048 + (col - 8192)) = v4;
;                 else if (col < nvalid) *(uint4*)(C + m * ldc + col) = v4;
	s_lshl_b32 s8, s8, 1
	s_and_b32 s8, s8, 0x7fffffe0
	s_add_i32 s8, s8, s33
	s_lshr_b32 s9, s8, 3
	s_and_b32 s22, s9, 4
	s_or_b32 s22, s22, s45
	s_and_b32 s9, s9, 0xfffff8
	s_or_b32 s9, s9, s74
	s_lshl_b32 s28, s22, 8
	v_lshl_add_u64 v[136:137], v[134:135], 0, s[28:29]
	s_lshl_b32 s28, s9, 8
	s_cmpk_lt_u32 s8, 0x100
	s_cselect_b64 s[8:9], -1, 0
	s_xor_b64 s[22:23], s[56:57], -1
	v_lshlrev_b64 v[138:139], 14, v[136:137]
	v_or_b32_e32 v128, s28, v143
	s_mov_b64 s[40:41], -1
	s_or_b64 s[44:45], s[22:23], s[8:9]
	v_lshl_add_u64 v[138:139], s[30:31], 0, v[138:139]
	v_cvt_pk_bf16_f32 v112, v112, v113
	v_cvt_pk_bf16_f32 v113, v114, v115
	v_cvt_pk_bf16_f32 v114, v116, v117
	v_cvt_pk_bf16_f32 v115, v118, v119
	s_nop 0
	v_permlane32_swap_b32_e32 v112, v114
	v_permlane32_swap_b32_e32 v113, v115
	s_and_b64 vcc, exec, s[44:45]
	s_cbranch_vccz .LBB0_223
	s_cmp_gt_u32 s28, 0x3fffffff
	s_cbranch_scc1 .LBB0_222
	v_lshl_add_u64 v[116:117], v[128:129], 1, v[138:139]
	global_store_dwordx4 v[116:117], v[112:115], off

; DI f32x16 zero16() { f32x16 z; for (int i = 0; i < 16; ++i) z[i] = 0.f; return z; }
; DI void hg_scan_phase(int wvs, char* smem, const bf16_t* __restrict__ PROJ, const float* __restrict__ lbraw, bf16_t* OF, bf16_t* OB) {
;     ...
;     const int dh = it & 1, dir = (it >> 1) & 1, h = (it >> 2) & 15, b = it >> 6;
;     const int kp = lane, seg = w;
;     float lbv[2];
; #pragma unroll
;     for (int u = 0; u < 2; ++u) {
;       const int idx = dir * 2048 + h * 128 + 2 * kp + u;
;       const float l0 = lbraw[idx], l1 = lbraw[4096 + idx], l2 = lbraw[8192 + idx], l3 = lbraw[12288 + idx];
;       const float mx = fmaxf(fmaxf(l0, l1), fmaxf(l2, l3));
;       const float e0 = expf(l0 - mx), e1 = expf(l1 - mx), e2 = expf(l2 - mx), e3 = expf(l3 - mx);
;       lbv[u] = (e1 + e2) / (e0 + e1 + e2 + e3);
;     }
;     const float lb0 = lbv[0], lb1 = lbv[1];
;     bf16_t* O = dir ? OB : OF;
;     f32x16 sacc = zero16();
;     const int kb = w & 3, db = w >> 2;
;     ...
;     unsigned rq[8], rf[8]; bf16_t rv[8];
.LBB0_375:
	s_or_b64 exec, exec, s[24:25]
	v_mul_f32_e32 v8, 0x3fb8aa3b, v0
	v_fma_f32 v9, v0, s97, -v8
	v_fmac_f32_e32 v9, 0x32a5705f, v0
	v_rndne_f32_e32 v0, v8
	v_sub_f32_e32 v8, v8, v0
	v_add_f32_e32 v8, v8, v9
	v_exp_f32_e32 v8, v8
	v_cvt_i32_f32_e32 v0, v0
	s_mov_b64 s[94:95], s[12:13]
	v_readlane_b32 s12, v253, 5
	v_readlane_b32 s13, v253, 6
	v_ldexp_f32 v0, v8, v0
	v_mul_f32_e32 v8, 0x3fb8aa3b, v2
	v_fma_f32 v9, v2, s97, -v8
	v_fmac_f32_e32 v9, 0x32a5705f, v2
	v_rndne_f32_e32 v2, v8
	v_sub_f32_e32 v8, v8, v2
	v_add_f32_e32 v8, v8, v9
	v_exp_f32_e32 v8, v8
	v_cvt_i32_f32_e32 v2, v2
	v_lshlrev_b32_e32 v128, 1, v92
	v_mov_b32_e32 v17, v129
	v_cndmask_b32_e64 v0, 0, v0, s[90:91]
	v_ldexp_f32 v2, v8, v2
	v_mul_f32_e32 v8, 0x3fb8aa3b, v4
	v_fma_f32 v9, v4, s97, -v8
	v_fmac_f32_e32 v9, 0x32a5705f, v4
	v_rndne_f32_e32 v4, v8
	v_sub_f32_e32 v8, v8, v4
	v_add_f32_e32 v8, v8, v9
	v_exp_f32_e32 v8, v8
	v_cvt_i32_f32_e32 v4, v4
	v_cndmask_b32_e64 v2, 0, v2, s[86:87]
	v_cndmask_b32_e64 v0, v181, v0, s[92:93]
	v_cndmask_b32_e64 v2, v181, v2, s[88:89]
	v_ldexp_f32 v4, v8, v4
	v_mul_f32_e32 v8, 0x3fb8aa3b, v6
	v_fma_f32 v9, v6, s97, -v8
	v_fmac_f32_e32 v9, 0x32a5705f, v6
	v_rndne_f32_e32 v6, v8
	v_sub_f32_e32 v8, v8, v6
	v_add_f32_e32 v8, v8, v9
	v_exp_f32_e32 v8, v8
	v_cvt_i32_f32_e32 v6, v6
	v_cndmask_b32_e64 v4, 0, v4, s[82:83]
	v_cndmask_b32_e64 v4, v181, v4, s[84:85]
	v_mov_b32_e32 v97, v129
	v_ldexp_f32 v6, v8, v6
	v_mul_f32_e32 v8, 0x3fb8aa3b, v1
	v_fma_f32 v9, v1, s97, -v8
	v_fmac_f32_e32 v9, 0x32a5705f, v1
	v_rndne_f32_e32 v1, v8
	v_sub_f32_e32 v8, v8, v1
	v_add_f32_e32 v8, v8, v9
	v_exp_f32_e32 v8, v8
	v_cvt_i32_f32_e32 v1, v1
	v_cndmask_b32_e64 v6, 0, v6, s[78:79]
	v_cndmask_b32_e64 v6, v181, v6, s[80:81]
	v_mov_b32_e32 v99, v129
	v_ldexp_f32 v1, v8, v1
	v_mul_f32_e32 v8, 0x3fb8aa3b, v3
	v_fma_f32 v9, v3, s97, -v8
	v_fmac_f32_e32 v9, 0x32a5705f, v3
	v_rndne_f32_e32 v3, v8
	v_sub_f32_e32 v8, v8, v3
	v_add_f32_e32 v8, v8, v9
	v_exp_f32_e32 v8, v8
	v_cvt_i32_f32_e32 v3, v3
	v_cndmask_b32_e64 v1, 0, v1, s[74:75]
	v_cndmask_b32_e64 v1, v181, v1, s[76:77]
	v_ldexp_f32 v3, v8, v3
	v_mul_f32_e32 v8, 0x3fb8aa3b, v5
	v_fma_f32 v9, v5, s97, -v8
	v_fmac_f32_e32 v9, 0x32a5705f, v5
	v_rndne_f32_e32 v5, v8
	v_sub_f32_e32 v8, v8, v5
	v_add_f32_e32 v8, v8, v9
	v_exp_f32_e32 v8, v8
	v_cvt_i32_f32_e32 v5, v5
	v_cndmask_b32_e64 v3, 0, v3, s[70:71]
	s_ashr_i32 s70, s7, 6
	s_cmp_eq_u32 s28, 0
	v_ldexp_f32 v5, v8, v5
	v_mul_f32_e32 v8, 0x3fb8aa3b, v7
	v_fma_f32 v9, v7, s97, -v8
	v_fmac_f32_e32 v9, 0x32a5705f, v7
	v_rndne_f32_e32 v7, v8
	v_sub_f32_e32 v8, v8, v7
	v_add_f32_e32 v8, v8, v9
	v_exp_f32_e32 v8, v8
	v_cvt_i32_f32_e32 v7, v7
	v_cndmask_b32_e64 v5, 0, v5, s[66:67]
	v_cndmask_b32_e64 v5, v181, v5, s[68:69]
	v_cndmask_b32_e64 v3, v181, v3, s[72:73]
	v_ldexp_f32 v7, v8, v7
	v_cndmask_b32_e32 v7, 0, v7, vcc
	v_cndmask_b32_e64 v7, v181, v7, s[64:65]
	s_cselect_b64 s[64:65], -1, 0
	s_cmp_lg_u32 s28, 0
	s_cselect_b64 s[66:67], -1, 0
	s_and_b64 s[22:23], s[64:65], exec
	s_cselect_b32 s22, s95, s13
	s_cselect_b32 s23, s94, s12
	s_ashr_i32 s71, s70, 31
	s_lshl_b64 s[24:25], s[70:71], 26
	s_add_u32 s24, s30, s24
	v_cndmask_b32_e64 v10, v119, v108, s[64:65]
	s_addc_u32 s25, s31, s25
	s_lshl_b32 s9, s9, 1
	s_add_u32 s68, s24, s9
	v_ashrrev_i32_e32 v11, 31, v10
	s_addc_u32 s69, s25, 0
	v_lshlrev_b64 v[10:11], 14, v[10:11]
	s_lshl_b32 s24, s7, 6
	v_lshl_add_u64 v[10:11], s[68:69], 0, v[10:11]
	s_lshl_b32 s28, s8, 1
	s_and_b32 s25, s24, 64
	v_lshl_add_u64 v[14:15], v[10:11], 0, s[28:29]
	v_cndmask_b32_e64 v18, v121, v120, s[64:65]
	v_or_b32_e32 v8, s25, v93
	v_lshl_add_u64 v[14:15], v[14:15], 0, v[128:129]
	v_ashrrev_i32_e32 v19, 31, v18
	v_add_co_u32_e32 v14, vcc, s1, v14
	v_lshlrev_b32_e32 v16, 1, v8
	v_lshlrev_b64 v[18:19], 14, v[18:19]
	v_lshl_add_u64 v[12:13], v[10:11], 0, v[128:129]
	v_addc_co_u32_e32 v15, vcc, 0, v15, vcc
	v_lshl_add_u64 v[10:11], v[10:11], 0, v[16:17]
	v_lshl_add_u64 v[18:19], s[68:69], 0, v[18:19]
	v_add_co_u32_e32 v10, vcc, s2, v10
	v_lshl_add_u64 v[22:23], v[18:19], 0, s[28:29]
	v_cndmask_b32_e64 v24, v123, v122, s[64:65]
	v_addc_co_u32_e32 v11, vcc, 0, v11, vcc
	v_lshl_add_u64 v[22:23], v[22:23], 0, v[128:129]
	v_ashrrev_i32_e32 v25, 31, v24
	v_add_co_u32_e32 v22, vcc, s1, v22
	v_lshlrev_b64 v[24:25], 14, v[24:25]
	v_lshl_add_u64 v[20:21], v[18:19], 0, v[128:129]
	v_addc_co_u32_e32 v23, vcc, 0, v23, vcc
	v_lshl_add_u64 v[18:19], v[18:19], 0, v[16:17]
	v_lshl_add_u64 v[24:25], s[68:69], 0, v[24:25]
	v_add_co_u32_e32 v18, vcc, s2, v18
	v_lshl_add_u64 v[28:29], v[24:25], 0, s[28:29]
	s_nop 0
	v_addc_co_u32_e32 v19, vcc, 0, v19, vcc
	v_lshl_add_u64 v[28:29], v[28:29], 0, v[128:129]
	v_add_co_u32_e32 v28, vcc, s1, v28
	v_lshl_add_u64 v[26:27], v[24:25], 0, v[128:129]
	s_nop 0
	v_addc_co_u32_e32 v29, vcc, 0, v29, vcc
	global_load_dword v144, v[12:13], off
	global_load_dword v145, v[14:15], off
	global_load_ushort v9, v[10:11], off
	global_load_dword v146, v[20:21], off
	global_load_dword v147, v[22:23], off
	global_load_ushort v36, v[18:19], off
	global_load_dword v148, v[26:27], off
	global_load_dword v149, v[28:29], off
	v_cndmask_b32_e64 v12, v125, v124, s[64:65]
	v_ashrrev_i32_e32 v13, 31, v12
	v_lshl_add_u64 v[10:11], v[24:25], 0, v[16:17]
; DI f32x16 zero16() { f32x16 z; for (int i = 0; i < 16; ++i) z[i] = 0.f; return z; }
; #define HG_PREFETCH(cn) do { \
;     _Pragma("unroll") for (int e = 0; e < 8; ++e) { const bf16_t* pr = PROJ + ROWTOK(cn, seg * 8 + e) * 8192 + h * 128; \
;       rq[e] = *(const unsigned*)(pr + 2 * kp); rf[e] = *(const unsigned*)(pr + 2048 + dir * 2048 + 2 * kp); rv[e] = pr[6144 + dh * 64 + lane]; } } while (0)
; DI void hg_scan_phase(int wvs, char* smem, const bf16_t* __restrict__ PROJ, const float* __restrict__ lbraw, bf16_t* OF, bf16_t* OB) {
;     ...
;     float lbv[2];
; #pragma unroll
;     for (int u = 0; u < 2; ++u) {
;       const int idx = dir * 2048 + h * 128 + 2 * kp + u;
;       const float l0 = lbraw[idx], l1 = lbraw[4096 + idx], l2 = lbraw[8192 + idx], l3 = lbraw[12288 + idx];
;       const float mx = fmaxf(fmaxf(l0, l1), fmaxf(l2, l3));
;       const float e0 = expf(l0 - mx), e1 = expf(l1 - mx), e2 = expf(l2 - mx), e3 = expf(l3 - mx);
;       lbv[u] = (e1 + e2) / (e0 + e1 + e2 + e3);
;     }
;     const float lb0 = lbv[0], lb1 = lbv[1];
;     bf16_t* O = dir ? OB : OF;
;     f32x16 sacc = zero16();
;     const int kb = w & 3, db = w >> 2;
;     ...
;     unsigned rq[8], rf[8]; bf16_t rv[8];
;     ...
;     __syncthreads();
;     for (int e = tid; e < 64 * SD / 2; e += NT) ((unsigned*)St)[e] = 0u;
;     HG_PREFETCH(0);
;     ...
;         u32x4 vv;
;         vv[0] = (unsigned)rv[0] | ((unsigned)rv[1] << 16); vv[1] = (unsigned)rv[2] | ((unsigned)rv[3] << 16);
;         vv[2] = (unsigned)rv[4] | ((unsigned)rv[5] << 16); vv[3] = (unsigned)rv[6] | ((unsigned)rv[7] << 16);
	v_lshlrev_b64 v[12:13], 14, v[12:13]
	v_cndmask_b32_e64 v20, v127, v126, s[64:65]
	v_add_co_u32_e32 v10, vcc, s2, v10
	v_lshl_add_u64 v[12:13], s[68:69], 0, v[12:13]
	v_ashrrev_i32_e32 v21, 31, v20
	v_addc_co_u32_e32 v11, vcc, 0, v11, vcc
	v_lshl_add_u64 v[18:19], v[12:13], 0, v[16:17]
	v_lshlrev_b64 v[20:21], 14, v[20:21]
	v_add_co_u32_e32 v18, vcc, s2, v18
	v_lshl_add_u64 v[20:21], s[68:69], 0, v[20:21]
	s_nop 0
	v_addc_co_u32_e32 v19, vcc, 0, v19, vcc
	v_lshl_add_u64 v[22:23], v[20:21], 0, v[16:17]
	v_add_co_u32_e32 v22, vcc, s2, v22
	v_cndmask_b32_e64 v24, v134, v133, s[64:65]
	s_nop 0
	v_addc_co_u32_e32 v23, vcc, 0, v23, vcc
	global_load_ushort v37, v[10:11], off
	global_load_ushort v38, v[18:19], off
	global_load_ushort v39, v[22:23], off
	v_cndmask_b32_e64 v10, v132, v131, s[64:65]
	v_ashrrev_i32_e32 v11, 31, v10
	v_lshlrev_b64 v[10:11], 14, v[10:11]
	v_lshl_add_u64 v[10:11], s[68:69], 0, v[10:11]
	v_lshl_add_u64 v[18:19], v[10:11], 0, s[28:29]
	v_lshl_add_u64 v[18:19], v[18:19], 0, v[128:129]
	v_ashrrev_i32_e32 v25, 31, v24
	v_add_co_u32_e32 v18, vcc, s1, v18
	v_lshlrev_b64 v[24:25], 14, v[24:25]
	s_nop 0
	v_addc_co_u32_e32 v19, vcc, 0, v19, vcc
	v_lshl_add_u64 v[22:23], v[10:11], 0, v[16:17]
	v_lshl_add_u64 v[24:25], s[68:69], 0, v[24:25]
	v_add_co_u32_e32 v22, vcc, s2, v22
	v_lshl_add_u64 v[28:29], v[24:25], 0, s[28:29]
	v_cndmask_b32_e64 v30, v136, v135, s[64:65]
	v_addc_co_u32_e32 v23, vcc, 0, v23, vcc
	v_lshl_add_u64 v[28:29], v[28:29], 0, v[128:129]
	v_ashrrev_i32_e32 v31, 31, v30
	v_add_co_u32_e32 v28, vcc, s1, v28
	v_lshlrev_b64 v[30:31], 14, v[30:31]
	v_lshl_add_u64 v[26:27], v[24:25], 0, v[128:129]
	v_addc_co_u32_e32 v29, vcc, 0, v29, vcc
	v_lshl_add_u64 v[24:25], v[24:25], 0, v[16:17]
	v_lshl_add_u64 v[30:31], s[68:69], 0, v[30:31]
	v_add_co_u32_e32 v24, vcc, s2, v24
	v_lshl_add_u64 v[34:35], v[30:31], 0, s[28:29]
	s_nop 0
	v_addc_co_u32_e32 v25, vcc, 0, v25, vcc
	v_lshl_add_u64 v[34:35], v[34:35], 0, v[128:129]
	v_add_co_u32_e32 v34, vcc, s1, v34
	v_lshl_add_u64 v[16:17], v[30:31], 0, v[16:17]
	s_nop 0
	v_addc_co_u32_e32 v35, vcc, 0, v35, vcc
	v_lshl_add_u64 v[14:15], v[12:13], 0, v[128:129]
	v_add_co_u32_e32 v16, vcc, s2, v16
	v_lshl_add_u64 v[12:13], v[12:13], 0, s[28:29]
	s_nop 0
	v_addc_co_u32_e32 v17, vcc, 0, v17, vcc
	v_lshl_add_u64 v[12:13], v[12:13], 0, v[128:129]
	v_lshl_add_u64 v[32:33], v[30:31], 0, v[128:129]
	global_load_dword v154, v[18:19], off
	s_nop 0
	global_load_ushort v22, v[22:23], off
	s_nop 0
	global_load_dword v156, v[26:27], off
	global_load_dword v157, v[28:29], off
	global_load_ushort v23, v[24:25], off
	global_load_dword v158, v[32:33], off
	global_load_dword v159, v[34:35], off
	s_nop 0
	global_load_ushort v24, v[16:17], off
	v_add_co_u32_e32 v12, vcc, s1, v12
	v_lshl_add_u64 v[18:19], v[20:21], 0, s[28:29]
	s_nop 0
	v_addc_co_u32_e32 v13, vcc, 0, v13, vcc
	v_lshl_add_u64 v[18:19], v[18:19], 0, v[128:129]
	v_add_co_u32_e32 v18, vcc, s1, v18
	v_lshl_add_u64 v[16:17], v[20:21], 0, v[128:129]
	s_nop 0
	v_addc_co_u32_e32 v19, vcc, 0, v19, vcc
	v_lshl_add_u64 v[10:11], v[10:11], 0, v[128:129]
	global_load_dword v150, v[14:15], off
	global_load_dword v152, v[16:17], off
	global_load_dword v155, v[10:11], off
	global_load_dword v153, v[18:19], off
	global_load_dword v151, v[12:13], off
	v_pk_add_f32 v[0:1], v[0:1], v[2:3]
	v_pk_add_f32 v[10:11], v[2:3], v[4:5]
	v_pk_add_f32 v[0:1], v[4:5], v[0:1]
	s_lshl_b64 s[70:71], s[70:71], 24
	v_pk_add_f32 v[0:1], v[6:7], v[0:1]
	s_add_u32 s23, s23, s70
	v_div_scale_f32 v2, s[72:73], v1, v1, v11
	v_rcp_f32_e32 v3, v2
	s_addc_u32 s22, s22, s71
	s_add_u32 s9, s23, s9
	s_addc_u32 s23, s22, 0
	v_fma_f32 v4, -v2, v3, 1.0
	v_fmac_f32_e32 v3, v4, v3
	v_div_scale_f32 v4, vcc, v11, v1, v11
	v_mul_f32_e32 v5, v4, v3
	v_fma_f32 v6, -v2, v5, v4
	v_fmac_f32_e32 v5, v6, v3
	v_fma_f32 v2, -v2, v5, v4
	v_div_scale_f32 v4, s[72:73], v0, v0, v10
	v_rcp_f32_e32 v6, v4
	v_div_fmas_f32 v2, v2, v3, v5
	v_div_fixup_f32 v101, v2, v1, v11
	s_lshl_b32 s22, s25, 1
	v_fma_f32 v1, -v4, v6, 1.0
	v_fmac_f32_e32 v6, v1, v6
	v_div_scale_f32 v1, vcc, v10, v0, v10
	v_mul_f32_e32 v2, v1, v6
	v_fma_f32 v3, -v4, v2, v1
	v_fmac_f32_e32 v2, v3, v6
	v_fma_f32 v1, -v4, v2, v1
	s_add_u32 s22, s9, s22
	v_div_fmas_f32 v1, v1, v6, v2
	s_addc_u32 s23, s23, 0
	v_div_fixup_f32 v100, v1, v0, v10
	v_lshl_add_u64 v[0:1], s[22:23], 0, v[96:97]
	v_lshl_add_u64 v[104:105], v[0:1], 0, v[98:99]
	v_mov_b32_e32 v0, 0
	s_mov_b32 s24, 0
	v_pk_add_f32 v[102:103], v[100:101], 1.0 op_sel_hi:[1,0] neg_lo:[1,0] neg_hi:[1,0]
	s_waitcnt vmcnt(18)
	v_perm_b32 v48, v36, v9, s3
	s_waitcnt vmcnt(14)
	v_perm_b32 v49, v38, v37, s3
	s_lshl_b32 s28, s8, 1
	v_lshlrev_b32_e32 v106, 1, v8
	v_mov_b32_e32 v1, v0
	v_mov_b32_e32 v2, v0
	v_mov_b32_e32 v3, v0
	v_mov_b32_e32 v4, v0
	v_mov_b32_e32 v5, v0
	v_mov_b32_e32 v6, v0
	v_mov_b32_e32 v7, v0
	v_mov_b32_e32 v8, v0
	v_mov_b32_e32 v9, v0
	v_mov_b32_e32 v10, v0
	v_mov_b32_e32 v11, v0
	v_mov_b32_e32 v12, v0
	v_mov_b32_e32 v13, v0
	s_waitcnt vmcnt(11)
	v_perm_b32 v50, v22, v39, s3
	v_mov_b32_e32 v14, v0
	v_mov_b32_e32 v15, v0
	s_waitcnt vmcnt(5)
	v_perm_b32 v51, v24, v23, s3
	s_waitcnt vmcnt(0)
	s_branch .LBB0_378
.Lhg_w47:
	s_waitcnt vmcnt(0)
	s_branch .LBB0_377

; DI unsigned pack2(float a, float b) { f32x2_t v = {a, b}; return __builtin_bit_cast(unsigned, __builtin_convertvector(v, bf16x2_t)); }
; DI void hg_scan_phase(int wvs, char* smem, const bf16_t* __restrict__ PROJ, const float* __restrict__ lbraw, bf16_t* OF, bf16_t* OB) {
;     ...
;       {
;         const int d = db * 32 + r;
; #pragma unroll
;         for (int gq = 0; gq < 4; ++gq) {
;           uint2 pk; pk.x = pack2(sacc[4 * gq], sacc[4 * gq + 1]); pk.y = pack2(sacc[4 * gq + 2], sacc[4 * gq + 3]);
;           *(uint2*)(St + d * SD + kb * 32 + 8 * gq + 4 * hh) = pk;
;         }
;       }
.LBB0_377:
	s_or_b64 exec, exec, s[70:71]
	s_waitcnt vmcnt(4)
	v_mov_b32_e32 v144, v200
	v_mov_b32_e32 v145, v201
	v_mov_b32_e32 v146, v202
	v_mov_b32_e32 v147, v203
	v_mov_b32_e32 v148, v204
	v_mov_b32_e32 v149, v205
	v_mov_b32_e32 v150, v206
	v_mov_b32_e32 v151, v207
	v_mov_b32_e32 v152, v208
	v_mov_b32_e32 v153, v209
	v_mov_b32_e32 v154, v215
	v_mov_b32_e32 v155, v216
	v_mov_b32_e32 v156, v217
	v_mov_b32_e32 v157, v218
	v_mov_b32_e32 v158, v219
	v_mov_b32_e32 v159, v220
	v_perm_b32 v48, v222, v221, s3
	v_perm_b32 v49, v224, v223, s3
	v_perm_b32 v50, v226, v225, s3
	v_perm_b32 v51, v228, v227, s3
	s_nop 8
	v_cvt_pk_bf16_f32 v16, v0, v1
	v_cvt_pk_bf16_f32 v17, v2, v3
	v_cvt_pk_bf16_f32 v18, v4, v5
	v_cvt_pk_bf16_f32 v19, v6, v7
	s_barrier
	ds_write2_b64 v143, v[16:17], v[18:19] offset1:2
	v_cvt_pk_bf16_f32 v16, v8, v9
	v_cvt_pk_bf16_f32 v17, v10, v11
	v_cvt_pk_bf16_f32 v18, v12, v13
	v_cvt_pk_bf16_f32 v19, v14, v15
	s_cmp_eq_u32 s25, 64
	s_mov_b32 s24, s25
	ds_write2_b64 v143, v[16:17], v[18:19] offset0:4 offset1:6
	s_cbranch_scc1 .LBB0_371
.LBB0_378:
	s_cmp_eq_u32 s24, 63
	s_cbranch_scc1 .Lhg_nopf
	s_add_i32 s25, s24, 1
	s_lshl_b32 s8, s25, 6
	v_add_u32_e32 v20, s8, v108
	v_sub_u32_e32 v16, 0xfff, v20
	v_cndmask_b32_e64 v16, v16, v20, s[64:65]
	v_ashrrev_i32_e32 v17, 31, v16
	v_lshlrev_b64 v[16:17], 14, v[16:17]
	v_lshl_add_u64 v[16:17], s[68:69], 0, v[16:17]
	v_lshl_add_u64 v[18:19], v[16:17], 0, v[128:129]
	global_load_dword v200, v[18:19], off
	v_lshl_add_u64 v[18:19], v[16:17], 0, s[28:29]
	v_lshl_add_u64 v[18:19], v[18:19], 0, v[128:129]
	v_add_co_u32_e32 v18, vcc, s1, v18
	v_mov_b32_e32 v107, v129
	s_nop 0
	v_addc_co_u32_e32 v19, vcc, 0, v19, vcc
	v_lshl_add_u64 v[16:17], v[16:17], 0, v[106:107]
	v_add_co_u32_e32 v16, vcc, s2, v16
	global_load_dword v201, v[18:19], off
	s_nop 0
	v_addc_co_u32_e32 v17, vcc, 0, v17, vcc
	global_load_ushort v221, v[16:17], off
	v_add_u32_e32 v16, s8, v120
	v_sub_u32_e32 v16, 0xfff, v16
	v_or_b32_e32 v17, 1, v20
	v_cndmask_b32_e64 v16, v16, v17, s[64:65]
	v_ashrrev_i32_e32 v17, 31, v16
	v_lshlrev_b64 v[16:17], 14, v[16:17]
	v_lshl_add_u64 v[16:17], s[68:69], 0, v[16:17]
	v_lshl_add_u64 v[18:19], v[16:17], 0, v[128:129]
	global_load_dword v202, v[18:19], off
	v_lshl_add_u64 v[18:19], v[16:17], 0, s[28:29]
	v_lshl_add_u64 v[18:19], v[18:19], 0, v[128:129]
	v_add_co_u32_e32 v18, vcc, s1, v18
	v_lshl_add_u64 v[16:17], v[16:17], 0, v[106:107]
	s_nop 0
	v_addc_co_u32_e32 v19, vcc, 0, v19, vcc
	v_add_co_u32_e32 v16, vcc, s2, v16
	global_load_dword v203, v[18:19], off
	s_nop 0
	v_addc_co_u32_e32 v17, vcc, 0, v17, vcc
	global_load_ushort v222, v[16:17], off
	v_add_u32_e32 v16, s8, v122
	v_sub_u32_e32 v16, 0xfff, v16
	v_or_b32_e32 v17, 2, v20
	v_cndmask_b32_e64 v16, v16, v17, s[64:65]
	v_ashrrev_i32_e32 v17, 31, v16
	v_lshlrev_b64 v[16:17], 14, v[16:17]
	v_lshl_add_u64 v[16:17], s[68:69], 0, v[16:17]
	v_lshl_add_u64 v[18:19], v[16:17], 0, v[128:129]
	global_load_dword v204, v[18:19], off
	v_lshl_add_u64 v[18:19], v[16:17], 0, s[28:29]
	v_lshl_add_u64 v[18:19], v[18:19], 0, v[128:129]
	v_add_co_u32_e32 v18, vcc, s1, v18
	v_lshl_add_u64 v[16:17], v[16:17], 0, v[106:107]
	s_nop 0
	v_addc_co_u32_e32 v19, vcc, 0, v19, vcc
	v_add_co_u32_e32 v16, vcc, s2, v16
	global_load_dword v205, v[18:19], off
	s_nop 0
	v_addc_co_u32_e32 v17, vcc, 0, v17, vcc
	global_load_ushort v223, v[16:17], off
	v_add_u32_e32 v16, s8, v124
	v_sub_u32_e32 v16, 0xfff, v16
	v_or_b32_e32 v17, 3, v20
	v_cndmask_b32_e64 v16, v16, v17, s[64:65]
	v_ashrrev_i32_e32 v17, 31, v16
	v_lshlrev_b64 v[16:17], 14, v[16:17]
	v_lshl_add_u64 v[16:17], s[68:69], 0, v[16:17]
	v_lshl_add_u64 v[18:19], v[16:17], 0, v[128:129]
	global_load_dword v206, v[18:19], off
	v_lshl_add_u64 v[18:19], v[16:17], 0, s[28:29]
	v_lshl_add_u64 v[18:19], v[18:19], 0, v[128:129]
	v_add_co_u32_e32 v18, vcc, s1, v18
	v_lshl_add_u64 v[16:17], v[16:17], 0, v[106:107]
	s_nop 0
	v_addc_co_u32_e32 v19, vcc, 0, v19, vcc
	v_add_co_u32_e32 v16, vcc, s2, v16
	global_load_dword v207, v[18:19], off
	s_nop 0
	v_addc_co_u32_e32 v17, vcc, 0, v17, vcc
	global_load_ushort v224, v[16:17], off
	v_add_u32_e32 v16, s8, v126
	v_sub_u32_e32 v16, 0xfff, v16
	v_or_b32_e32 v17, 4, v20
	v_cndmask_b32_e64 v16, v16, v17, s[64:65]
	v_ashrrev_i32_e32 v17, 31, v16
	v_lshlrev_b64 v[16:17], 14, v[16:17]
	v_lshl_add_u64 v[16:17], s[68:69], 0, v[16:17]
	v_lshl_add_u64 v[18:19], v[16:17], 0, v[128:129]
	global_load_dword v208, v[18:19], off
	v_lshl_add_u64 v[18:19], v[16:17], 0, s[28:29]
	v_lshl_add_u64 v[18:19], v[18:19], 0, v[128:129]
	v_add_co_u32_e32 v18, vcc, s1, v18
	v_lshl_add_u64 v[16:17], v[16:17], 0, v[106:107]
	s_nop 0
	v_addc_co_u32_e32 v19, vcc, 0, v19, vcc
	v_add_co_u32_e32 v16, vcc, s2, v16
	global_load_dword v209, v[18:19], off
	s_nop 0
	v_addc_co_u32_e32 v17, vcc, 0, v17, vcc
	global_load_ushort v225, v[16:17], off
	v_add_u32_e32 v16, s8, v131
	v_sub_u32_e32 v16, 0xfff, v16
	v_or_b32_e32 v17, 5, v20
	v_cndmask_b32_e64 v16, v16, v17, s[64:65]
	v_ashrrev_i32_e32 v17, 31, v16
	v_lshlrev_b64 v[16:17], 14, v[16:17]
	v_lshl_add_u64 v[16:17], s[68:69], 0, v[16:17]
	v_lshl_add_u64 v[18:19], v[16:17], 0, v[128:129]
	global_load_dword v216, v[18:19], off
	v_lshl_add_u64 v[18:19], v[16:17], 0, s[28:29]
	v_lshl_add_u64 v[18:19], v[18:19], 0, v[128:129]
	v_add_co_u32_e32 v18, vcc, s1, v18
	v_lshl_add_u64 v[16:17], v[16:17], 0, v[106:107]
	s_nop 0
	v_addc_co_u32_e32 v19, vcc, 0, v19, vcc
	v_add_co_u32_e32 v16, vcc, s2, v16
	global_load_dword v215, v[18:19], off
	s_nop 0
	v_addc_co_u32_e32 v17, vcc, 0, v17, vcc
	global_load_ushort v226, v[16:17], off
	v_add_u32_e32 v16, s8, v133
	v_sub_u32_e32 v16, 0xfff, v16
; DI float lo2f(unsigned v) { return __uint_as_float(v << 16); }
; DI float hi2f(unsigned v) { return __uint_as_float(v & 0xffff0000u); }
; DI void hg_scan_phase(int wvs, char* smem, const bf16_t* __restrict__ PROJ, const float* __restrict__ lbraw, bf16_t* OF, bf16_t* OB) {
;     ...
;       float gl0[8], gl1[8], q0[8], q1[8], k0v[8], k1v[8];
;       float run0 = 0.f, run1 = 0.f;
; #pragma unroll
;       for (int e = 0; e < 8; ++e) {
;         const float fa = lo2f(rf[e]), fb = hi2f(rf[e]);
;         const float sa = __builtin_amdgcn_rcpf(1.f + __builtin_amdgcn_exp2f(-1.4426950408889634f * fa)), sb = __builtin_amdgcn_rcpf(1.f + __builtin_amdgcn_exp2f(-1.4426950408889634f * fb));
;         run0 += __builtin_amdgcn_logf(lb0 + (1.f - lb0) * sa); run1 += __builtin_amdgcn_logf(lb1 + (1.f - lb1) * sb);
;         gl0[e] = run0; gl1[e] = run1;
;         q0[e] = lo2f(rq[e]); q1[e] = hi2f(rq[e]);
;         k0v[e] = (1.f - lb0) * (1.f - sa); k1v[e] = (1.f - lb1) * (1.f - sb);
;       }
;       *(float2*)(tot + seg * 128 + 2 * kp) = make_float2(run0, run1);
;       {
;         u32x4 vv;
;         vv[0] = (unsigned)rv[0] | ((unsigned)rv[1] << 16); vv[1] = (unsigned)rv[2] | ((unsigned)rv[3] << 16);
;         vv[2] = (unsigned)rv[4] | ((unsigned)rv[5] << 16); vv[3] = (unsigned)rv[6] | ((unsigned)rv[7] << 16);
;         *(u32x4*)(Vt + lane * SJ + seg * 8) = vv;
;       }
;       __syncthreads();
	v_or_b32_e32 v17, 6, v20
	v_cndmask_b32_e64 v16, v16, v17, s[64:65]
	v_ashrrev_i32_e32 v17, 31, v16
	v_lshlrev_b64 v[16:17], 14, v[16:17]
	v_lshl_add_u64 v[16:17], s[68:69], 0, v[16:17]
	v_lshl_add_u64 v[18:19], v[16:17], 0, v[128:129]
	global_load_dword v217, v[18:19], off
	v_lshl_add_u64 v[18:19], v[16:17], 0, s[28:29]
	v_lshl_add_u64 v[18:19], v[18:19], 0, v[128:129]
	v_add_co_u32_e32 v18, vcc, s1, v18
	v_lshl_add_u64 v[16:17], v[16:17], 0, v[106:107]
	s_nop 0
	v_addc_co_u32_e32 v19, vcc, 0, v19, vcc
	v_add_co_u32_e32 v16, vcc, s2, v16
	global_load_dword v218, v[18:19], off
	s_nop 0
	v_addc_co_u32_e32 v17, vcc, 0, v17, vcc
	global_load_ushort v227, v[16:17], off
	v_add_u32_e32 v16, s8, v135
	v_sub_u32_e32 v16, 0xfff, v16
	v_or_b32_e32 v17, 7, v20
	v_cndmask_b32_e64 v16, v16, v17, s[64:65]
	v_ashrrev_i32_e32 v17, 31, v16
	v_lshlrev_b64 v[16:17], 14, v[16:17]
	v_lshl_add_u64 v[16:17], s[68:69], 0, v[16:17]
	v_lshl_add_u64 v[18:19], v[16:17], 0, v[128:129]
	global_load_dword v219, v[18:19], off
	v_lshl_add_u64 v[18:19], v[16:17], 0, s[28:29]
	v_lshl_add_u64 v[18:19], v[18:19], 0, v[128:129]
	v_add_co_u32_e32 v18, vcc, 0x1000, v18
	v_lshl_add_u64 v[16:17], v[16:17], 0, v[106:107]
	s_nop 0
	v_addc_co_u32_e32 v19, vcc, 0, v19, vcc
	v_add_co_u32_e32 v16, vcc, 0x3000, v16
	global_load_dword v220, v[18:19], off
	s_nop 0
	v_addc_co_u32_e32 v17, vcc, 0, v17, vcc
	global_load_ushort v228, v[16:17], off
.Lhg_nopf:
	v_lshlrev_b32_e32 v16, 16, v145
	v_and_b32_e32 v17, 0xffff0000, v145
	v_mul_f32_e32 v16, 0xbfb8aa3b, v16
	v_exp_f32_e32 v16, v16
	v_mul_f32_e32 v17, 0xbfb8aa3b, v17
	v_exp_f32_e32 v17, v17
	v_and_b32_e32 v24, 0xffff0000, v159
	v_add_f32_e32 v16, 1.0, v16
	v_rcp_f32_e32 v42, v16
	v_add_f32_e32 v16, 1.0, v17
	v_rcp_f32_e32 v43, v16
	v_mul_f32_e32 v24, 0xbfb8aa3b, v24
	v_fma_f32 v16, v102, v42, v100
	v_log_f32_e32 v34, v16
	v_fma_f32 v17, v103, v43, v101
	v_lshlrev_b32_e32 v16, 16, v147
	v_log_f32_e32 v35, v17
	v_and_b32_e32 v17, 0xffff0000, v147
	v_mul_f32_e32 v16, 0xbfb8aa3b, v16
	v_exp_f32_e32 v16, v16
	v_mul_f32_e32 v17, 0xbfb8aa3b, v17
	v_exp_f32_e32 v17, v17
	v_exp_f32_e32 v24, v24
	v_add_f32_e32 v16, 1.0, v16
	v_rcp_f32_e32 v38, v16
	v_add_f32_e32 v16, 1.0, v17
	v_rcp_f32_e32 v39, v16
	v_and_b32_e32 v17, 0xffff0000, v149
	v_fma_f32 v16, v102, v38, v100
	v_log_f32_e32 v36, v16
	v_fma_f32 v16, v103, v39, v101
	v_log_f32_e32 v37, v16
	v_lshlrev_b32_e32 v16, 16, v149
	v_mul_f32_e32 v16, 0xbfb8aa3b, v16
	v_exp_f32_e32 v16, v16
	v_mul_f32_e32 v17, 0xbfb8aa3b, v17
	v_exp_f32_e32 v17, v17
	v_pk_add_f32 v[70:71], v[34:35], 0 op_sel_hi:[1,0]
	v_add_f32_e32 v16, 1.0, v16
	v_rcp_f32_e32 v28, v16
	v_add_f32_e32 v16, 1.0, v17
	v_rcp_f32_e32 v29, v16
	v_and_b32_e32 v17, 0xffff0000, v151
	v_fma_f32 v16, v102, v28, v100
	v_log_f32_e32 v46, v16
	v_fma_f32 v16, v103, v29, v101
	v_log_f32_e32 v47, v16
	v_lshlrev_b32_e32 v16, 16, v151
	v_mul_f32_e32 v16, 0xbfb8aa3b, v16
	v_exp_f32_e32 v16, v16
	v_mul_f32_e32 v17, 0xbfb8aa3b, v17
	v_exp_f32_e32 v17, v17
	v_pk_add_f32 v[72:73], v[70:71], v[36:37]
	v_add_f32_e32 v16, 1.0, v16
	v_rcp_f32_e32 v26, v16
	v_add_f32_e32 v16, 1.0, v17
	v_rcp_f32_e32 v27, v16
	v_and_b32_e32 v17, 0xffff0000, v153
	v_fma_f32 v16, v102, v26, v100
	v_log_f32_e32 v56, v16
	v_fma_f32 v16, v103, v27, v101
	v_log_f32_e32 v57, v16
	v_lshlrev_b32_e32 v16, 16, v153
	v_mul_f32_e32 v16, 0xbfb8aa3b, v16
	v_exp_f32_e32 v16, v16
	v_mul_f32_e32 v17, 0xbfb8aa3b, v17
	v_exp_f32_e32 v17, v17
	v_pk_add_f32 v[74:75], v[72:73], v[46:47]
	v_add_f32_e32 v16, 1.0, v16
	v_rcp_f32_e32 v22, v16
	v_add_f32_e32 v16, 1.0, v17
	v_rcp_f32_e32 v23, v16
	v_and_b32_e32 v17, 0xffff0000, v154
	v_fma_f32 v16, v102, v22, v100
	v_log_f32_e32 v58, v16
	v_fma_f32 v16, v103, v23, v101
	v_log_f32_e32 v59, v16
	v_lshlrev_b32_e32 v16, 16, v154
	v_mul_f32_e32 v16, 0xbfb8aa3b, v16
	v_exp_f32_e32 v16, v16
	v_mul_f32_e32 v17, 0xbfb8aa3b, v17
	v_exp_f32_e32 v17, v17
	v_pk_add_f32 v[76:77], v[74:75], v[56:57]
	v_add_f32_e32 v16, 1.0, v16
	v_rcp_f32_e32 v20, v16
	v_add_f32_e32 v16, 1.0, v17
	v_rcp_f32_e32 v21, v16
	v_and_b32_e32 v17, 0xffff0000, v157
	v_fma_f32 v16, v102, v20, v100
	v_log_f32_e32 v60, v16
	v_fma_f32 v16, v103, v21, v101
	v_log_f32_e32 v61, v16
	v_lshlrev_b32_e32 v16, 16, v157
	v_mul_f32_e32 v16, 0xbfb8aa3b, v16
	v_exp_f32_e32 v16, v16
	v_mul_f32_e32 v17, 0xbfb8aa3b, v17
	v_exp_f32_e32 v17, v17
	v_pk_add_f32 v[78:79], v[76:77], v[58:59]
	v_add_f32_e32 v16, 1.0, v16
	v_rcp_f32_e32 v18, v16
	v_add_f32_e32 v16, 1.0, v17
	v_lshlrev_b32_e32 v17, 16, v159
	v_rcp_f32_e32 v19, v16
	v_mul_f32_e32 v17, 0xbfb8aa3b, v17
	v_exp_f32_e32 v17, v17
	v_fma_f32 v16, v102, v18, v100
	v_log_f32_e32 v62, v16
	v_fma_f32 v16, v103, v19, v101
	v_log_f32_e32 v63, v16
	v_add_f32_e32 v16, 1.0, v17
	v_rcp_f32_e32 v16, v16
	v_add_f32_e32 v17, 1.0, v24
	v_rcp_f32_e32 v17, v17
	v_pk_add_f32 v[56:57], v[78:79], v[60:61]
	v_fma_f32 v25, v102, v16, v100
	v_log_f32_e32 v64, v25
	v_fma_f32 v25, v103, v17, v101
	v_log_f32_e32 v65, v25
	v_pk_add_f32 v[46:47], v[56:57], v[62:63]
	v_lshlrev_b32_e32 v54, 16, v144
	v_and_b32_e32 v55, 0xffff0000, v144
	v_pk_add_f32 v[36:37], v[46:47], v[64:65]
	ds_write_b64 v110, v[36:37]
	ds_write_b128 v111, v[48:51]
	s_waitcnt lgkmcnt(0)
	s_barrier
; DI unsigned pack2(float a, float b) { f32x2_t v = {a, b}; return __builtin_bit_cast(unsigned, __builtin_convertvector(v, bf16x2_t)); }
; DI void hg_scan_phase(int wvs, char* smem, const bf16_t* __restrict__ PROJ, const float* __restrict__ lbraw, bf16_t* OF, bf16_t* OB) {
;     ...
;       {
;         float pre0 = 0.f, pre1 = 0.f, gm0 = 0.f, gm1 = 0.f, ga0 = 0.f, ga1 = 0.f;
; #pragma unroll
;         for (int s2 = 0; s2 < 8; ++s2) {
;           const float2 tv = *(const float2*)(tot + s2 * 128 + 2 * kp);
;           if (s2 < seg) { pre0 += tv.x; pre1 += tv.y; }
;           if (s2 < 4) { gm0 += tv.x; gm1 += tv.y; }
;           ga0 += tv.x; ga1 += tv.y;
;         }
;         const float egm0 = __builtin_amdgcn_exp2f(gm0), egm1 = __builtin_amdgcn_exp2f(gm1), e63m0 = __builtin_amdgcn_exp2f(ga0 - gm0), e63m1 = __builtin_amdgcn_exp2f(ga1 - gm1);
;         float kh0[8], kh1[8];
; #pragma unroll
;         for (int e = 0; e < 8; ++e) {
;           const int il = seg * 8 + e;
;           const float d0 = pre0 + gl0[e] - gm0, d1 = pre1 + gl1[e] - gm1;
;           const float qt0 = q0[e] * __builtin_amdgcn_exp2f(d0), qt1 = q1[e] * __builtin_amdgcn_exp2f(d1);
;           const float kt0 = k0v[e] * __builtin_amdgcn_exp2f(-d0), kt1 = k1v[e] * __builtin_amdgcn_exp2f(-d1);
;           *(unsigned*)(Qt + il * SD + 2 * kp) = pack2(qt0, qt1);
;           *(unsigned*)(Qh + il * SD + 2 * kp) = pack2(qt0 * egm0, qt1 * egm1);
;           *(unsigned*)(Kt + il * SD + 2 * kp) = pack2(kt0, kt1);
;           kh0[e] = kt0 * e63m0; kh1[e] = kt1 * e63m1;
;         }
;         *(bf16x8*)(Kht + (2 * kp) * SJ + seg * 8) = pack8f(kh0);
;         *(bf16x8*)(Kht + (2 * kp + 1) * SJ + seg * 8) = pack8f(kh1);
	ds_read2st64_b64 v[58:61], v109 offset1:1
	ds_read2st64_b64 v[62:65], v109 offset0:2 offset1:3
	v_pk_add_f32 v[42:43], v[42:43], 1.0 op_sel_hi:[1,0] neg_lo:[1,0] neg_hi:[1,0]
	v_lshlrev_b32_e32 v52, 16, v146
	v_pk_mul_f32 v[42:43], v[102:103], v[42:43]
	s_waitcnt lgkmcnt(1)
	v_add_f32_e32 v58, 0, v58
	v_add_f32_e32 v59, 0, v59
	v_cndmask_b32_e64 v66, 0, v59, s[48:49]
	v_cndmask_b32_e64 v67, 0, v58, s[48:49]
	v_add_f32_e32 v68, v67, v60
	v_add_f32_e32 v69, v66, v61
	v_cndmask_b32_e64 v66, v66, v69, s[50:51]
	v_cndmask_b32_e64 v67, v67, v68, s[50:51]
	v_add_f32_e32 v58, v58, v60
	v_add_f32_e32 v60, v59, v61
	s_waitcnt lgkmcnt(0)
	v_add_f32_e32 v59, v67, v62
	v_add_f32_e32 v61, v66, v63
	v_cndmask_b32_e64 v66, v66, v61, s[52:53]
	v_cndmask_b32_e64 v67, v67, v59, s[52:53]
	v_add_f32_e32 v59, v58, v62
	v_add_f32_e32 v81, v60, v63
	ds_read2st64_b64 v[60:63], v109 offset0:4 offset1:5
	v_add_f32_e32 v58, v67, v64
	v_add_f32_e32 v68, v66, v65
	v_cndmask_b32_e64 v80, v66, v68, s[54:55]
	v_cndmask_b32_e64 v58, v67, v58, s[54:55]
	ds_read2st64_b64 v[66:69], v109 offset0:6 offset1:7
	s_waitcnt lgkmcnt(1)
	v_add_f32_e32 v82, v58, v60
	v_add_f32_e32 v83, v80, v61
	v_cndmask_b32_e64 v80, v80, v83, s[56:57]
	v_cndmask_b32_e64 v58, v58, v82, s[56:57]
	v_add_f32_e32 v82, v58, v62
	v_add_f32_e32 v83, v80, v63
	v_cndmask_b32_e64 v80, v80, v83, s[58:59]
	v_cndmask_b32_e64 v58, v58, v82, s[58:59]
	s_waitcnt lgkmcnt(0)
	v_add_f32_e32 v82, v58, v66
	v_add_f32_e32 v83, v80, v67
	v_cndmask_b32_e64 v80, v80, v83, s[60:61]
	v_cndmask_b32_e64 v58, v58, v82, s[60:61]
	v_add_f32_e32 v83, v58, v68
	v_add_f32_e32 v82, v80, v69
	v_cndmask_b32_e64 v82, v80, v82, s[62:63]
	v_cndmask_b32_e64 v84, v58, v83, s[62:63]
	v_mov_b32_e32 v58, v70
	v_mov_b32_e32 v85, v64
	v_mov_b32_e32 v80, v71
	v_mov_b32_e32 v83, v65
	v_pk_add_f32 v[86:87], v[58:59], v[84:85]
	v_pk_add_f32 v[64:65], v[80:81], v[82:83]
	v_add_f32_e32 v58, v87, v60
	v_add_f32_e32 v60, v65, v61
	v_add_f32_e32 v58, v58, v62
	v_add_f32_e32 v60, v60, v63
	v_add_f32_e32 v58, v58, v66
	v_add_f32_e32 v60, v60, v67
	v_add_f32_e32 v59, v58, v68
	v_sub_f32_e32 v68, v86, v87
	v_add_f32_e32 v60, v60, v69
	v_sub_f32_e32 v69, v64, v65
	v_exp_f32_e32 v66, v68
	v_exp_f32_e32 v67, v69
	v_exp_f32_e32 v62, v87
	v_exp_f32_e32 v63, v65
	v_exp_f32_e64 v68, -v68
	v_exp_f32_e64 v69, -v69
	v_sub_f32_e32 v61, v60, v65
	v_pk_mul_f32 v[54:55], v[66:67], v[54:55]
	v_exp_f32_e32 v64, v61
	v_cvt_pk_bf16_f32 v61, v54, v55
	v_pk_mul_f32 v[54:55], v[62:63], v[54:55]
	v_pk_mul_f32 v[42:43], v[42:43], v[68:69]
	v_cvt_pk_bf16_f32 v68, v54, v55
	v_add_f32_e32 v54, v72, v84
	v_sub_f32_e32 v66, v54, v87
	v_add_f32_e32 v54, v73, v82
	v_sub_f32_e32 v67, v54, v65
	v_exp_f32_e32 v54, v66
	v_exp_f32_e32 v55, v67
	v_exp_f32_e64 v66, -v66
	v_exp_f32_e64 v67, -v67
	v_and_b32_e32 v53, 0xffff0000, v146
	v_pk_mul_f32 v[52:53], v[54:55], v[52:53]
	v_pk_add_f32 v[38:39], v[38:39], 1.0 op_sel_hi:[1,0] neg_lo:[1,0] neg_hi:[1,0]
	v_cvt_pk_bf16_f32 v54, v52, v53
	v_pk_mul_f32 v[38:39], v[102:103], v[38:39]
	v_pk_mul_f32 v[52:53], v[62:63], v[52:53]
	v_pk_mul_f32 v[38:39], v[38:39], v[66:67]
	ds_write2_b32 v94, v61, v54 offset1:68
	v_cvt_pk_bf16_f32 v52, v52, v53
	v_add_u32_e32 v61, 0x4400, v94
	v_cvt_pk_bf16_f32 v69, v42, v43
	ds_write2_b32 v61, v68, v52 offset1:68
	v_cvt_pk_bf16_f32 v52, v38, v39
	v_add_u32_e32 v66, 0x8800, v94
	ds_write2_b32 v66, v69, v52 offset1:68
	v_mov_b32_e32 v52, v42
	v_add_f32_e32 v42, v74, v84
	v_sub_f32_e32 v54, v42, v87
	v_add_f32_e32 v42, v75, v82
	v_sub_f32_e32 v55, v42, v65
	v_mov_b32_e32 v53, v38
	v_mov_b32_e32 v38, v43
	v_exp_f32_e32 v42, v54
	v_exp_f32_e32 v43, v55
	v_exp_f32_e64 v54, -v54
	v_exp_f32_e64 v55, -v55
	v_lshlrev_b32_e32 v44, 16, v148
	v_and_b32_e32 v45, 0xffff0000, v148
	v_pk_add_f32 v[28:29], v[28:29], 1.0 op_sel_hi:[1,0] neg_lo:[1,0] neg_hi:[1,0]
	v_pk_mul_f32 v[42:43], v[42:43], v[44:45]
	v_pk_mul_f32 v[28:29], v[102:103], v[28:29]
	v_lshlrev_b32_e32 v40, 16, v150
	v_pk_mul_f32 v[28:29], v[28:29], v[54:55]
	v_cvt_pk_bf16_f32 v54, v42, v43
	v_pk_mul_f32 v[42:43], v[62:63], v[42:43]
	v_and_b32_e32 v41, 0xffff0000, v150
	v_cvt_pk_bf16_f32 v55, v42, v43
	v_add_f32_e32 v42, v76, v84
	v_sub_f32_e32 v44, v42, v87
	v_add_f32_e32 v42, v77, v82
	v_sub_f32_e32 v45, v42, v65
	v_exp_f32_e32 v42, v44
	v_exp_f32_e32 v43, v45
	v_exp_f32_e64 v44, -v44
	v_exp_f32_e64 v45, -v45
	v_pk_add_f32 v[26:27], v[26:27], 1.0 op_sel_hi:[1,0] neg_lo:[1,0] neg_hi:[1,0]
	v_pk_mul_f32 v[40:41], v[42:43], v[40:41]
	v_pk_mul_f32 v[26:27], v[102:103], v[26:27]
	v_cvt_pk_bf16_f32 v42, v40, v41
	v_pk_mul_f32 v[40:41], v[62:63], v[40:41]
	v_pk_mul_f32 v[26:27], v[26:27], v[44:45]
	v_cvt_pk_bf16_f32 v40, v40, v41
	v_cvt_pk_bf16_f32 v67, v28, v29
	ds_write2_b32 v61, v55, v40 offset0:136 offset1:204
	v_cvt_pk_bf16_f32 v40, v26, v27
	ds_write2_b32 v66, v67, v40 offset0:136 offset1:204
	v_mov_b32_e32 v40, v28
	v_add_f32_e32 v28, v78, v84
	ds_write2_b32 v94, v54, v42 offset0:136 offset1:204
	v_sub_f32_e32 v42, v28, v87
	v_add_f32_e32 v28, v79, v82
	v_sub_f32_e32 v43, v28, v65
	v_mov_b32_e32 v41, v26
	v_mov_b32_e32 v26, v29
	v_exp_f32_e32 v28, v42
	v_exp_f32_e32 v29, v43
	v_exp_f32_e64 v42, -v42
	v_exp_f32_e64 v43, -v43
	v_lshlrev_b32_e32 v32, 16, v152
	v_and_b32_e32 v33, 0xffff0000, v152
	v_pk_add_f32 v[22:23], v[22:23], 1.0 op_sel_hi:[1,0] neg_lo:[1,0] neg_hi:[1,0]
	v_pk_mul_f32 v[28:29], v[28:29], v[32:33]
	v_pk_mul_f32 v[22:23], v[102:103], v[22:23]
	v_lshlrev_b32_e32 v30, 16, v155
	v_pk_mul_f32 v[22:23], v[22:23], v[42:43]
	v_cvt_pk_bf16_f32 v42, v28, v29
	v_pk_mul_f32 v[28:29], v[62:63], v[28:29]
	v_and_b32_e32 v31, 0xffff0000, v155
	v_cvt_pk_bf16_f32 v43, v28, v29
; DI void hg_scan_phase(int wvs, char* smem, const bf16_t* __restrict__ PROJ, const float* __restrict__ lbraw, bf16_t* OF, bf16_t* OB) {
;     ...
;         float kh0[8], kh1[8];
; #pragma unroll
;         for (int e = 0; e < 8; ++e) {
;           const int il = seg * 8 + e;
;           const float d0 = pre0 + gl0[e] - gm0, d1 = pre1 + gl1[e] - gm1;
;           const float qt0 = q0[e] * __builtin_amdgcn_exp2f(d0), qt1 = q1[e] * __builtin_amdgcn_exp2f(d1);
;           const float kt0 = k0v[e] * __builtin_amdgcn_exp2f(-d0), kt1 = k1v[e] * __builtin_amdgcn_exp2f(-d1);
;           *(unsigned*)(Qt + il * SD + 2 * kp) = pack2(qt0, qt1);
;           *(unsigned*)(Qh + il * SD + 2 * kp) = pack2(qt0 * egm0, qt1 * egm1);
;           *(unsigned*)(Kt + il * SD + 2 * kp) = pack2(kt0, kt1);
;           kh0[e] = kt0 * e63m0; kh1[e] = kt1 * e63m1;
;         }
;         *(bf16x8*)(Kht + (2 * kp) * SJ + seg * 8) = pack8f(kh0);
;         *(bf16x8*)(Kht + (2 * kp + 1) * SJ + seg * 8) = pack8f(kh1);
;         if (seg == 0) *(float2*)(eG + 2 * kp) = make_float2(__builtin_amdgcn_exp2f(ga0), __builtin_amdgcn_exp2f(ga1));
;       }
;       __syncthreads();
;       if (ci + 1 < 64) HG_PREFETCH(ci + 1);
;       {
; #pragma unroll
;         for (int gq = 0; gq < 4; ++gq) {
;           const float4 ev = *(const float4*)(eG + kb * 32 + 8 * gq + 4 * hh);
;           sacc[4 * gq] *= ev.x; sacc[4 * gq + 1] *= ev.y; sacc[4 * gq + 2] *= ev.z; sacc[4 * gq + 3] *= ev.w;
;         }
;         bf16x8 kq[4], vq[4];
; #pragma unroll
;         for (int kk = 0; kk < 4; ++kk) { kq[kk] = ldfrag(Kht + (kb * 32 + r) * SJ + kk * 16 + 8 * hh); vq[kk] = ldfrag(Vt + (db * 32 + r) * SJ + kk * 16 + 8 * hh); }
;         __builtin_amdgcn_sched_barrier(0);
; #pragma unroll
;         for (int kk = 0; kk < 4; ++kk) sacc = MFMA(kq[kk], vq[kk], sacc);
;       }
;       if (w < 4) {
;         const int db2 = w & 1, ib2 = w >> 1;
;         const int i = ib2 * 32 + r;
;         f32x16 oacc = zero16();
;         {
;           bf16x8 sq[8], hq[8];
; #pragma unroll
;           for (int kk = 0; kk < 8; ++kk) { sq[kk] = ldfrag(St + (db2 * 32 + r) * SD + kk * 16 + 8 * hh); hq[kk] = ldfrag(Qh + (ib2 * 32 + r) * SD + kk * 16 + 8 * hh); }
;           __builtin_amdgcn_sched_barrier(0);
; #pragma unroll
;           for (int kk = 0; kk < 8; ++kk) oacc = MFMA(sq[kk], hq[kk], oacc);
;           __builtin_amdgcn_sched_barrier(0);
;         }
	v_add_f32_e32 v28, v56, v84
	v_sub_f32_e32 v32, v28, v87
	v_add_f32_e32 v28, v57, v82
	v_sub_f32_e32 v33, v28, v65
	v_exp_f32_e32 v28, v32
	v_exp_f32_e32 v29, v33
	v_exp_f32_e64 v32, -v32
	v_exp_f32_e64 v33, -v33
	v_pk_add_f32 v[20:21], v[20:21], 1.0 op_sel_hi:[1,0] neg_lo:[1,0] neg_hi:[1,0]
	v_pk_mul_f32 v[28:29], v[28:29], v[30:31]
	v_pk_mul_f32 v[20:21], v[102:103], v[20:21]
	v_cvt_pk_bf16_f32 v30, v28, v29
	v_pk_mul_f32 v[28:29], v[62:63], v[28:29]
	v_pk_mul_f32 v[20:21], v[20:21], v[32:33]
	v_add_u32_e32 v32, 0x400, v94
	v_cvt_pk_bf16_f32 v28, v28, v29
	v_add_u32_e32 v33, 0x4800, v94
	v_cvt_pk_bf16_f32 v44, v22, v23
	ds_write2_b32 v32, v42, v30 offset0:16 offset1:84
	ds_write2_b32 v33, v43, v28 offset0:16 offset1:84
	v_cvt_pk_bf16_f32 v28, v20, v21
	v_add_u32_e32 v42, 0x8c00, v94
	ds_write2_b32 v42, v44, v28 offset0:16 offset1:84
	v_mov_b32_e32 v28, v22
	v_add_f32_e32 v22, v46, v84
	v_sub_f32_e32 v30, v22, v87
	v_add_f32_e32 v22, v47, v82
	v_sub_f32_e32 v31, v22, v65
	v_mov_b32_e32 v29, v20
	v_mov_b32_e32 v20, v23
	v_exp_f32_e32 v22, v30
	v_exp_f32_e32 v23, v31
	v_exp_f32_e64 v30, -v30
	v_exp_f32_e64 v31, -v31
	v_lshlrev_b32_e32 v24, 16, v156
	v_and_b32_e32 v25, 0xffff0000, v156
	v_pk_add_f32 v[18:19], v[18:19], 1.0 op_sel_hi:[1,0] neg_lo:[1,0] neg_hi:[1,0]
	v_pk_mul_f32 v[22:23], v[22:23], v[24:25]
	v_pk_mul_f32 v[18:19], v[102:103], v[18:19]
	v_lshlrev_b32_e32 v34, 16, v158
	v_pk_mul_f32 v[18:19], v[18:19], v[30:31]
	v_cvt_pk_bf16_f32 v30, v22, v23
	v_pk_mul_f32 v[22:23], v[62:63], v[22:23]
	v_and_b32_e32 v35, 0xffff0000, v158
	v_cvt_pk_bf16_f32 v31, v22, v23
	v_add_f32_e32 v22, v36, v84
	v_sub_f32_e32 v24, v22, v87
	v_add_f32_e32 v22, v37, v82
	v_sub_f32_e32 v25, v22, v65
	v_exp_f32_e32 v22, v24
	v_exp_f32_e32 v23, v25
	v_exp_f32_e64 v24, -v24
	v_exp_f32_e64 v25, -v25
	v_pk_add_f32 v[16:17], v[16:17], 1.0 op_sel_hi:[1,0] neg_lo:[1,0] neg_hi:[1,0]
	v_sub_f32_e32 v58, v59, v87
	v_pk_mul_f32 v[22:23], v[22:23], v[34:35]
	v_pk_mul_f32 v[16:17], v[102:103], v[16:17]
	v_exp_f32_e32 v58, v58
	v_pk_mul_f32 v[16:17], v[16:17], v[24:25]
	v_cvt_pk_bf16_f32 v24, v22, v23
	v_pk_mul_f32 v[22:23], v[62:63], v[22:23]
	v_cvt_pk_bf16_f32 v36, v18, v19
	v_cvt_pk_bf16_f32 v22, v22, v23
	ds_write2_b32 v33, v31, v22 offset0:152 offset1:220
	v_cvt_pk_bf16_f32 v22, v16, v17
	ds_write2_b32 v42, v36, v22 offset0:152 offset1:220
	v_mov_b32_e32 v22, v18
	v_mov_b32_e32 v23, v16
	v_pk_mul_f32 v[52:53], v[58:59], v[52:53] op_sel_hi:[0,1]
	v_pk_mul_f32 v[40:41], v[58:59], v[40:41] op_sel_hi:[0,1]
	v_pk_mul_f32 v[28:29], v[58:59], v[28:29] op_sel_hi:[0,1]
	v_pk_mul_f32 v[22:23], v[58:59], v[22:23] op_sel_hi:[0,1]
	v_mov_b32_e32 v16, v19
	v_pk_mul_f32 v[38:39], v[64:65], v[38:39] op_sel_hi:[0,1]
	v_pk_mul_f32 v[26:27], v[64:65], v[26:27] op_sel_hi:[0,1]
	v_pk_mul_f32 v[20:21], v[64:65], v[20:21] op_sel_hi:[0,1]
	ds_write2_b32 v32, v30, v24 offset0:152 offset1:220
	v_pk_mul_f32 v[24:25], v[64:65], v[16:17] op_sel_hi:[0,1]
	v_cvt_pk_bf16_f32 v16, v52, v53
	v_cvt_pk_bf16_f32 v17, v40, v41
	v_cvt_pk_bf16_f32 v18, v28, v29
	v_cvt_pk_bf16_f32 v19, v22, v23
	ds_write_b128 v112, v[16:19] offset:52224
	v_cvt_pk_bf16_f32 v16, v38, v39
	v_cvt_pk_bf16_f32 v17, v26, v27
	v_cvt_pk_bf16_f32 v18, v20, v21
	v_cvt_pk_bf16_f32 v19, v24, v25
	ds_write_b128 v112, v[16:19] offset:52368
	s_and_saveexec_b64 s[22:23], s[42:43]
	s_cbranch_execz .LBB0_380
	v_exp_f32_e32 v16, v59
	v_exp_f32_e32 v17, v60
	ds_write_b64 v115, v[16:17]
.LBB0_380:
	s_or_b64 exec, exec, s[22:23]
	s_add_i32 s25, s24, 1
	s_cmp_eq_u32 s24, 63
	s_waitcnt lgkmcnt(0)
	s_barrier
.LBB0_382:
	ds_read_b128 v[16:19], v142
	ds_read_b128 v[20:23], v142 offset:32
	ds_read_b128 v[24:27], v142 offset:64
	ds_read_b128 v[28:31], v142 offset:96
	ds_read_b128 v[32:35], v113 offset:52224
	ds_read_b128 v[36:39], v113 offset:52256
	ds_read_b128 v[40:43], v114
	ds_read_b128 v[44:47], v114 offset:32
	ds_read_b128 v[52:55], v113 offset:52288
	ds_read_b128 v[56:59], v113 offset:52320
	ds_read_b128 v[60:63], v114 offset:64
	ds_read_b128 v[64:67], v114 offset:96
	s_waitcnt lgkmcnt(8)
	v_pk_mul_f32 v[12:13], v[12:13], v[28:29]
	v_pk_mul_f32 v[8:9], v[8:9], v[24:25]
	v_pk_mul_f32 v[4:5], v[4:5], v[20:21]
	v_pk_mul_f32 v[0:1], v[0:1], v[16:17]
	v_pk_mul_f32 v[14:15], v[14:15], v[30:31]
	v_pk_mul_f32 v[10:11], v[10:11], v[26:27]
	v_pk_mul_f32 v[6:7], v[6:7], v[22:23]
	v_pk_mul_f32 v[2:3], v[2:3], v[18:19]
	s_waitcnt lgkmcnt(5)
	s_nop 0
	v_mfma_f32_32x32x16_bf16 v[0:15], v[32:35], v[40:43], v[0:15]
	s_waitcnt lgkmcnt(4)
	v_mfma_f32_32x32x16_bf16 v[0:15], v[36:39], v[44:47], v[0:15]
	s_waitcnt lgkmcnt(1)
	v_mfma_f32_32x32x16_bf16 v[0:15], v[52:55], v[60:63], v[0:15]
	s_waitcnt lgkmcnt(0)
	v_mfma_f32_32x32x16_bf16 v[0:15], v[56:59], v[64:67], v[0:15]
	s_and_saveexec_b64 s[70:71], s[44:45]
	s_cbranch_execz .Lhg_w47
	ds_read_b128 v[16:19], v117
	ds_read_b128 v[32:35], v117 offset:32
	ds_read_b128 v[20:23], v118 offset:17408
	ds_read_b128 v[36:39], v118 offset:17440
	ds_read_b128 v[40:43], v117 offset:64
	ds_read_b128 v[44:47], v117 offset:96
	ds_read_b128 v[52:55], v118 offset:17472
	ds_read_b128 v[56:59], v118 offset:17504
	ds_read_b128 v[60:63], v117 offset:128
	ds_read_b128 v[64:67], v117 offset:160
	ds_read_b128 v[68:71], v118 offset:17536
	ds_read_b128 v[72:75], v118 offset:17568
	ds_read_b128 v[76:79], v117 offset:192
	ds_read_b128 v[80:83], v117 offset:224
	ds_read_b128 v[84:87], v118 offset:17600
	ds_read_b128 v[88:91], v118 offset:17632
	s_waitcnt lgkmcnt(13)
	v_mfma_f32_32x32x16_bf16 v[16:31], v[16:19], v[20:23], 0
	s_waitcnt lgkmcnt(12)
	v_mfma_f32_32x32x16_bf16 v[16:31], v[32:35], v[36:39], v[16:31]
	s_waitcnt lgkmcnt(9)
	v_mfma_f32_32x32x16_bf16 v[16:31], v[40:43], v[52:55], v[16:31]
	s_waitcnt lgkmcnt(8)
	v_mfma_f32_32x32x16_bf16 v[16:31], v[44:47], v[56:59], v[16:31]
	s_waitcnt lgkmcnt(5)
	v_mfma_f32_32x32x16_bf16 v[16:31], v[60:63], v[68:71], v[16:31]
	s_waitcnt lgkmcnt(4)
	v_mfma_f32_32x32x16_bf16 v[16:31], v[64:67], v[72:75], v[16:31]
	s_waitcnt lgkmcnt(1)
	v_mfma_f32_32x32x16_bf16 v[16:31], v[76:79], v[84:87], v[16:31]
	s_waitcnt lgkmcnt(0)
	v_mfma_f32_32x32x16_bf16 v[16:31], v[80:83], v[88:91], v[16:31]
	s_and_saveexec_b64 s[72:73], s[46:47]
	s_cbranch_execz .LBB0_387
	ds_read_b128 v[52:55], v118
	ds_read_b128 v[56:59], v118 offset:32
	ds_read_b128 v[60:63], v118 offset:64
	ds_read_b128 v[64:67], v118 offset:96
	ds_read_b128 v[68:71], v118 offset:128
	ds_read_b128 v[72:75], v118 offset:160
	ds_read_b128 v[76:79], v118 offset:192
	ds_read_b128 v[80:83], v118 offset:224
	s_mov_b64 s[74:75], 0
	v_mov_b32_e32 v97, v141
	v_mov_b32_e32 v99, v140
	v_mov_b32_e32 v107, v139
	v_mov_b32_e32 v160, v138

; #define MFMA(a, b, c) __builtin_amdgcn_mfma_f32_32x32x16_bf16((a), (b), (c), 0, 0, 0)
; DI f32x16 zero16() { f32x16 z; for (int i = 0; i < 16; ++i) z[i] = 0.f; return z; }
;     ...
;   const int fP = r * 128, fsw = (r >> 1) & 7;
;   const int fA = wm * 8192 + fP, fB = 32768 + wn * 16384 + fP;
;   f32x16 acc[2][4];
; #pragma unroll
;   for (int i = 0; i < 2; ++i)
; #pragma unroll
;     for (int j = 0; j < 4; ++j) acc[i][j] = zero16();
;   __syncthreads();
;   G_DMA(0, 0);
;   asm volatile("s_waitcnt vmcnt(0)" ::: "memory");
;   asm volatile("s_waitcnt lgkmcnt(0)" ::: "memory"); __builtin_amdgcn_s_barrier(); asm volatile("" ::: "memory");
;   int cur = 0;
;   for (int s = 0; s < S; ++s) {
;     G_DMA(s + 1, cur ^ BUFB);
;     {
;       const char* Ab = smem + cur + fA;
;       const char* Bb = smem + cur + fB;
;       __builtin_amdgcn_sched_barrier(0);
; #pragma unroll
;       for (int kk = 0; kk < 4; ++kk) {
;         const int ko = (((kk * 2 + hh) ^ fsw) << 4);
;         bf16x8 af[2], wf[4];
;         af[0] = *(const bf16x8*)(Ab + ko); af[1] = *(const bf16x8*)(Ab + 4096 + ko);
; #pragma unroll
;         for (int ni = 0; ni < 4; ++ni) wf[ni] = *(const bf16x8*)(Bb + ni * 4096 + ko);
; #pragma unroll
;         for (int mi = 0; mi < 2; ++mi)
; #pragma unroll
;           for (int ni = 0; ni < 4; ++ni) acc[mi][ni] = MFMA(wf[ni], af[mi], acc[mi][ni]);
;         if (kk == 1) __builtin_amdgcn_sched_barrier(0);
;       }
;       __builtin_amdgcn_sched_barrier(0);
;     }
;     asm volatile("s_waitcnt vmcnt(0)" ::: "memory");
.LBB0_734:
	s_lshl_b32 s8, s6, 16
	s_and_b32 s8, s8, 0x200000
	s_add_i32 s8, s93, s8
	s_lshl_b32 s8, s8, 1
	s_and_b32 s28, s8, 0x700000
	s_xor_b32 s8, s7, 0x10000
	v_add_u32_e32 v128, s8, v150
	v_lshl_add_u64 v[160:161], v[136:137], 0, s[40:41]
	s_mov_b64 s[22:23], 0x17e00080
	v_readfirstlane_b32 s9, v128
	v_add_u32_e32 v164, 0x2000, v128
	v_lshl_add_u64 v[162:163], v[160:161], 0, s[22:23]
	s_mov_b32 m0, s9
	s_mov_b64 s[22:23], 0x17e40080
	v_readfirstlane_b32 s9, v164
	v_add_u32_e32 v164, 0x4000, v128
	global_load_lds_dwordx4 v[162:163], off
	v_add3_u32 v187, s7, v144, v147
	v_add3_u32 v208, s7, v149, v147
	v_add_u32_e32 v182, v208, v148
	v_add_u32_e32 v183, v187, v148
	ds_read_b128 v[192:195], v182 offset:32768
	ds_read_b128 v[216:219], v183
	ds_read_b128 v[196:199], v182 offset:36864
	ds_read_b128 v[200:203], v182 offset:40960
	ds_read_b128 v[204:207], v182 offset:45056
	ds_read_b128 v[220:223], v183 offset:4096
	v_add_u32_e32 v184, v208, v145
	v_add_u32_e32 v185, v187, v145
	ds_read_b128 v[224:227], v184 offset:32768
	ds_read_b128 v[240:243], v185
	ds_read_b128 v[228:231], v184 offset:36864
	ds_read_b128 v[232:235], v184 offset:40960
	ds_read_b128 v[236:239], v184 offset:45056
	ds_read_b128 v[244:247], v185 offset:4096
	s_waitcnt lgkmcnt(10)
	v_mfma_f32_32x32x16_bf16 v[112:127], v[192:195], v[216:219], v[112:127]
	s_waitcnt lgkmcnt(9)
	v_mfma_f32_32x32x16_bf16 v[96:111], v[196:199], v[216:219], v[96:111]
	v_lshl_add_u64 v[162:163], v[160:161], 0, s[22:23]
	s_mov_b32 m0, s9
	s_mov_b64 s[22:23], 0x17e80080
	v_readfirstlane_b32 s9, v164
	global_load_lds_dwordx4 v[162:163], off
	s_waitcnt lgkmcnt(8)
	v_mfma_f32_32x32x16_bf16 v[80:95], v[200:203], v[216:219], v[80:95]
	s_waitcnt lgkmcnt(7)
	v_mfma_f32_32x32x16_bf16 v[64:79], v[204:207], v[216:219], v[64:79]
	v_lshl_add_u64 v[162:163], v[160:161], 0, s[22:23]
	s_mov_b32 m0, s9
	v_lshl_add_u64 v[158:159], v[138:139], 0, s[28:29]
	global_load_lds_dwordx4 v[162:163], off
	s_waitcnt lgkmcnt(6)
	v_mfma_f32_32x32x16_bf16 v[48:63], v[192:195], v[220:223], v[48:63]
	v_mfma_f32_32x32x16_bf16 v[32:47], v[196:199], v[220:223], v[32:47]
	v_add_u32_e32 v162, 0x6000, v128
	s_mov_b64 s[22:23], 0x17ec0080
	v_readfirstlane_b32 s9, v162
	v_add_u32_e32 v162, 0x8000, v128
	v_lshl_add_u64 v[160:161], v[160:161], 0, s[22:23]
	s_mov_b32 m0, s9
	v_lshl_add_u64 v[158:159], v[158:159], 0, s[40:41]
	v_readfirstlane_b32 s9, v162
	v_add_u32_e32 v162, 0xa000, v128
	global_load_lds_dwordx4 v[160:161], off
	v_mfma_f32_32x32x16_bf16 v[16:31], v[200:203], v[220:223], v[16:31]
	v_mfma_f32_32x32x16_bf16 v[0:15], v[204:207], v[220:223], v[0:15]
	v_lshl_add_u64 v[160:161], v[158:159], 0, s[24:25]
	s_mov_b32 m0, s9
	v_readfirstlane_b32 s9, v162
	v_add_u32_e32 v162, 0xc000, v128
	global_load_lds_dwordx4 v[160:161], off
	v_add_u32_e32 v182, v208, v141
	v_add_u32_e32 v183, v187, v141
	ds_read_b128 v[192:195], v182 offset:32768
	ds_read_b128 v[216:219], v183
	ds_read_b128 v[196:199], v182 offset:36864
	ds_read_b128 v[200:203], v182 offset:40960
	ds_read_b128 v[204:207], v182 offset:45056
	ds_read_b128 v[220:223], v183 offset:4096
	s_waitcnt lgkmcnt(10)
	v_mfma_f32_32x32x16_bf16 v[112:127], v[224:227], v[240:243], v[112:127]
	s_waitcnt lgkmcnt(9)
	v_mfma_f32_32x32x16_bf16 v[96:111], v[228:231], v[240:243], v[96:111]
	v_lshl_add_u64 v[160:161], v[158:159], 0, s[42:43]
	s_mov_b32 m0, s9
	v_readfirstlane_b32 s9, v162
	v_add_u32_e32 v128, 0xe000, v128
	global_load_lds_dwordx4 v[160:161], off
	s_waitcnt lgkmcnt(8)
	v_mfma_f32_32x32x16_bf16 v[80:95], v[232:235], v[240:243], v[80:95]
	s_waitcnt lgkmcnt(7)
	v_mfma_f32_32x32x16_bf16 v[64:79], v[236:239], v[240:243], v[64:79]
	v_lshl_add_u64 v[160:161], v[158:159], 0, s[44:45]
	s_mov_b32 m0, s9
	v_readfirstlane_b32 s9, v128
	global_load_lds_dwordx4 v[160:161], off
	s_waitcnt lgkmcnt(6)
	v_mfma_f32_32x32x16_bf16 v[48:63], v[224:227], v[244:247], v[48:63]
	v_mfma_f32_32x32x16_bf16 v[32:47], v[228:231], v[244:247], v[32:47]
	v_lshl_add_u64 v[158:159], v[158:159], 0, s[46:47]
	s_mov_b32 m0, s9
	s_add_i32 s7, s7, 0
	global_load_lds_dwordx4 v[158:159], off
	v_mfma_f32_32x32x16_bf16 v[16:31], v[232:235], v[244:247], v[16:31]
	v_mfma_f32_32x32x16_bf16 v[0:15], v[236:239], v[244:247], v[0:15]
	v_add_u32_e32 v184, v208, v140
	v_add_u32_e32 v185, v187, v140
	ds_read_b128 v[224:227], v184 offset:32768
	ds_read_b128 v[240:243], v185
	ds_read_b128 v[228:231], v184 offset:36864
	ds_read_b128 v[232:235], v184 offset:40960
	ds_read_b128 v[236:239], v184 offset:45056
	ds_read_b128 v[244:247], v185 offset:4096
	s_waitcnt lgkmcnt(10)
	v_mfma_f32_32x32x16_bf16 v[112:127], v[192:195], v[216:219], v[112:127]
	s_waitcnt lgkmcnt(9)
	v_mfma_f32_32x32x16_bf16 v[96:111], v[196:199], v[216:219], v[96:111]
	s_waitcnt lgkmcnt(8)
	v_mfma_f32_32x32x16_bf16 v[80:95], v[200:203], v[216:219], v[80:95]
	s_waitcnt lgkmcnt(7)
	v_mfma_f32_32x32x16_bf16 v[64:79], v[204:207], v[216:219], v[64:79]
	s_waitcnt lgkmcnt(6)
	v_mfma_f32_32x32x16_bf16 v[48:63], v[192:195], v[220:223], v[48:63]
	v_mfma_f32_32x32x16_bf16 v[32:47], v[196:199], v[220:223], v[32:47]
	v_mfma_f32_32x32x16_bf16 v[16:31], v[200:203], v[220:223], v[16:31]
	v_mfma_f32_32x32x16_bf16 v[0:15], v[204:207], v[220:223], v[0:15]
	s_waitcnt lgkmcnt(4)
	v_mfma_f32_32x32x16_bf16 v[112:127], v[224:227], v[240:243], v[112:127]
	s_waitcnt lgkmcnt(3)
	v_mfma_f32_32x32x16_bf16 v[96:111], v[228:231], v[240:243], v[96:111]
	s_waitcnt lgkmcnt(2)
	v_mfma_f32_32x32x16_bf16 v[80:95], v[232:235], v[240:243], v[80:95]
	s_waitcnt lgkmcnt(1)
	v_mfma_f32_32x32x16_bf16 v[64:79], v[236:239], v[240:243], v[64:79]
	s_waitcnt lgkmcnt(0)
	v_mfma_f32_32x32x16_bf16 v[48:63], v[224:227], v[244:247], v[48:63]
	v_mfma_f32_32x32x16_bf16 v[32:47], v[228:231], v[244:247], v[32:47]
	v_mfma_f32_32x32x16_bf16 v[16:31], v[232:235], v[244:247], v[16:31]
	v_mfma_f32_32x32x16_bf16 v[0:15], v[236:239], v[244:247], v[0:15]
	s_waitcnt vmcnt(0)
	s_waitcnt lgkmcnt(0)
	s_barrier
; #define MFMA(a, b, c) __builtin_amdgcn_mfma_f32_32x32x16_bf16((a), (b), (c), 0, 0, 0)
;     ...
;   for (int s = 0; s < S; ++s) {
;     G_DMA(s + 1, cur ^ BUFB);
;     {
;       const char* Ab = smem + cur + fA;
;       const char* Bb = smem + cur + fB;
;       __builtin_amdgcn_sched_barrier(0);
; #pragma unroll
;       for (int kk = 0; kk < 4; ++kk) {
;         const int ko = (((kk * 2 + hh) ^ fsw) << 4);
;         bf16x8 af[2], wf[4];
;         af[0] = *(const bf16x8*)(Ab + ko); af[1] = *(const bf16x8*)(Ab + 4096 + ko);
; #pragma unroll
;         for (int ni = 0; ni < 4; ++ni) wf[ni] = *(const bf16x8*)(Bb + ni * 4096 + ko);
; #pragma unroll
;         for (int mi = 0; mi < 2; ++mi)
; #pragma unroll
;           for (int ni = 0; ni < 4; ++ni) acc[mi][ni] = MFMA(wf[ni], af[mi], acc[mi][ni]);
;         if (kk == 1) __builtin_amdgcn_sched_barrier(0);
;       }
;       __builtin_amdgcn_sched_barrier(0);
;     }
;     asm volatile("s_waitcnt vmcnt(0)" ::: "memory");
;     if ((s & (nk - 1)) == nk - 1) {
;       const int q = slot + (s >> lnk) * nslots;
	s_add_u32 s40, s40, 0x80
	s_addc_u32 s41, s41, 0
	s_add_i32 s6, s6, 1
	s_cmpk_eq_i32 s40, 0xf80
	s_mov_b32 s7, s8
	s_cbranch_scc0 .LBB0_734
	s_mov_b64 s[8:9], 0xf80
	v_readfirstlane_b32 s6, v150
	v_lshl_add_u64 v[136:137], v[132:133], 0, s[8:9]
	s_mov_b32 m0, s6
	s_mov_b64 s[22:23], 0x40f80
	v_readfirstlane_b32 s6, v151
	global_load_lds_dwordx4 v[136:137], off
	v_lshl_add_u64 v[136:137], v[132:133], 0, s[22:23]
	s_mov_b32 m0, s6
	s_mov_b64 s[24:25], 0x80f80
	v_readfirstlane_b32 s6, v152
	global_load_lds_dwordx4 v[136:137], off
	v_lshl_add_u64 v[136:137], v[132:133], 0, s[24:25]
	s_mov_b32 m0, s6
	s_mov_b64 s[40:41], 0xc0f80
	v_readfirstlane_b32 s6, v153
	global_load_lds_dwordx4 v[136:137], off
	v_lshl_add_u64 v[132:133], v[132:133], 0, s[40:41]
	s_mov_b32 m0, s6
	v_readfirstlane_b32 s6, v154
	global_load_lds_dwordx4 v[132:133], off
	v_lshl_add_u64 v[132:133], v[134:135], 0, s[8:9]
	s_mov_b32 m0, s6
	v_readfirstlane_b32 s6, v155
	global_load_lds_dwordx4 v[132:133], off
	v_lshl_add_u64 v[132:133], v[134:135], 0, s[22:23]
	s_mov_b32 m0, s6
	v_readfirstlane_b32 s6, v156
	global_load_lds_dwordx4 v[132:133], off
	v_lshl_add_u64 v[132:133], v[134:135], 0, s[24:25]
	s_mov_b32 m0, s6
	v_readfirstlane_b32 s6, v157
	global_load_lds_dwordx4 v[132:133], off
	v_lshl_add_u64 v[132:133], v[134:135], 0, s[40:41]
	s_mov_b32 m0, s6
	s_add_i32 s28, s60, -1
	global_load_lds_dwordx4 v[132:133], off
	s_lshl_b64 s[6:7], s[28:29], 25
	v_readlane_b32 s8, v253, 39
	v_readlane_b32 s9, v253, 40
	s_add_u32 s40, s8, s6
	v_lshlrev_b32_e32 v132, 6, v146
	s_addc_u32 s41, s9, s7
	v_readlane_b32 s6, v253, 27
	v_ashrrev_i32_e32 v133, 31, v132
	v_readlane_b32 s7, v253, 28
	v_lshlrev_b32_e32 v128, 3, v142
	s_nop 0
	v_lshl_add_u64 v[162:163], v[132:133], 0, s[6:7]
	v_lshlrev_b32_e32 v132, 4, v142
	v_mov_b32_e32 v133, v129
	s_add_i32 s6, 0, 0x10000
	v_or_b32_e32 v162, v162, v143
	v_lshl_add_u64 v[132:133], s[40:41], 0, v[132:133]
	v_add3_u32 v138, s6, v144, v147
	v_add3_u32 v139, s6, v149, v147
	v_add_u32_e32 v182, v139, v148
	v_add_u32_e32 v183, v138, v148
	ds_read_b128 v[134:137], v182 offset:32768
	ds_read_b128 v[146:149], v183
	ds_read_b128 v[150:153], v182 offset:36864
	ds_read_b128 v[154:157], v182 offset:40960
	ds_read_b128 v[158:161], v182 offset:45056
	ds_read_b128 v[192:195], v183 offset:4096
	v_add_u32_e32 v184, v139, v145
	v_add_u32_e32 v185, v138, v145
	ds_read_b128 v[196:199], v184 offset:32768
	ds_read_b128 v[220:223], v185
	ds_read_b128 v[200:203], v184 offset:36864
	ds_read_b128 v[204:207], v184 offset:40960
	ds_read_b128 v[216:219], v184 offset:45056
	ds_read_b128 v[224:227], v185 offset:4096
	s_waitcnt lgkmcnt(10)
	v_mfma_f32_32x32x16_bf16 v[112:127], v[134:137], v[146:149], v[112:127]
	s_waitcnt lgkmcnt(9)
	v_mfma_f32_32x32x16_bf16 v[96:111], v[150:153], v[146:149], v[96:111]
	s_waitcnt lgkmcnt(8)
	v_mfma_f32_32x32x16_bf16 v[80:95], v[154:157], v[146:149], v[80:95]
	s_waitcnt lgkmcnt(7)
	v_mfma_f32_32x32x16_bf16 v[64:79], v[158:161], v[146:149], v[64:79]
	s_waitcnt lgkmcnt(6)
	v_mfma_f32_32x32x16_bf16 v[48:63], v[134:137], v[192:195], v[48:63]
	v_mfma_f32_32x32x16_bf16 v[32:47], v[150:153], v[192:195], v[32:47]
	v_mfma_f32_32x32x16_bf16 v[16:31], v[154:157], v[192:195], v[16:31]
	v_mfma_f32_32x32x16_bf16 v[0:15], v[158:161], v[192:195], v[0:15]
	v_add_u32_e32 v182, v139, v141
	v_add_u32_e32 v183, v138, v141
	ds_read_b128 v[134:137], v182 offset:32768
	ds_read_b128 v[146:149], v183
	ds_read_b128 v[150:153], v182 offset:36864
	ds_read_b128 v[154:157], v182 offset:40960
	ds_read_b128 v[158:161], v182 offset:45056
	ds_read_b128 v[192:195], v183 offset:4096
	s_waitcnt lgkmcnt(10)
	v_mfma_f32_32x32x16_bf16 v[112:127], v[196:199], v[220:223], v[112:127]
	s_waitcnt lgkmcnt(9)
	v_mfma_f32_32x32x16_bf16 v[96:111], v[200:203], v[220:223], v[96:111]
	s_waitcnt lgkmcnt(8)
	v_mfma_f32_32x32x16_bf16 v[80:95], v[204:207], v[220:223], v[80:95]
	s_waitcnt lgkmcnt(7)
	v_mfma_f32_32x32x16_bf16 v[64:79], v[216:219], v[220:223], v[64:79]
	s_waitcnt lgkmcnt(6)
	v_mfma_f32_32x32x16_bf16 v[48:63], v[196:199], v[224:227], v[48:63]
	v_mfma_f32_32x32x16_bf16 v[32:47], v[200:203], v[224:227], v[32:47]
	v_mfma_f32_32x32x16_bf16 v[16:31], v[204:207], v[224:227], v[16:31]
	v_mfma_f32_32x32x16_bf16 v[0:15], v[216:219], v[224:227], v[0:15]
	v_add_u32_e32 v184, v139, v140
	v_add_u32_e32 v185, v138, v140
	ds_read_b128 v[196:199], v184 offset:32768
	ds_read_b128 v[220:223], v185
	ds_read_b128 v[200:203], v184 offset:36864
	ds_read_b128 v[204:207], v184 offset:40960
	ds_read_b128 v[216:219], v184 offset:45056
	ds_read_b128 v[224:227], v185 offset:4096
	s_waitcnt lgkmcnt(10)
	v_mfma_f32_32x32x16_bf16 v[112:127], v[134:137], v[146:149], v[112:127]
	s_waitcnt lgkmcnt(9)
	v_mfma_f32_32x32x16_bf16 v[96:111], v[150:153], v[146:149], v[96:111]
	s_waitcnt lgkmcnt(8)
	v_mfma_f32_32x32x16_bf16 v[80:95], v[154:157], v[146:149], v[80:95]
	s_waitcnt lgkmcnt(7)
	v_mfma_f32_32x32x16_bf16 v[64:79], v[158:161], v[146:149], v[64:79]
	s_waitcnt lgkmcnt(6)
	v_mfma_f32_32x32x16_bf16 v[48:63], v[134:137], v[192:195], v[48:63]
	v_mfma_f32_32x32x16_bf16 v[32:47], v[150:153], v[192:195], v[32:47]
	v_mfma_f32_32x32x16_bf16 v[16:31], v[154:157], v[192:195], v[16:31]
	v_mfma_f32_32x32x16_bf16 v[0:15], v[158:161], v[192:195], v[0:15]
	s_waitcnt lgkmcnt(4)
	v_mfma_f32_32x32x16_bf16 v[112:127], v[196:199], v[220:223], v[112:127]
	s_waitcnt lgkmcnt(3)
	v_mfma_f32_32x32x16_bf16 v[96:111], v[200:203], v[220:223], v[96:111]
	s_waitcnt lgkmcnt(2)
	v_mfma_f32_32x32x16_bf16 v[80:95], v[204:207], v[220:223], v[80:95]
	s_waitcnt lgkmcnt(1)
	v_mfma_f32_32x32x16_bf16 v[64:79], v[216:219], v[220:223], v[64:79]
	s_waitcnt lgkmcnt(0)
;     ...
;     asm volatile("s_waitcnt vmcnt(0)" ::: "memory");
;     if ((s & (nk - 1)) == nk - 1) {
;       const int q = slot + (s >> lnk) * nslots;
;       int mt, nt; G_TILEMAP(q, mt, nt);
;       if (dostore) {
; #pragma unroll
;         for (int mi = 0; mi < 2; ++mi) {
;           const size_t m = (size_t)mt * 256 + wm * 64 + mi * 32 + r;
; #pragma unroll
;           for (int ni = 0; ni < 4; ++ni) {
;             __builtin_amdgcn_sched_barrier(0);
;             if (MODE == 0) {
; #pragma unroll
;               for (int gp = 0; gp < 2; ++gp) {
;                 const int g0 = 2 * gp;
;                 uint2 pa, pb;
;                 pa.x = pack2(acc[mi][ni][4 * g0], acc[mi][ni][4 * g0 + 1]); pa.y = pack2(acc[mi][ni][4 * g0 + 2], acc[mi][ni][4 * g0 + 3]);
;                 pb.x = pack2(acc[mi][ni][4 * g0 + 4], acc[mi][ni][4 * g0 + 5]); pb.y = pack2(acc[mi][ni][4 * g0 + 6], acc[mi][ni][4 * g0 + 7]);
;                 { auto rx = __builtin_amdgcn_permlane32_swap(pa.x, pb.x, false, false); pa.x = rx[0]; pb.x = rx[1]; }
;                 { auto ry = __builtin_amdgcn_permlane32_swap(pa.y, pb.y, false, false); pa.y = ry[0]; pb.y = ry[1]; }
;                 const int col = nt * 256 + wn * 128 + ni * 32 + 8 * g0 + 8 * hh;
;                 const uint4 v4 = make_uint4(pa.x, pa.y, pb.x, pb.y);
;                 if (outp != nullptr && nt >= 32) *(uint4*)(outp + m * 2048 + (col - 8192)) = v4;
;                 else if (col < nvalid) *(uint4*)(C + m * ldc + col) = v4;
;               }
;             } else if (MODE == 1) {
; #pragma unroll
;               for (int gp = 0; gp < 2; ++gp) {
;                 const int g0 = 2 * gp;
;                 const int nb_ = nt * 256 + wn * 128 + ni * 32 + 8 * g0;
;                 const uint2 ra = *(const uint2*)(res + m * 1024 + nb_ + 4 * hh), rb = *(const uint2*)(res + m * 1024 + nb_ + 8 + 4 * hh);
;                 uint2 pa, pb;
;                 pa.x = pack2(alpha * lo2f(ra.x) + acc[mi][ni][4 * g0], alpha * hi2f(ra.x) + acc[mi][ni][4 * g0 + 1]);
;                 pa.y = pack2(alpha * lo2f(ra.y) + acc[mi][ni][4 * g0 + 2], alpha * hi2f(ra.y) + acc[mi][ni][4 * g0 + 3]);
;                 pb.x = pack2(alpha * lo2f(rb.x) + acc[mi][ni][4 * g0 + 4], alpha * hi2f(rb.x) + acc[mi][ni][4 * g0 + 5]);
;                 pb.y = pack2(alpha * lo2f(rb.y) + acc[mi][ni][4 * g0 + 6], alpha * hi2f(rb.y) + acc[mi][ni][4 * g0 + 7]);
	v_mfma_f32_32x32x16_bf16 v[48:63], v[196:199], v[224:227], v[48:63]
	v_mfma_f32_32x32x16_bf16 v[32:47], v[200:203], v[224:227], v[32:47]
	v_mfma_f32_32x32x16_bf16 v[16:31], v[204:207], v[224:227], v[16:31]
	v_mfma_f32_32x32x16_bf16 v[0:15], v[216:219], v[224:227], v[0:15]
	s_waitcnt vmcnt(0)
	v_lshlrev_b64 v[136:137], 11, v[162:163]
	v_lshl_add_u64 v[138:139], s[40:41], 0, v[136:137]
	v_lshl_add_u64 v[144:145], v[132:133], 0, v[136:137]
	v_readlane_b32 s6, v251, 32
	s_lshl_b32 s6, s6, 1
	v_mov_b32_e32 v135, v129
	v_lshl_or_b32 v134, v131, 8, s6
	v_lshl_add_u64 v[138:139], v[138:139], 0, v[134:135]
	v_lshl_add_u64 v[138:139], v[138:139], 0, v[128:129]
	global_load_dwordx2 v[140:141], v[138:139], off
	global_load_dwordx2 v[142:143], v[138:139], off offset:16
	s_mov_b32 s6, 0x3fd744fd
	s_waitcnt vmcnt(0)
	v_lshlrev_b32_e32 v146, 16, v140
	v_and_b32_e32 v147, 0xffff0000, v140
	v_pk_fma_f32 v[112:113], v[146:147], s[6:7], v[112:113] op_sel_hi:[1,0,1]
	s_nop 0
	v_cvt_pk_bf16_f32 v140, v112, v113
	v_lshlrev_b32_e32 v112, 16, v141
	v_and_b32_e32 v113, 0xffff0000, v141
	v_pk_fma_f32 v[112:113], v[112:113], s[6:7], v[114:115] op_sel_hi:[1,0,1]
	s_nop 0
	v_cvt_pk_bf16_f32 v141, v112, v113
	v_lshlrev_b32_e32 v112, 16, v142
	v_and_b32_e32 v113, 0xffff0000, v142
	v_pk_fma_f32 v[112:113], v[112:113], s[6:7], v[116:117] op_sel_hi:[1,0,1]
	s_nop 0
	v_cvt_pk_bf16_f32 v142, v112, v113
	v_lshlrev_b32_e32 v112, 16, v143
	v_and_b32_e32 v113, 0xffff0000, v143
	v_pk_fma_f32 v[112:113], v[112:113], s[6:7], v[118:119] op_sel_hi:[1,0,1]
	v_permlane32_swap_b32_e32 v140, v142
	v_cvt_pk_bf16_f32 v143, v112, v113
	s_nop 1
	v_permlane32_swap_b32_e32 v141, v143
	v_lshl_add_u64 v[112:113], v[144:145], 0, v[134:135]
	global_store_dwordx4 v[112:113], v[140:143], off
	global_load_dwordx2 v[114:115], v[138:139], off offset:32
	global_load_dwordx2 v[116:117], v[138:139], off offset:48
	s_waitcnt vmcnt(1)
	v_lshlrev_b32_e32 v118, 16, v114
	v_and_b32_e32 v119, 0xffff0000, v114
	v_pk_fma_f32 v[118:119], v[118:119], s[6:7], v[120:121] op_sel_hi:[1,0,1]
	s_nop 0
	v_cvt_pk_bf16_f32 v114, v118, v119
	v_lshlrev_b32_e32 v118, 16, v115
	v_and_b32_e32 v119, 0xffff0000, v115
	v_pk_fma_f32 v[118:119], v[118:119], s[6:7], v[122:123] op_sel_hi:[1,0,1]
	s_nop 0
	v_cvt_pk_bf16_f32 v115, v118, v119
	s_waitcnt vmcnt(0)
	v_lshlrev_b32_e32 v118, 16, v116
	v_and_b32_e32 v119, 0xffff0000, v116
	v_pk_fma_f32 v[118:119], v[118:119], s[6:7], v[124:125] op_sel_hi:[1,0,1]
	s_nop 0
	v_cvt_pk_bf16_f32 v116, v118, v119
	v_lshlrev_b32_e32 v118, 16, v117
	v_and_b32_e32 v119, 0xffff0000, v117
	v_pk_fma_f32 v[118:119], v[118:119], s[6:7], v[126:127] op_sel_hi:[1,0,1]
	v_permlane32_swap_b32_e32 v114, v116
	v_cvt_pk_bf16_f32 v117, v118, v119
	s_nop 1
	v_permlane32_swap_b32_e32 v115, v117
	global_store_dwordx4 v[112:113], v[114:117], off offset:32
	global_load_dwordx2 v[114:115], v[138:139], off offset:64
	s_nop 0
	global_load_dwordx2 v[116:117], v[138:139], off offset:80
	s_waitcnt vmcnt(1)
	v_lshlrev_b32_e32 v118, 16, v114
	v_and_b32_e32 v119, 0xffff0000, v114
	v_lshlrev_b32_e32 v114, 16, v115
	v_and_b32_e32 v115, 0xffff0000, v115
	v_pk_fma_f32 v[96:97], v[118:119], s[6:7], v[96:97] op_sel_hi:[1,0,1]
	v_pk_fma_f32 v[98:99], v[114:115], s[6:7], v[98:99] op_sel_hi:[1,0,1]
	v_cvt_pk_bf16_f32 v96, v96, v97
	v_cvt_pk_bf16_f32 v97, v98, v99
	s_waitcnt vmcnt(0)
	v_lshlrev_b32_e32 v98, 16, v116
	v_and_b32_e32 v99, 0xffff0000, v116
	v_pk_fma_f32 v[98:99], v[98:99], s[6:7], v[100:101] op_sel_hi:[1,0,1]
	v_lshlrev_b32_e32 v100, 16, v117
	v_and_b32_e32 v101, 0xffff0000, v117
	v_pk_fma_f32 v[100:101], v[100:101], s[6:7], v[102:103] op_sel_hi:[1,0,1]
	v_cvt_pk_bf16_f32 v98, v98, v99
	v_cvt_pk_bf16_f32 v99, v100, v101
	s_nop 0
	v_permlane32_swap_b32_e32 v96, v98
	v_permlane32_swap_b32_e32 v97, v99
	global_store_dwordx4 v[112:113], v[96:99], off offset:64
	global_load_dwordx2 v[96:97], v[138:139], off offset:96
	s_nop 0
	global_load_dwordx2 v[98:99], v[138:139], off offset:112
	s_waitcnt vmcnt(1)
	v_lshlrev_b32_e32 v100, 16, v96
	v_and_b32_e32 v101, 0xffff0000, v96
	v_pk_fma_f32 v[100:101], v[100:101], s[6:7], v[104:105] op_sel_hi:[1,0,1]
	s_nop 0
	v_cvt_pk_bf16_f32 v96, v100, v101
	v_lshlrev_b32_e32 v100, 16, v97
	v_and_b32_e32 v101, 0xffff0000, v97
	v_pk_fma_f32 v[100:101], v[100:101], s[6:7], v[106:107] op_sel_hi:[1,0,1]
	s_nop 0
	v_cvt_pk_bf16_f32 v97, v100, v101
	s_waitcnt vmcnt(0)
	v_lshlrev_b32_e32 v100, 16, v98
	v_and_b32_e32 v101, 0xffff0000, v98
	v_pk_fma_f32 v[100:101], v[100:101], s[6:7], v[108:109] op_sel_hi:[1,0,1]
	s_nop 0
	v_cvt_pk_bf16_f32 v98, v100, v101
	v_lshlrev_b32_e32 v100, 16, v99
	v_and_b32_e32 v101, 0xffff0000, v99
	v_pk_fma_f32 v[100:101], v[100:101], s[6:7], v[110:111] op_sel_hi:[1,0,1]
	v_permlane32_swap_b32_e32 v96, v98
	v_cvt_pk_bf16_f32 v99, v100, v101
	s_nop 1
	v_permlane32_swap_b32_e32 v97, v99
	global_store_dwordx4 v[112:113], v[96:99], off offset:96
	global_load_dwordx2 v[96:97], v[138:139], off offset:128
	s_nop 0
	global_load_dwordx2 v[98:99], v[138:139], off offset:144
	s_waitcnt vmcnt(1)
	v_lshlrev_b32_e32 v100, 16, v96
	v_and_b32_e32 v101, 0xffff0000, v96
	v_lshlrev_b32_e32 v96, 16, v97
	v_and_b32_e32 v97, 0xffff0000, v97
	v_pk_fma_f32 v[80:81], v[100:101], s[6:7], v[80:81] op_sel_hi:[1,0,1]
	v_pk_fma_f32 v[82:83], v[96:97], s[6:7], v[82:83] op_sel_hi:[1,0,1]
	v_cvt_pk_bf16_f32 v80, v80, v81
	v_cvt_pk_bf16_f32 v81, v82, v83
	s_waitcnt vmcnt(0)
; DI unsigned pack2(float a, float b) { f32x2_t v = {a, b}; return __builtin_bit_cast(unsigned, __builtin_convertvector(v, bf16x2_t)); }
; DI float lo2f(unsigned v) { return __uint_as_float(v << 16); }
; DI float hi2f(unsigned v) { return __uint_as_float(v & 0xffff0000u); }
;     ...
;             } else if (MODE == 1) {
; #pragma unroll
;               for (int gp = 0; gp < 2; ++gp) {
;                 const int g0 = 2 * gp;
;                 const int nb_ = nt * 256 + wn * 128 + ni * 32 + 8 * g0;
;                 const uint2 ra = *(const uint2*)(res + m * 1024 + nb_ + 4 * hh), rb = *(const uint2*)(res + m * 1024 + nb_ + 8 + 4 * hh);
;                 uint2 pa, pb;
;                 pa.x = pack2(alpha * lo2f(ra.x) + acc[mi][ni][4 * g0], alpha * hi2f(ra.x) + acc[mi][ni][4 * g0 + 1]);
;                 pa.y = pack2(alpha * lo2f(ra.y) + acc[mi][ni][4 * g0 + 2], alpha * hi2f(ra.y) + acc[mi][ni][4 * g0 + 3]);
;                 pb.x = pack2(alpha * lo2f(rb.x) + acc[mi][ni][4 * g0 + 4], alpha * hi2f(rb.x) + acc[mi][ni][4 * g0 + 5]);
;                 pb.y = pack2(alpha * lo2f(rb.y) + acc[mi][ni][4 * g0 + 6], alpha * hi2f(rb.y) + acc[mi][ni][4 * g0 + 7]);
;                 { auto rx = __builtin_amdgcn_permlane32_swap(pa.x, pb.x, false, false); pa.x = rx[0]; pb.x = rx[1]; }
;                 { auto ry = __builtin_amdgcn_permlane32_swap(pa.y, pb.y, false, false); pa.y = ry[0]; pb.y = ry[1]; }
;                 *(uint4*)(outp + m * 1024 + nb_ + 8 * hh) = make_uint4(pa.x, pa.y, pb.x, pb.y);
;               }
	v_lshlrev_b32_e32 v82, 16, v98
	v_and_b32_e32 v83, 0xffff0000, v98
	v_pk_fma_f32 v[82:83], v[82:83], s[6:7], v[84:85] op_sel_hi:[1,0,1]
	v_lshlrev_b32_e32 v84, 16, v99
	v_and_b32_e32 v85, 0xffff0000, v99
	v_pk_fma_f32 v[84:85], v[84:85], s[6:7], v[86:87] op_sel_hi:[1,0,1]
	v_cvt_pk_bf16_f32 v82, v82, v83
	v_cvt_pk_bf16_f32 v83, v84, v85
	s_nop 0
	v_permlane32_swap_b32_e32 v80, v82
	v_permlane32_swap_b32_e32 v81, v83
	global_store_dwordx4 v[112:113], v[80:83], off offset:128
	global_load_dwordx2 v[80:81], v[138:139], off offset:160
	s_nop 0
	global_load_dwordx2 v[82:83], v[138:139], off offset:176
	s_waitcnt vmcnt(1)
	v_lshlrev_b32_e32 v84, 16, v80
	v_and_b32_e32 v85, 0xffff0000, v80
	v_pk_fma_f32 v[84:85], v[84:85], s[6:7], v[88:89] op_sel_hi:[1,0,1]
	s_nop 0
	v_cvt_pk_bf16_f32 v80, v84, v85
	v_lshlrev_b32_e32 v84, 16, v81
	v_and_b32_e32 v85, 0xffff0000, v81
	v_pk_fma_f32 v[84:85], v[84:85], s[6:7], v[90:91] op_sel_hi:[1,0,1]
	s_nop 0
	v_cvt_pk_bf16_f32 v81, v84, v85
	s_waitcnt vmcnt(0)
	v_lshlrev_b32_e32 v84, 16, v82
	v_and_b32_e32 v85, 0xffff0000, v82
	v_pk_fma_f32 v[84:85], v[84:85], s[6:7], v[92:93] op_sel_hi:[1,0,1]
	s_nop 0
	v_cvt_pk_bf16_f32 v82, v84, v85
	v_lshlrev_b32_e32 v84, 16, v83
	v_and_b32_e32 v85, 0xffff0000, v83
	v_pk_fma_f32 v[84:85], v[84:85], s[6:7], v[94:95] op_sel_hi:[1,0,1]
	v_permlane32_swap_b32_e32 v80, v82
	v_cvt_pk_bf16_f32 v83, v84, v85
	s_nop 1
	v_permlane32_swap_b32_e32 v81, v83
	global_store_dwordx4 v[112:113], v[80:83], off offset:160
	global_load_dwordx2 v[80:81], v[138:139], off offset:192
	s_nop 0
	global_load_dwordx2 v[82:83], v[138:139], off offset:208
	v_or_b32_e32 v136, 0x10000, v136
	s_waitcnt vmcnt(1)
	v_lshlrev_b32_e32 v84, 16, v80
	v_and_b32_e32 v85, 0xffff0000, v80
	v_lshlrev_b32_e32 v80, 16, v81
	v_and_b32_e32 v81, 0xffff0000, v81
	v_pk_fma_f32 v[64:65], v[84:85], s[6:7], v[64:65] op_sel_hi:[1,0,1]
	v_pk_fma_f32 v[66:67], v[80:81], s[6:7], v[66:67] op_sel_hi:[1,0,1]
	v_cvt_pk_bf16_f32 v64, v64, v65
	v_cvt_pk_bf16_f32 v65, v66, v67
	s_waitcnt vmcnt(0)
	v_lshlrev_b32_e32 v66, 16, v82
	v_and_b32_e32 v67, 0xffff0000, v82
	v_pk_fma_f32 v[66:67], v[66:67], s[6:7], v[68:69] op_sel_hi:[1,0,1]
	v_lshlrev_b32_e32 v68, 16, v83
	v_and_b32_e32 v69, 0xffff0000, v83
	v_pk_fma_f32 v[68:69], v[68:69], s[6:7], v[70:71] op_sel_hi:[1,0,1]
	v_cvt_pk_bf16_f32 v66, v66, v67
	v_cvt_pk_bf16_f32 v67, v68, v69
	s_nop 0
	v_permlane32_swap_b32_e32 v64, v66
	v_permlane32_swap_b32_e32 v65, v67
	global_store_dwordx4 v[112:113], v[64:67], off offset:192
	global_load_dwordx2 v[64:65], v[138:139], off offset:224
	s_nop 0
	global_load_dwordx2 v[66:67], v[138:139], off offset:240
	v_lshl_add_u64 v[70:71], v[132:133], 0, v[136:137]
	s_waitcnt vmcnt(1)
	v_lshlrev_b32_e32 v68, 16, v64
	v_and_b32_e32 v69, 0xffff0000, v64
	v_pk_fma_f32 v[68:69], v[68:69], s[6:7], v[72:73] op_sel_hi:[1,0,1]
	s_nop 0
	v_cvt_pk_bf16_f32 v64, v68, v69
	v_lshlrev_b32_e32 v68, 16, v65
	v_and_b32_e32 v69, 0xffff0000, v65
	v_pk_fma_f32 v[68:69], v[68:69], s[6:7], v[74:75] op_sel_hi:[1,0,1]
	s_nop 0
	v_cvt_pk_bf16_f32 v65, v68, v69
	s_waitcnt vmcnt(0)
	v_lshlrev_b32_e32 v68, 16, v66
	v_and_b32_e32 v69, 0xffff0000, v66
	v_pk_fma_f32 v[68:69], v[68:69], s[6:7], v[76:77] op_sel_hi:[1,0,1]
	s_nop 0
	v_cvt_pk_bf16_f32 v66, v68, v69
	v_lshlrev_b32_e32 v68, 16, v67
	v_and_b32_e32 v69, 0xffff0000, v67
	v_pk_fma_f32 v[68:69], v[68:69], s[6:7], v[78:79] op_sel_hi:[1,0,1]
	v_permlane32_swap_b32_e32 v64, v66
	v_cvt_pk_bf16_f32 v67, v68, v69
	s_nop 1
	v_permlane32_swap_b32_e32 v65, v67
	global_store_dwordx4 v[112:113], v[64:67], off offset:224
	s_nop 1
	v_lshl_add_u64 v[64:65], s[40:41], 0, v[136:137]
	v_lshl_add_u64 v[64:65], v[64:65], 0, v[134:135]
	v_lshl_add_u64 v[64:65], v[64:65], 0, v[128:129]
	global_load_dwordx2 v[66:67], v[64:65], off
	global_load_dwordx2 v[68:69], v[64:65], off offset:16
	s_waitcnt vmcnt(1)
	v_lshlrev_b32_e32 v72, 16, v66
	v_and_b32_e32 v73, 0xffff0000, v66
	v_pk_fma_f32 v[48:49], v[72:73], s[6:7], v[48:49] op_sel_hi:[1,0,1]
	s_nop 0
	v_cvt_pk_bf16_f32 v66, v48, v49
	v_lshlrev_b32_e32 v48, 16, v67
	v_and_b32_e32 v49, 0xffff0000, v67
	v_pk_fma_f32 v[48:49], v[48:49], s[6:7], v[50:51] op_sel_hi:[1,0,1]
	s_nop 0
	v_cvt_pk_bf16_f32 v67, v48, v49
	s_waitcnt vmcnt(0)
	v_lshlrev_b32_e32 v48, 16, v68
	v_and_b32_e32 v49, 0xffff0000, v68
	v_pk_fma_f32 v[48:49], v[48:49], s[6:7], v[52:53] op_sel_hi:[1,0,1]
	s_nop 0
	v_cvt_pk_bf16_f32 v68, v48, v49
	v_lshlrev_b32_e32 v48, 16, v69
	v_and_b32_e32 v49, 0xffff0000, v69
	v_pk_fma_f32 v[48:49], v[48:49], s[6:7], v[54:55] op_sel_hi:[1,0,1]
	v_permlane32_swap_b32_e32 v66, v68
	v_cvt_pk_bf16_f32 v69, v48, v49
	s_nop 1
	v_permlane32_swap_b32_e32 v67, v69
	v_lshl_add_u64 v[48:49], v[70:71], 0, v[134:135]
	global_store_dwordx4 v[48:49], v[66:69], off
	global_load_dwordx2 v[50:51], v[64:65], off offset:32
	global_load_dwordx2 v[52:53], v[64:65], off offset:48
	s_waitcnt vmcnt(1)
	v_lshlrev_b32_e32 v54, 16, v50
	v_and_b32_e32 v55, 0xffff0000, v50
	v_pk_fma_f32 v[54:55], v[54:55], s[6:7], v[56:57] op_sel_hi:[1,0,1]
	s_nop 0
	v_cvt_pk_bf16_f32 v50, v54, v55
	v_lshlrev_b32_e32 v54, 16, v51
	v_and_b32_e32 v55, 0xffff0000, v51
	v_pk_fma_f32 v[54:55], v[54:55], s[6:7], v[58:59] op_sel_hi:[1,0,1]
	s_nop 0
	v_cvt_pk_bf16_f32 v51, v54, v55
	s_waitcnt vmcnt(0)
	v_lshlrev_b32_e32 v54, 16, v52
	v_and_b32_e32 v55, 0xffff0000, v52
	v_pk_fma_f32 v[54:55], v[54:55], s[6:7], v[60:61] op_sel_hi:[1,0,1]
	s_nop 0
	v_cvt_pk_bf16_f32 v52, v54, v55
	v_lshlrev_b32_e32 v54, 16, v53
	v_and_b32_e32 v55, 0xffff0000, v53
	v_pk_fma_f32 v[54:55], v[54:55], s[6:7], v[62:63] op_sel_hi:[1,0,1]
	v_permlane32_swap_b32_e32 v50, v52
	v_cvt_pk_bf16_f32 v53, v54, v55
	s_nop 1
	v_permlane32_swap_b32_e32 v51, v53
	global_store_dwordx4 v[48:49], v[50:53], off offset:32
	global_load_dwordx2 v[50:51], v[64:65], off offset:64
	s_nop 0
	global_load_dwordx2 v[52:53], v[64:65], off offset:80
	s_waitcnt vmcnt(1)
; DI unsigned pack2(float a, float b) { f32x2_t v = {a, b}; return __builtin_bit_cast(unsigned, __builtin_convertvector(v, bf16x2_t)); }
; DI float lo2f(unsigned v) { return __uint_as_float(v << 16); }
; DI float hi2f(unsigned v) { return __uint_as_float(v & 0xffff0000u); }
;     ...
;             } else if (MODE == 1) {
; #pragma unroll
;               for (int gp = 0; gp < 2; ++gp) {
;                 const int g0 = 2 * gp;
;                 const int nb_ = nt * 256 + wn * 128 + ni * 32 + 8 * g0;
;                 const uint2 ra = *(const uint2*)(res + m * 1024 + nb_ + 4 * hh), rb = *(const uint2*)(res + m * 1024 + nb_ + 8 + 4 * hh);
;                 uint2 pa, pb;
;                 pa.x = pack2(alpha * lo2f(ra.x) + acc[mi][ni][4 * g0], alpha * hi2f(ra.x) + acc[mi][ni][4 * g0 + 1]);
;                 pa.y = pack2(alpha * lo2f(ra.y) + acc[mi][ni][4 * g0 + 2], alpha * hi2f(ra.y) + acc[mi][ni][4 * g0 + 3]);
;                 pb.x = pack2(alpha * lo2f(rb.x) + acc[mi][ni][4 * g0 + 4], alpha * hi2f(rb.x) + acc[mi][ni][4 * g0 + 5]);
;                 pb.y = pack2(alpha * lo2f(rb.y) + acc[mi][ni][4 * g0 + 6], alpha * hi2f(rb.y) + acc[mi][ni][4 * g0 + 7]);
;                 { auto rx = __builtin_amdgcn_permlane32_swap(pa.x, pb.x, false, false); pa.x = rx[0]; pb.x = rx[1]; }
;                 { auto ry = __builtin_amdgcn_permlane32_swap(pa.y, pb.y, false, false); pa.y = ry[0]; pb.y = ry[1]; }
;                 *(uint4*)(outp + m * 1024 + nb_ + 8 * hh) = make_uint4(pa.x, pa.y, pb.x, pb.y);
;               }
;     ...
;     asm volatile("s_waitcnt lgkmcnt(0)" ::: "memory"); __builtin_amdgcn_s_barrier(); asm volatile("" ::: "memory");
;     cur ^= BUFB;
;   }
;   asm volatile("s_waitcnt vmcnt(0)" ::: "memory");
;   __syncthreads();
	v_lshlrev_b32_e32 v54, 16, v50
	v_and_b32_e32 v55, 0xffff0000, v50
	v_lshlrev_b32_e32 v50, 16, v51
	v_and_b32_e32 v51, 0xffff0000, v51
	v_pk_fma_f32 v[32:33], v[54:55], s[6:7], v[32:33] op_sel_hi:[1,0,1]
	v_pk_fma_f32 v[34:35], v[50:51], s[6:7], v[34:35] op_sel_hi:[1,0,1]
	v_cvt_pk_bf16_f32 v32, v32, v33
	v_cvt_pk_bf16_f32 v33, v34, v35
	s_waitcnt vmcnt(0)
	v_lshlrev_b32_e32 v34, 16, v52
	v_and_b32_e32 v35, 0xffff0000, v52
	v_pk_fma_f32 v[34:35], v[34:35], s[6:7], v[36:37] op_sel_hi:[1,0,1]
	v_lshlrev_b32_e32 v36, 16, v53
	v_and_b32_e32 v37, 0xffff0000, v53
	v_pk_fma_f32 v[36:37], v[36:37], s[6:7], v[38:39] op_sel_hi:[1,0,1]
	v_cvt_pk_bf16_f32 v34, v34, v35
	v_cvt_pk_bf16_f32 v35, v36, v37
	s_nop 0
	v_permlane32_swap_b32_e32 v32, v34
	v_permlane32_swap_b32_e32 v33, v35
	global_store_dwordx4 v[48:49], v[32:35], off offset:64
	global_load_dwordx2 v[32:33], v[64:65], off offset:96
	s_nop 0
	global_load_dwordx2 v[34:35], v[64:65], off offset:112
	s_waitcnt vmcnt(1)
	v_lshlrev_b32_e32 v36, 16, v32
	v_and_b32_e32 v37, 0xffff0000, v32
	v_pk_fma_f32 v[36:37], v[36:37], s[6:7], v[40:41] op_sel_hi:[1,0,1]
	s_nop 0
	v_cvt_pk_bf16_f32 v32, v36, v37
	v_lshlrev_b32_e32 v36, 16, v33
	v_and_b32_e32 v37, 0xffff0000, v33
	v_pk_fma_f32 v[36:37], v[36:37], s[6:7], v[42:43] op_sel_hi:[1,0,1]
	s_nop 0
	v_cvt_pk_bf16_f32 v33, v36, v37
	s_waitcnt vmcnt(0)
	v_lshlrev_b32_e32 v36, 16, v34
	v_and_b32_e32 v37, 0xffff0000, v34
	v_pk_fma_f32 v[36:37], v[36:37], s[6:7], v[44:45] op_sel_hi:[1,0,1]
	s_nop 0
	v_cvt_pk_bf16_f32 v34, v36, v37
	v_lshlrev_b32_e32 v36, 16, v35
	v_and_b32_e32 v37, 0xffff0000, v35
	v_pk_fma_f32 v[36:37], v[36:37], s[6:7], v[46:47] op_sel_hi:[1,0,1]
	v_permlane32_swap_b32_e32 v32, v34
	v_cvt_pk_bf16_f32 v35, v36, v37
	s_nop 1
	v_permlane32_swap_b32_e32 v33, v35
	global_store_dwordx4 v[48:49], v[32:35], off offset:96
	global_load_dwordx2 v[32:33], v[64:65], off offset:128
	s_nop 0
	global_load_dwordx2 v[34:35], v[64:65], off offset:144
	s_waitcnt vmcnt(1)
	v_lshlrev_b32_e32 v36, 16, v32
	v_and_b32_e32 v37, 0xffff0000, v32
	v_lshlrev_b32_e32 v32, 16, v33
	v_and_b32_e32 v33, 0xffff0000, v33
	v_pk_fma_f32 v[16:17], v[36:37], s[6:7], v[16:17] op_sel_hi:[1,0,1]
	v_pk_fma_f32 v[18:19], v[32:33], s[6:7], v[18:19] op_sel_hi:[1,0,1]
	v_cvt_pk_bf16_f32 v16, v16, v17
	v_cvt_pk_bf16_f32 v17, v18, v19
	s_waitcnt vmcnt(0)
	v_lshlrev_b32_e32 v18, 16, v34
	v_and_b32_e32 v19, 0xffff0000, v34
	v_pk_fma_f32 v[18:19], v[18:19], s[6:7], v[20:21] op_sel_hi:[1,0,1]
	v_lshlrev_b32_e32 v20, 16, v35
	v_and_b32_e32 v21, 0xffff0000, v35
	v_pk_fma_f32 v[20:21], v[20:21], s[6:7], v[22:23] op_sel_hi:[1,0,1]
	v_cvt_pk_bf16_f32 v18, v18, v19
	v_cvt_pk_bf16_f32 v19, v20, v21
	s_nop 0
	v_permlane32_swap_b32_e32 v16, v18
	v_permlane32_swap_b32_e32 v17, v19
	global_store_dwordx4 v[48:49], v[16:19], off offset:128
	global_load_dwordx2 v[16:17], v[64:65], off offset:160
	s_nop 0
	global_load_dwordx2 v[18:19], v[64:65], off offset:176
	s_waitcnt vmcnt(1)
	v_lshlrev_b32_e32 v20, 16, v16
	v_and_b32_e32 v21, 0xffff0000, v16
	v_pk_fma_f32 v[20:21], v[20:21], s[6:7], v[24:25] op_sel_hi:[1,0,1]
	s_nop 0
	v_cvt_pk_bf16_f32 v16, v20, v21
	v_lshlrev_b32_e32 v20, 16, v17
	v_and_b32_e32 v21, 0xffff0000, v17
	v_pk_fma_f32 v[20:21], v[20:21], s[6:7], v[26:27] op_sel_hi:[1,0,1]
	s_nop 0
	v_cvt_pk_bf16_f32 v17, v20, v21
	s_waitcnt vmcnt(0)
	v_lshlrev_b32_e32 v20, 16, v18
	v_and_b32_e32 v21, 0xffff0000, v18
	v_pk_fma_f32 v[20:21], v[20:21], s[6:7], v[28:29] op_sel_hi:[1,0,1]
	s_nop 0
	v_cvt_pk_bf16_f32 v18, v20, v21
	v_lshlrev_b32_e32 v20, 16, v19
	v_and_b32_e32 v21, 0xffff0000, v19
	v_pk_fma_f32 v[20:21], v[20:21], s[6:7], v[30:31] op_sel_hi:[1,0,1]
	v_permlane32_swap_b32_e32 v16, v18
	v_cvt_pk_bf16_f32 v19, v20, v21
	s_nop 1
	v_permlane32_swap_b32_e32 v17, v19
	global_store_dwordx4 v[48:49], v[16:19], off offset:160
	global_load_dwordx2 v[16:17], v[64:65], off offset:192
	s_nop 0
	global_load_dwordx2 v[18:19], v[64:65], off offset:208
	s_waitcnt vmcnt(1)
	v_lshlrev_b32_e32 v20, 16, v16
	v_and_b32_e32 v21, 0xffff0000, v16
	v_lshlrev_b32_e32 v16, 16, v17
	v_and_b32_e32 v17, 0xffff0000, v17
	v_pk_fma_f32 v[0:1], v[20:21], s[6:7], v[0:1] op_sel_hi:[1,0,1]
	v_pk_fma_f32 v[2:3], v[16:17], s[6:7], v[2:3] op_sel_hi:[1,0,1]
	v_cvt_pk_bf16_f32 v0, v0, v1
	v_cvt_pk_bf16_f32 v1, v2, v3
	s_waitcnt vmcnt(0)
	v_lshlrev_b32_e32 v2, 16, v18
	v_and_b32_e32 v3, 0xffff0000, v18
	v_pk_fma_f32 v[2:3], v[2:3], s[6:7], v[4:5] op_sel_hi:[1,0,1]
	v_lshlrev_b32_e32 v4, 16, v19
	v_and_b32_e32 v5, 0xffff0000, v19
	v_pk_fma_f32 v[4:5], v[4:5], s[6:7], v[6:7] op_sel_hi:[1,0,1]
	v_cvt_pk_bf16_f32 v2, v2, v3
	v_cvt_pk_bf16_f32 v3, v4, v5
	s_nop 0
	v_permlane32_swap_b32_e32 v0, v2
	v_permlane32_swap_b32_e32 v1, v3
	global_store_dwordx4 v[48:49], v[0:3], off offset:192
	global_load_dwordx2 v[0:1], v[64:65], off offset:224
	s_nop 0
	global_load_dwordx2 v[2:3], v[64:65], off offset:240
	s_waitcnt vmcnt(1)
	v_lshlrev_b32_e32 v4, 16, v0
	v_and_b32_e32 v5, 0xffff0000, v0
	v_pk_fma_f32 v[4:5], v[4:5], s[6:7], v[8:9] op_sel_hi:[1,0,1]
	s_nop 0
	v_cvt_pk_bf16_f32 v0, v4, v5
	v_lshlrev_b32_e32 v4, 16, v1
	v_and_b32_e32 v5, 0xffff0000, v1
	v_pk_fma_f32 v[4:5], v[4:5], s[6:7], v[10:11] op_sel_hi:[1,0,1]
	s_nop 0
	v_cvt_pk_bf16_f32 v1, v4, v5
	s_waitcnt vmcnt(0)
	v_lshlrev_b32_e32 v4, 16, v2
	v_and_b32_e32 v5, 0xffff0000, v2
	v_pk_fma_f32 v[4:5], v[4:5], s[6:7], v[12:13] op_sel_hi:[1,0,1]
	s_nop 0
	v_cvt_pk_bf16_f32 v2, v4, v5
	v_lshlrev_b32_e32 v4, 16, v3
	v_and_b32_e32 v5, 0xffff0000, v3
	v_pk_fma_f32 v[4:5], v[4:5], s[6:7], v[14:15] op_sel_hi:[1,0,1]
	v_permlane32_swap_b32_e32 v0, v2
	v_cvt_pk_bf16_f32 v3, v4, v5
	s_nop 1
	v_permlane32_swap_b32_e32 v1, v3
	global_store_dwordx4 v[48:49], v[0:3], off offset:224
	s_waitcnt lgkmcnt(0)
	s_barrier
	s_waitcnt vmcnt(0)
	s_barrier

;     ...
;   const int fP = r * 128, fsw = (r >> 1) & 7;
;   const int fA = wm * 8192 + fP, fB = 32768 + wn * 16384 + fP;
;   f32x16 acc[2][4];
; #pragma unroll
;   for (int i = 0; i < 2; ++i)
; #pragma unroll
;     for (int j = 0; j < 4; ++j) acc[i][j] = zero16();
;   __syncthreads();
;   G_DMA(0, 0);
;   asm volatile("s_waitcnt vmcnt(0)" ::: "memory");
;   asm volatile("s_waitcnt lgkmcnt(0)" ::: "memory"); __builtin_amdgcn_s_barrier(); asm volatile("" ::: "memory");
;   int cur = 0;
;   for (int s = 0; s < S; ++s) {
;     G_DMA(s + 1, cur ^ BUFB);
;     {
;       const char* Ab = smem + cur + fA;
;       const char* Bb = smem + cur + fB;
;       __builtin_amdgcn_sched_barrier(0);
; #pragma unroll
;       for (int kk = 0; kk < 4; ++kk) {
;         const int ko = (((kk * 2 + hh) ^ fsw) << 4);
;         bf16x8 af[2], wf[4];
;         af[0] = *(const bf16x8*)(Ab + ko); af[1] = *(const bf16x8*)(Ab + 4096 + ko);
; #pragma unroll
;         for (int ni = 0; ni < 4; ++ni) wf[ni] = *(const bf16x8*)(Bb + ni * 4096 + ko);
; #pragma unroll
;         for (int mi = 0; mi < 2; ++mi)
; #pragma unroll
;           for (int ni = 0; ni < 4; ++ni) acc[mi][ni] = MFMA(wf[ni], af[mi], acc[mi][ni]);
;         if (kk == 1) __builtin_amdgcn_sched_barrier(0);
;       }
;       __builtin_amdgcn_sched_barrier(0);
;     }
;     asm volatile("s_waitcnt vmcnt(0)" ::: "memory");
;     if ((s & (nk - 1)) == nk - 1) {
;       const int q = slot + (s >> lnk) * nslots;
;       int mt, nt; G_TILEMAP(q, mt, nt);
;       if (dostore) {
; #pragma unroll
;         for (int mi = 0; mi < 2; ++mi) {
;           const size_t m = (size_t)mt * 256 + wm * 64 + mi * 32 + r;
; #pragma unroll
;           for (int ni = 0; ni < 4; ++ni) {
;             __builtin_amdgcn_sched_barrier(0);
;             if (MODE == 0) {
; #pragma unroll
;               for (int gp = 0; gp < 2; ++gp) {
;                 const int g0 = 2 * gp;
;                 uint2 pa, pb;
;                 pa.x = pack2(acc[mi][ni][4 * g0], acc[mi][ni][4 * g0 + 1]); pa.y = pack2(acc[mi][ni][4 * g0 + 2], acc[mi][ni][4 * g0 + 3]);
;                 pb.x = pack2(acc[mi][ni][4 * g0 + 4], acc[mi][ni][4 * g0 + 5]); pb.y = pack2(acc[mi][ni][4 * g0 + 6], acc[mi][ni][4 * g0 + 7]);
;                 { auto rx = __builtin_amdgcn_permlane32_swap(pa.x, pb.x, false, false); pa.x = rx[0]; pb.x = rx[1]; }
.LBB0_741:
	s_add_i32 s7, s8, 1
	s_mov_b32 s9, s6
	s_cmp_lt_u32 s7, s22
	v_readlane_b32 s6, v251, 36
	s_cselect_b32 s24, s7, s6
	s_lshl_b32 s6, s24, 1
	s_and_b32 s6, s6, 0x7ffffe0
	s_add_i32 s6, s6, s33
	s_lshl_b32 s6, s6, 5
	s_and_b32 s22, s6, 0xffffff00
	s_ashr_i32 s23, s22, 31
	s_lshl_b64 s[22:23], s[22:23], 11
	s_add_u32 s22, s62, s22
	s_addc_u32 s23, s63, s23
	s_xor_b32 s6, s9, 0x10000
	v_add_u32_e32 v128, s6, v142
	s_lshl_b32 s24, s24, 7
	s_and_b32 s28, s24, 0x780
	v_readfirstlane_b32 s24, v128
	v_add_u32_e32 v152, 0x2000, v128
	v_lshl_add_u64 v[148:149], v[134:135], 0, s[28:29]
	s_mov_b32 m0, s24
	s_mov_b64 s[44:45], 0x20000
	v_readfirstlane_b32 s24, v152
	v_add_u32_e32 v152, 0x4000, v128
	global_load_lds_dwordx4 v[148:149], off
	v_add3_u32 v187, s9, v131, v140
	v_add3_u32 v208, s9, v141, v140
	v_add_u32_e32 v182, v208, v144
	v_add_u32_e32 v183, v187, v144
	ds_read_b128 v[192:195], v182 offset:32768
	ds_read_b128 v[216:219], v183
	ds_read_b128 v[196:199], v182 offset:36864
	ds_read_b128 v[200:203], v182 offset:40960
	ds_read_b128 v[204:207], v182 offset:45056
	ds_read_b128 v[220:223], v183 offset:4096
	v_add_u32_e32 v184, v208, v145
	v_add_u32_e32 v185, v187, v145
	ds_read_b128 v[224:227], v184 offset:32768
	ds_read_b128 v[240:243], v185
	ds_read_b128 v[228:231], v184 offset:36864
	ds_read_b128 v[232:235], v184 offset:40960
	ds_read_b128 v[236:239], v184 offset:45056
	ds_read_b128 v[244:247], v185 offset:4096
	s_waitcnt lgkmcnt(10)
	v_mfma_f32_32x32x16_bf16 v[112:127], v[192:195], v[216:219], v[112:127]
	s_waitcnt lgkmcnt(9)
	v_mfma_f32_32x32x16_bf16 v[96:111], v[196:199], v[216:219], v[96:111]
	v_lshl_add_u64 v[150:151], v[148:149], 0, s[44:45]
	s_mov_b32 m0, s24
	s_mov_b64 s[42:43], 0x40000
	v_readfirstlane_b32 s24, v152
	global_load_lds_dwordx4 v[150:151], off
	s_waitcnt lgkmcnt(8)
	v_mfma_f32_32x32x16_bf16 v[80:95], v[200:203], v[216:219], v[80:95]
	s_waitcnt lgkmcnt(7)
	v_mfma_f32_32x32x16_bf16 v[64:79], v[204:207], v[216:219], v[64:79]
	v_lshl_add_u64 v[150:151], v[148:149], 0, s[42:43]
	s_mov_b32 m0, s24
	s_mov_b64 s[46:47], 0x60000
	global_load_lds_dwordx4 v[150:151], off
	s_waitcnt lgkmcnt(6)
	v_mfma_f32_32x32x16_bf16 v[48:63], v[192:195], v[220:223], v[48:63]
	v_mfma_f32_32x32x16_bf16 v[32:47], v[196:199], v[220:223], v[32:47]
	v_add_u32_e32 v150, 0x6000, v128
	s_add_u32 s22, s22, s28
	v_readfirstlane_b32 s24, v150
	v_lshl_add_u64 v[148:149], v[148:149], 0, s[46:47]
	s_mov_b32 m0, s24
	s_addc_u32 s23, s23, 0
	v_add_u32_e32 v150, 0x8000, v128
	global_load_lds_dwordx4 v[148:149], off
	v_mfma_f32_32x32x16_bf16 v[16:31], v[200:203], v[220:223], v[16:31]
	v_mfma_f32_32x32x16_bf16 v[0:15], v[204:207], v[220:223], v[0:15]
	v_lshl_add_u64 v[148:149], s[22:23], 0, v[132:133]
	v_readfirstlane_b32 s22, v150
	v_add_u32_e32 v152, 0xa000, v128
	s_mov_b32 m0, s22
	v_readfirstlane_b32 s22, v152
	v_add_u32_e32 v152, 0xc000, v128
	global_load_lds_dwordx4 v[148:149], off
	v_add_u32_e32 v182, v208, v146
	v_add_u32_e32 v183, v187, v146
	ds_read_b128 v[192:195], v182 offset:32768
	ds_read_b128 v[216:219], v183
	ds_read_b128 v[196:199], v182 offset:36864
	ds_read_b128 v[200:203], v182 offset:40960
	ds_read_b128 v[204:207], v182 offset:45056
	ds_read_b128 v[220:223], v183 offset:4096
	s_waitcnt lgkmcnt(10)
	v_mfma_f32_32x32x16_bf16 v[112:127], v[224:227], v[240:243], v[112:127]
	s_waitcnt lgkmcnt(9)
	v_mfma_f32_32x32x16_bf16 v[96:111], v[228:231], v[240:243], v[96:111]
	v_lshl_add_u64 v[150:151], v[148:149], 0, s[44:45]
	s_mov_b32 m0, s22
	v_readfirstlane_b32 s22, v152
	v_add_u32_e32 v128, 0xe000, v128
	global_load_lds_dwordx4 v[150:151], off
	s_waitcnt lgkmcnt(8)
	v_mfma_f32_32x32x16_bf16 v[80:95], v[232:235], v[240:243], v[80:95]
	s_waitcnt lgkmcnt(7)
	v_mfma_f32_32x32x16_bf16 v[64:79], v[236:239], v[240:243], v[64:79]
	v_lshl_add_u64 v[150:151], v[148:149], 0, s[42:43]
	s_mov_b32 m0, s22
	v_readfirstlane_b32 s22, v128
	global_load_lds_dwordx4 v[150:151], off
	s_waitcnt lgkmcnt(6)
	v_mfma_f32_32x32x16_bf16 v[48:63], v[224:227], v[244:247], v[48:63]
	v_mfma_f32_32x32x16_bf16 v[32:47], v[228:231], v[244:247], v[32:47]
	v_lshl_add_u64 v[148:149], v[148:149], 0, s[46:47]
	s_mov_b32 m0, s22
	s_add_i32 s9, s9, 0
	global_load_lds_dwordx4 v[148:149], off
	v_mfma_f32_32x32x16_bf16 v[16:31], v[232:235], v[244:247], v[16:31]
	v_mfma_f32_32x32x16_bf16 v[0:15], v[236:239], v[244:247], v[0:15]
	v_add_u32_e32 v184, v208, v147
	v_add_u32_e32 v185, v187, v147
	ds_read_b128 v[224:227], v184 offset:32768
	ds_read_b128 v[240:243], v185
	ds_read_b128 v[228:231], v184 offset:36864
	ds_read_b128 v[232:235], v184 offset:40960
	ds_read_b128 v[236:239], v184 offset:45056
	ds_read_b128 v[244:247], v185 offset:4096
	s_waitcnt lgkmcnt(10)
	v_mfma_f32_32x32x16_bf16 v[112:127], v[192:195], v[216:219], v[112:127]
	s_waitcnt lgkmcnt(9)
	v_mfma_f32_32x32x16_bf16 v[96:111], v[196:199], v[216:219], v[96:111]
	s_waitcnt lgkmcnt(8)
	v_mfma_f32_32x32x16_bf16 v[80:95], v[200:203], v[216:219], v[80:95]
	s_waitcnt lgkmcnt(7)
	v_mfma_f32_32x32x16_bf16 v[64:79], v[204:207], v[216:219], v[64:79]
	s_waitcnt lgkmcnt(6)
	v_mfma_f32_32x32x16_bf16 v[48:63], v[192:195], v[220:223], v[48:63]
	v_mfma_f32_32x32x16_bf16 v[32:47], v[196:199], v[220:223], v[32:47]
	v_mfma_f32_32x32x16_bf16 v[16:31], v[200:203], v[220:223], v[16:31]
	v_mfma_f32_32x32x16_bf16 v[0:15], v[204:207], v[220:223], v[0:15]
	s_waitcnt lgkmcnt(4)
	v_mfma_f32_32x32x16_bf16 v[112:127], v[224:227], v[240:243], v[112:127]
	s_waitcnt lgkmcnt(3)
	v_mfma_f32_32x32x16_bf16 v[96:111], v[228:231], v[240:243], v[96:111]
	s_waitcnt lgkmcnt(2)
	v_mfma_f32_32x32x16_bf16 v[80:95], v[232:235], v[240:243], v[80:95]
	s_waitcnt lgkmcnt(1)
	v_mfma_f32_32x32x16_bf16 v[64:79], v[236:239], v[240:243], v[64:79]
	s_waitcnt lgkmcnt(0)
	v_mfma_f32_32x32x16_bf16 v[48:63], v[224:227], v[244:247], v[48:63]
	v_mfma_f32_32x32x16_bf16 v[32:47], v[228:231], v[244:247], v[32:47]
	v_mfma_f32_32x32x16_bf16 v[16:31], v[232:235], v[244:247], v[16:31]
	v_mfma_f32_32x32x16_bf16 v[0:15], v[236:239], v[244:247], v[0:15]
	s_waitcnt vmcnt(0)
	s_and_b32 s9, s8, 15
	s_cmp_lg_u32 s9, 15
	s_cbranch_scc1 .LBB0_740
	s_lshl_b32 s8, s8, 1
	s_and_b32 s8, s8, 0x3ffffe0
	s_add_i32 s8, s8, s33
	s_lshl_b32 s8, s8, 5
	s_and_b32 s8, s8, 0x7fffff00
	v_or_b32_e32 v148, s8, v143
	v_cvt_pk_bf16_f32 v112, v112, v113
	v_cvt_pk_bf16_f32 v113, v114, v115
	v_cvt_pk_bf16_f32 v114, v116, v117
	v_cvt_pk_bf16_f32 v115, v118, v119
	s_movk_i32 s8, 0x1480
	v_permlane32_swap_b32_e32 v112, v114
	v_permlane32_swap_b32_e32 v113, v115
	v_cmp_gt_u32_e32 vcc, s8, v148
	v_lshlrev_b32_e32 v128, 1, v148
	s_and_saveexec_b64 s[22:23], vcc
	s_cbranch_execz .LBB0_744
	v_lshl_add_u64 v[116:117], v[136:137], 0, v[128:129]
	global_store_dwordx4 v[116:117], v[112:115], off

; #define MFMA(a, b, c) __builtin_amdgcn_mfma_f32_32x32x16_bf16((a), (b), (c), 0, 0, 0)
;     ...
;   for (int s = 0; s < S; ++s) {
;     G_DMA(s + 1, cur ^ BUFB);
;     {
;       const char* Ab = smem + cur + fA;
;       const char* Bb = smem + cur + fB;
;       __builtin_amdgcn_sched_barrier(0);
; #pragma unroll
;       for (int kk = 0; kk < 4; ++kk) {
;         const int ko = (((kk * 2 + hh) ^ fsw) << 4);
;         bf16x8 af[2], wf[4];
;         af[0] = *(const bf16x8*)(Ab + ko); af[1] = *(const bf16x8*)(Ab + 4096 + ko);
; #pragma unroll
;         for (int ni = 0; ni < 4; ++ni) wf[ni] = *(const bf16x8*)(Bb + ni * 4096 + ko);
; #pragma unroll
;         for (int mi = 0; mi < 2; ++mi)
; #pragma unroll
;           for (int ni = 0; ni < 4; ++ni) acc[mi][ni] = MFMA(wf[ni], af[mi], acc[mi][ni]);
;         if (kk == 1) __builtin_amdgcn_sched_barrier(0);
;       }
;       __builtin_amdgcn_sched_barrier(0);
;     }
;     asm volatile("s_waitcnt vmcnt(0)" ::: "memory");
.LBB0_1108:
	s_add_i32 s7, s8, 1
	s_mov_b32 s9, s6
	s_cmp_lt_u32 s7, s60
	v_readlane_b32 s6, v253, 59
	s_cselect_b32 s6, s7, s6
	s_lshl_b32 s22, s6, 1
	s_andn2_b32 s22, s22, 31
	s_add_i32 s22, s22, s33
	s_lshr_b32 s23, s22, 4
	s_lshr_b32 s22, s22, 3
	s_and_b32 s22, s22, 12
	v_readlane_b32 s46, v252, 41
	s_and_b32 s23, s23, 0xfffff8
	s_or_b32 s22, s22, s46
	s_or_b32 s24, s23, s74
	s_lshl_b32 s22, s22, 19
	v_readlane_b32 s40, v253, 39
	v_readlane_b32 s41, v253, 40
	s_add_u32 s22, s40, s22
	s_addc_u32 s23, s41, 0
	s_lshl_b32 s6, s6, 7
	s_and_b32 s28, s6, 0x780
	s_add_u32 s22, s22, s28
	s_addc_u32 s23, s23, 0
	s_lshl_b32 s24, s24, 8
	s_ashr_i32 s25, s24, 31
	s_lshl_b64 s[24:25], s[24:25], 11
	s_add_u32 s24, s62, s24
	s_addc_u32 s25, s63, s25
	s_xor_b32 s6, s9, 0x10000
	v_add_u32_e32 v128, s6, v131
	v_lshl_add_u64 v[170:171], s[22:23], 0, v[132:133]
	v_readfirstlane_b32 s22, v128
	v_add_u32_e32 v169, 0x2000, v128
	s_mov_b32 m0, s22
	s_mov_b64 s[42:43], 0x20000
	v_readfirstlane_b32 s22, v169
	v_add_u32_e32 v169, 0x4000, v128
	global_load_lds_dwordx4 v[170:171], off
	v_lshl_add_u64 v[172:173], v[170:171], 0, s[42:43]
	s_mov_b32 m0, s22
	s_mov_b64 s[40:41], 0x40000
	v_readfirstlane_b32 s22, v169
	v_add_u32_e32 v169, 0x6000, v128
	global_load_lds_dwordx4 v[172:173], off
	v_lshl_add_u64 v[172:173], v[170:171], 0, s[40:41]
	s_mov_b32 m0, s22
	v_readfirstlane_b32 s22, v169
	global_load_lds_dwordx4 v[172:173], off
	s_mov_b64 s[44:45], 0x60000
	s_mov_b32 m0, s22
	s_add_u32 s22, s24, s28
	v_lshl_add_u64 v[170:171], v[170:171], 0, s[44:45]
	s_addc_u32 s23, s25, 0
	v_add_u32_e32 v169, 0x8000, v128
	global_load_lds_dwordx4 v[170:171], off
	v_lshl_add_u64 v[170:171], s[22:23], 0, v[132:133]
	v_readfirstlane_b32 s22, v169
	v_add_u32_e32 v169, 0xa000, v128
	s_mov_b32 m0, s22
	v_readfirstlane_b32 s22, v169
	v_add_u32_e32 v169, 0xc000, v128
	global_load_lds_dwordx4 v[170:171], off
	v_lshl_add_u64 v[172:173], v[170:171], 0, s[42:43]
	s_mov_b32 m0, s22
	v_readfirstlane_b32 s22, v169
	v_add_u32_e32 v128, 0xe000, v128
	global_load_lds_dwordx4 v[172:173], off
	v_lshl_add_u64 v[172:173], v[170:171], 0, s[40:41]
	s_mov_b32 m0, s22
	v_readfirstlane_b32 s22, v128
	global_load_lds_dwordx4 v[172:173], off
	v_lshl_add_u64 v[170:171], v[170:171], 0, s[44:45]
	s_mov_b32 m0, s22
	s_add_i32 s9, s9, 0
	global_load_lds_dwordx4 v[170:171], off
	v_add3_u32 v128, s9, v187, v189
	v_add3_u32 v169, s9, v188, v189
	v_add_u32_e32 v182, v169, v190
	v_add_u32_e32 v183, v128, v190
	ds_read_b128 v[170:173], v182 offset:32768
	ds_read_b128 v[194:197], v183
	ds_read_b128 v[198:201], v182 offset:36864
	ds_read_b128 v[202:205], v182 offset:40960
	ds_read_b128 v[206:209], v182 offset:45056
	ds_read_b128 v[216:219], v183 offset:4096
	v_add_u32_e32 v184, v169, v191
	v_add_u32_e32 v185, v128, v191
	ds_read_b128 v[220:223], v184 offset:32768
	ds_read_b128 v[236:239], v185
	ds_read_b128 v[224:227], v184 offset:36864
	ds_read_b128 v[228:231], v184 offset:40960
	ds_read_b128 v[232:235], v184 offset:45056
	ds_read_b128 v[240:243], v185 offset:4096
	s_waitcnt lgkmcnt(10)
	v_mfma_f32_32x32x16_bf16 v[112:127], v[170:173], v[194:197], v[112:127]
	s_waitcnt lgkmcnt(9)
	v_mfma_f32_32x32x16_bf16 v[96:111], v[198:201], v[194:197], v[96:111]
	s_waitcnt lgkmcnt(8)
	v_mfma_f32_32x32x16_bf16 v[80:95], v[202:205], v[194:197], v[80:95]
	s_waitcnt lgkmcnt(7)
	v_mfma_f32_32x32x16_bf16 v[64:79], v[206:209], v[194:197], v[64:79]
	s_waitcnt lgkmcnt(6)
	v_mfma_f32_32x32x16_bf16 v[48:63], v[170:173], v[216:219], v[48:63]
	v_mfma_f32_32x32x16_bf16 v[32:47], v[198:201], v[216:219], v[32:47]
	v_mfma_f32_32x32x16_bf16 v[16:31], v[202:205], v[216:219], v[16:31]
	v_mfma_f32_32x32x16_bf16 v[0:15], v[206:209], v[216:219], v[0:15]
	v_add_u32_e32 v182, v169, v192
	v_add_u32_e32 v183, v128, v192
	ds_read_b128 v[170:173], v182 offset:32768
	ds_read_b128 v[194:197], v183
	ds_read_b128 v[198:201], v182 offset:36864
	ds_read_b128 v[202:205], v182 offset:40960
	ds_read_b128 v[206:209], v182 offset:45056
	ds_read_b128 v[216:219], v183 offset:4096
	s_waitcnt lgkmcnt(10)
	v_mfma_f32_32x32x16_bf16 v[112:127], v[220:223], v[236:239], v[112:127]
	s_waitcnt lgkmcnt(9)
	v_mfma_f32_32x32x16_bf16 v[96:111], v[224:227], v[236:239], v[96:111]
	s_waitcnt lgkmcnt(8)
	v_mfma_f32_32x32x16_bf16 v[80:95], v[228:231], v[236:239], v[80:95]
	s_waitcnt lgkmcnt(7)
	v_mfma_f32_32x32x16_bf16 v[64:79], v[232:235], v[236:239], v[64:79]
	s_waitcnt lgkmcnt(6)
	v_mfma_f32_32x32x16_bf16 v[48:63], v[220:223], v[240:243], v[48:63]
	v_mfma_f32_32x32x16_bf16 v[32:47], v[224:227], v[240:243], v[32:47]
	v_mfma_f32_32x32x16_bf16 v[16:31], v[228:231], v[240:243], v[16:31]
	v_mfma_f32_32x32x16_bf16 v[0:15], v[232:235], v[240:243], v[0:15]
	v_add_u32_e32 v184, v169, v193
	v_add_u32_e32 v185, v128, v193
	ds_read_b128 v[220:223], v184 offset:32768
	ds_read_b128 v[236:239], v185
	ds_read_b128 v[224:227], v184 offset:36864
	ds_read_b128 v[228:231], v184 offset:40960
	ds_read_b128 v[232:235], v184 offset:45056
	ds_read_b128 v[240:243], v185 offset:4096
	s_waitcnt lgkmcnt(10)
	v_mfma_f32_32x32x16_bf16 v[112:127], v[170:173], v[194:197], v[112:127]
	s_waitcnt lgkmcnt(9)
	v_mfma_f32_32x32x16_bf16 v[96:111], v[198:201], v[194:197], v[96:111]
	s_waitcnt lgkmcnt(8)
	v_mfma_f32_32x32x16_bf16 v[80:95], v[202:205], v[194:197], v[80:95]
	s_waitcnt lgkmcnt(7)
	v_mfma_f32_32x32x16_bf16 v[64:79], v[206:209], v[194:197], v[64:79]
	s_waitcnt lgkmcnt(6)
	v_mfma_f32_32x32x16_bf16 v[48:63], v[170:173], v[216:219], v[48:63]
	v_mfma_f32_32x32x16_bf16 v[32:47], v[198:201], v[216:219], v[32:47]
	v_mfma_f32_32x32x16_bf16 v[16:31], v[202:205], v[216:219], v[16:31]
	v_mfma_f32_32x32x16_bf16 v[0:15], v[206:209], v[216:219], v[0:15]
	s_waitcnt lgkmcnt(4)
	v_mfma_f32_32x32x16_bf16 v[112:127], v[220:223], v[236:239], v[112:127]
	s_waitcnt lgkmcnt(3)
	v_mfma_f32_32x32x16_bf16 v[96:111], v[224:227], v[236:239], v[96:111]
	s_waitcnt lgkmcnt(2)
	v_mfma_f32_32x32x16_bf16 v[80:95], v[228:231], v[236:239], v[80:95]
	s_waitcnt lgkmcnt(1)
	v_mfma_f32_32x32x16_bf16 v[64:79], v[232:235], v[236:239], v[64:79]
	s_waitcnt lgkmcnt(0)
	v_mfma_f32_32x32x16_bf16 v[48:63], v[220:223], v[240:243], v[48:63]
	v_mfma_f32_32x32x16_bf16 v[32:47], v[224:227], v[240:243], v[32:47]
	v_mfma_f32_32x32x16_bf16 v[16:31], v[228:231], v[240:243], v[16:31]
	v_mfma_f32_32x32x16_bf16 v[0:15], v[232:235], v[240:243], v[0:15]
	s_waitcnt vmcnt(0)
	s_and_b32 s9, s8, 15
	s_cmp_lg_u32 s9, 15
	s_cbranch_scc1 .LBB0_1107
; DI unsigned pack2(float a, float b) { f32x2_t v = {a, b}; return __builtin_bit_cast(unsigned, __builtin_convertvector(v, bf16x2_t)); }
; #define G_TILEMAP(q, MT, NT) do { if (sq) { const int grp_ = (q) >> 5, i_ = (q) & 31; \
;       MT = xcd * mpx + (grp_ & (mpx / 4 - 1)) * 4 + (i_ & 3); NT = (grp_ >> (LMPX - 2)) * 8 + (i_ >> 2); } \
;     else { MT = xcd * mpx + ((q) & (mpx - 1)); NT = (q) >> LMPX; } } while (0)
;     ...
;     if ((s & (nk - 1)) == nk - 1) {
;       const int q = slot + (s >> lnk) * nslots;
;       int mt, nt; G_TILEMAP(q, mt, nt);
;       if (dostore) {
; #pragma unroll
;         for (int mi = 0; mi < 2; ++mi) {
;           const size_t m = (size_t)mt * 256 + wm * 64 + mi * 32 + r;
;     ...
;             for (int g = 0; g < 4; ++g) {
;               const int n = nt * 256 + wn * 128 + ni * 32 + 8 * g + 4 * hh;
;               const float a0 = acc[mi][ni][4 * g], a1 = acc[mi][ni][4 * g + 1], a2 = acc[mi][ni][4 * g + 2], a3 = acc[mi][ni][4 * g + 3];
;               if (MODE == 0) {
;                 uint2 pk; pk.x = pack2(a0, a1); pk.y = pack2(a2, a3);
;                 if (outp != nullptr && nt >= 32) *(uint2*)(outp + m * 2048 + (n - 8192)) = pk;
;                 else if (n < nvalid) *(uint2*)(C + m * ldc + n) = pk;
;               } else if (MODE == 2) {
;                 const unsigned p01 = pack2(a0, a1), p23 = pack2(a2, a3);
;                 bf16_t* dst = ((nt < 8) ? C : outp) + ((size_t)(n & 2047) * 8 + (m >> 12)) * SEQ + (m & 4095);
;                 dst[0] = (bf16_t)(p01 & 0xffffu); dst[(size_t)8 * SEQ] = (bf16_t)(p01 >> 16);
;                 dst[(size_t)16 * SEQ] = (bf16_t)(p23 & 0xffffu); dst[(size_t)24 * SEQ] = (bf16_t)(p23 >> 16);
	s_lshl_b32 s8, s8, 1
	s_and_b32 s8, s8, 0x7fffffe0
	s_add_i32 s8, s8, s33
	s_lshr_b32 s9, s8, 3
	s_and_b32 s9, s9, 12
	s_or_b32 s9, s9, s46
	s_lshl_b32 s28, s9, 8
	s_cmpk_lt_u32 s8, 0x80
	v_lshl_add_u64 v[170:171], s[28:29], 0, v[134:135]
	s_cselect_b32 s8, s11, s31
	s_cselect_b32 s9, s10, s30
	v_mov_b32_e32 v172, s9
	v_mov_b32_e32 v173, s8
	v_and_b32_e32 v175, 0x7fffffff, v171
	v_and_b32_e32 v174, 0xfffff000, v170
	v_and_b32_e32 v128, 0xfc0, v170
	v_lshl_add_u64 v[172:173], v[174:175], 1, v[172:173]
	v_lshlrev_b32_e32 v128, 1, v128
	v_lshl_add_u64 v[170:171], v[172:173], 0, v[128:129]
	v_mov_b32_e32 v169, v129
	v_lshl_add_u64 v[170:171], v[170:171], 0, v[168:169]
	v_cvt_pk_bf16_f32 v128, v112, v113
	v_lshl_add_u64 v[112:113], v[170:171], 0, v[136:137]
	s_mov_b32 s8, 0x10000
	v_cvt_pk_bf16_f32 v169, v114, v115
	v_add_co_u32_e32 v114, vcc, s8, v112
	s_mov_b32 s9, 0x20000
	s_nop 0
	v_addc_co_u32_e32 v115, vcc, 0, v113, vcc
	v_add_co_u32_e32 v172, vcc, s9, v112
	s_mov_b32 s22, 0x30000
	s_nop 0
	v_addc_co_u32_e32 v173, vcc, 0, v113, vcc
	v_add_co_u32_e32 v174, vcc, s22, v112
	global_store_short v[112:113], v128, off
	global_store_short_d16_hi v[114:115], v128, off
	v_addc_co_u32_e32 v175, vcc, 0, v113, vcc
	v_cvt_pk_bf16_f32 v128, v116, v117
	v_lshl_add_u64 v[116:117], v[170:171], 0, v[138:139]
	global_store_short v[172:173], v169, off
	global_store_short_d16_hi v[174:175], v169, off
	v_cvt_pk_bf16_f32 v169, v118, v119
	v_add_co_u32_e32 v118, vcc, s8, v116
	global_store_short v[116:117], v128, off
	s_nop 0
	v_addc_co_u32_e32 v119, vcc, 0, v117, vcc
	global_store_short_d16_hi v[118:119], v128, off
	v_add_co_u32_e32 v118, vcc, s9, v116
	v_cvt_pk_bf16_f32 v120, v120, v121
	s_nop 0
	v_addc_co_u32_e32 v119, vcc, 0, v117, vcc
	v_add_co_u32_e32 v116, vcc, s22, v116
	global_store_short v[118:119], v169, off
	s_nop 0
	v_addc_co_u32_e32 v117, vcc, 0, v117, vcc
	global_store_short_d16_hi v[116:117], v169, off
	v_lshl_add_u64 v[116:117], v[170:171], 0, v[140:141]
	v_add_co_u32_e32 v118, vcc, s8, v116
	global_store_short v[116:117], v120, off
	s_nop 0
	v_addc_co_u32_e32 v119, vcc, 0, v117, vcc
	global_store_short_d16_hi v[118:119], v120, off
	v_add_co_u32_e32 v118, vcc, s9, v116
	v_cvt_pk_bf16_f32 v121, v122, v123
	s_nop 0
	v_addc_co_u32_e32 v119, vcc, 0, v117, vcc
	v_add_co_u32_e32 v116, vcc, s22, v116
	global_store_short v[118:119], v121, off
	s_nop 0
	v_addc_co_u32_e32 v117, vcc, 0, v117, vcc
	global_store_short_d16_hi v[116:117], v121, off
	v_lshl_add_u64 v[116:117], v[170:171], 0, v[142:143]
	v_add_co_u32_e32 v118, vcc, s8, v116
	v_cvt_pk_bf16_f32 v120, v124, v125
	s_nop 0
	v_addc_co_u32_e32 v119, vcc, 0, v117, vcc
	global_store_short_d16_hi v[118:119], v120, off
	v_add_co_u32_e32 v118, vcc, s9, v116
	global_store_short v[116:117], v120, off
	s_nop 0
	v_addc_co_u32_e32 v119, vcc, 0, v117, vcc
	v_add_co_u32_e32 v116, vcc, s22, v116
	v_cvt_pk_bf16_f32 v121, v126, v127
	s_nop 0
	v_addc_co_u32_e32 v117, vcc, 0, v117, vcc
	global_store_short v[118:119], v121, off
	global_store_short_d16_hi v[116:117], v121, off
	v_cvt_pk_bf16_f32 v116, v96, v97
	v_lshl_add_u64 v[96:97], v[170:171], 0, v[144:145]
	v_cvt_pk_bf16_f32 v117, v98, v99
	v_add_co_u32_e32 v98, vcc, s8, v96
	global_store_short v[96:97], v116, off
	s_nop 0
	v_addc_co_u32_e32 v99, vcc, 0, v97, vcc
	global_store_short_d16_hi v[98:99], v116, off
	v_add_co_u32_e32 v98, vcc, s9, v96
	v_cvt_pk_bf16_f32 v100, v100, v101
	s_nop 0
	v_addc_co_u32_e32 v99, vcc, 0, v97, vcc
	v_add_co_u32_e32 v96, vcc, s22, v96
	global_store_short v[98:99], v117, off
	s_nop 0
	v_addc_co_u32_e32 v97, vcc, 0, v97, vcc
	global_store_short_d16_hi v[96:97], v117, off
	v_lshl_add_u64 v[96:97], v[170:171], 0, v[146:147]
	v_add_co_u32_e32 v98, vcc, s8, v96
	global_store_short v[96:97], v100, off
	s_nop 0
	v_addc_co_u32_e32 v99, vcc, 0, v97, vcc
	global_store_short_d16_hi v[98:99], v100, off
	v_add_co_u32_e32 v98, vcc, s9, v96
	v_cvt_pk_bf16_f32 v101, v102, v103
	s_nop 0
	v_addc_co_u32_e32 v99, vcc, 0, v97, vcc
	v_add_co_u32_e32 v96, vcc, s22, v96
	global_store_short v[98:99], v101, off
	s_nop 0
	v_addc_co_u32_e32 v97, vcc, 0, v97, vcc
	global_store_short_d16_hi v[96:97], v101, off
	v_lshl_add_u64 v[96:97], v[170:171], 0, v[148:149]
	v_add_co_u32_e32 v98, vcc, s8, v96
	v_cvt_pk_bf16_f32 v100, v104, v105
	s_nop 0
	v_addc_co_u32_e32 v99, vcc, 0, v97, vcc
	global_store_short_d16_hi v[98:99], v100, off
	v_add_co_u32_e32 v98, vcc, s9, v96
	global_store_short v[96:97], v100, off
	s_nop 0
	v_addc_co_u32_e32 v99, vcc, 0, v97, vcc
	v_add_co_u32_e32 v96, vcc, s22, v96
	v_cvt_pk_bf16_f32 v101, v106, v107
	s_nop 0
	v_addc_co_u32_e32 v97, vcc, 0, v97, vcc
	global_store_short_d16_hi v[96:97], v101, off
	v_lshl_add_u64 v[96:97], v[170:171], 0, v[150:151]
	global_store_short v[98:99], v101, off
	v_add_co_u32_e32 v98, vcc, s8, v96
	v_cvt_pk_bf16_f32 v100, v108, v109
	s_nop 0
	v_addc_co_u32_e32 v99, vcc, 0, v97, vcc
	global_store_short_d16_hi v[98:99], v100, off
	v_add_co_u32_e32 v98, vcc, s9, v96
	global_store_short v[96:97], v100, off
	s_nop 0
	v_addc_co_u32_e32 v99, vcc, 0, v97, vcc
	v_add_co_u32_e32 v96, vcc, s22, v96
	v_cvt_pk_bf16_f32 v101, v110, v111
	s_nop 0
	v_addc_co_u32_e32 v97, vcc, 0, v97, vcc
	global_store_short v[98:99], v101, off
	global_store_short_d16_hi v[96:97], v101, off
	v_cvt_pk_bf16_f32 v96, v80, v81
	v_lshl_add_u64 v[80:81], v[170:171], 0, v[152:153]
	v_cvt_pk_bf16_f32 v97, v82, v83
	v_add_co_u32_e32 v82, vcc, s8, v80
	global_store_short v[80:81], v96, off
	s_nop 0
	v_addc_co_u32_e32 v83, vcc, 0, v81, vcc
	global_store_short_d16_hi v[82:83], v96, off
	v_add_co_u32_e32 v82, vcc, s9, v80
	v_cvt_pk_bf16_f32 v84, v84, v85
	s_nop 0
; DI unsigned pack2(float a, float b) { f32x2_t v = {a, b}; return __builtin_bit_cast(unsigned, __builtin_convertvector(v, bf16x2_t)); }
;     ...
;             for (int g = 0; g < 4; ++g) {
;               const int n = nt * 256 + wn * 128 + ni * 32 + 8 * g + 4 * hh;
;               const float a0 = acc[mi][ni][4 * g], a1 = acc[mi][ni][4 * g + 1], a2 = acc[mi][ni][4 * g + 2], a3 = acc[mi][ni][4 * g + 3];
;               if (MODE == 0) {
;                 uint2 pk; pk.x = pack2(a0, a1); pk.y = pack2(a2, a3);
;                 if (outp != nullptr && nt >= 32) *(uint2*)(outp + m * 2048 + (n - 8192)) = pk;
;                 else if (n < nvalid) *(uint2*)(C + m * ldc + n) = pk;
;               } else if (MODE == 2) {
;                 const unsigned p01 = pack2(a0, a1), p23 = pack2(a2, a3);
;                 bf16_t* dst = ((nt < 8) ? C : outp) + ((size_t)(n & 2047) * 8 + (m >> 12)) * SEQ + (m & 4095);
;                 dst[0] = (bf16_t)(p01 & 0xffffu); dst[(size_t)8 * SEQ] = (bf16_t)(p01 >> 16);
;                 dst[(size_t)16 * SEQ] = (bf16_t)(p23 & 0xffffu); dst[(size_t)24 * SEQ] = (bf16_t)(p23 >> 16);
	v_addc_co_u32_e32 v83, vcc, 0, v81, vcc
	v_add_co_u32_e32 v80, vcc, s22, v80
	global_store_short v[82:83], v97, off
	s_nop 0
	v_addc_co_u32_e32 v81, vcc, 0, v81, vcc
	global_store_short_d16_hi v[80:81], v97, off
	v_lshl_add_u64 v[80:81], v[170:171], 0, v[154:155]
	v_add_co_u32_e32 v82, vcc, s8, v80
	global_store_short v[80:81], v84, off
	s_nop 0
	v_addc_co_u32_e32 v83, vcc, 0, v81, vcc
	global_store_short_d16_hi v[82:83], v84, off
	v_add_co_u32_e32 v82, vcc, s9, v80
	v_cvt_pk_bf16_f32 v85, v86, v87
	s_nop 0
	v_addc_co_u32_e32 v83, vcc, 0, v81, vcc
	v_add_co_u32_e32 v80, vcc, s22, v80
	global_store_short v[82:83], v85, off
	s_nop 0
	v_addc_co_u32_e32 v81, vcc, 0, v81, vcc
	global_store_short_d16_hi v[80:81], v85, off
	v_lshl_add_u64 v[80:81], v[170:171], 0, v[156:157]
	v_add_co_u32_e32 v82, vcc, s8, v80
	v_cvt_pk_bf16_f32 v84, v88, v89
	s_nop 0
	v_addc_co_u32_e32 v83, vcc, 0, v81, vcc
	global_store_short_d16_hi v[82:83], v84, off
	v_add_co_u32_e32 v82, vcc, s9, v80
	global_store_short v[80:81], v84, off
	s_nop 0
	v_addc_co_u32_e32 v83, vcc, 0, v81, vcc
	v_add_co_u32_e32 v80, vcc, s22, v80
	v_cvt_pk_bf16_f32 v85, v90, v91
	s_nop 0
	v_addc_co_u32_e32 v81, vcc, 0, v81, vcc
	global_store_short_d16_hi v[80:81], v85, off
	v_lshl_add_u64 v[80:81], v[170:171], 0, v[158:159]
	global_store_short v[82:83], v85, off
	v_add_co_u32_e32 v82, vcc, s8, v80
	v_cvt_pk_bf16_f32 v84, v92, v93
	s_nop 0
	v_addc_co_u32_e32 v83, vcc, 0, v81, vcc
	global_store_short_d16_hi v[82:83], v84, off
	v_add_co_u32_e32 v82, vcc, s9, v80
	global_store_short v[80:81], v84, off
	s_nop 0
	v_addc_co_u32_e32 v83, vcc, 0, v81, vcc
	v_add_co_u32_e32 v80, vcc, s22, v80
	v_cvt_pk_bf16_f32 v85, v94, v95
	s_nop 0
	v_addc_co_u32_e32 v81, vcc, 0, v81, vcc
	global_store_short v[82:83], v85, off
	global_store_short_d16_hi v[80:81], v85, off
	v_cvt_pk_bf16_f32 v80, v64, v65
	v_lshl_add_u64 v[64:65], v[170:171], 0, v[160:161]
	v_cvt_pk_bf16_f32 v81, v66, v67
	v_add_co_u32_e32 v66, vcc, s8, v64
	global_store_short v[64:65], v80, off
	s_nop 0
	v_addc_co_u32_e32 v67, vcc, 0, v65, vcc
	global_store_short_d16_hi v[66:67], v80, off
	v_add_co_u32_e32 v66, vcc, s9, v64
	v_cvt_pk_bf16_f32 v68, v68, v69
	s_nop 0
	v_addc_co_u32_e32 v67, vcc, 0, v65, vcc
	v_add_co_u32_e32 v64, vcc, s22, v64
	global_store_short v[66:67], v81, off
	s_nop 0
	v_addc_co_u32_e32 v65, vcc, 0, v65, vcc
	global_store_short_d16_hi v[64:65], v81, off
	v_lshl_add_u64 v[64:65], v[170:171], 0, v[162:163]
	v_add_co_u32_e32 v66, vcc, s8, v64
	global_store_short v[64:65], v68, off
	s_nop 0
	v_addc_co_u32_e32 v67, vcc, 0, v65, vcc
	global_store_short_d16_hi v[66:67], v68, off
	v_add_co_u32_e32 v66, vcc, s9, v64
	v_cvt_pk_bf16_f32 v69, v70, v71
	s_nop 0
	v_addc_co_u32_e32 v67, vcc, 0, v65, vcc
	v_add_co_u32_e32 v64, vcc, s22, v64
	global_store_short v[66:67], v69, off
	s_nop 0
	v_addc_co_u32_e32 v65, vcc, 0, v65, vcc
	global_store_short_d16_hi v[64:65], v69, off
	v_lshl_add_u64 v[64:65], v[170:171], 0, v[164:165]
	v_add_co_u32_e32 v66, vcc, s8, v64
	v_cvt_pk_bf16_f32 v68, v72, v73
	s_nop 0
	v_addc_co_u32_e32 v67, vcc, 0, v65, vcc
	global_store_short_d16_hi v[66:67], v68, off
	v_add_co_u32_e32 v66, vcc, s9, v64
	global_store_short v[64:65], v68, off
	s_nop 0
	v_addc_co_u32_e32 v67, vcc, 0, v65, vcc
	v_add_co_u32_e32 v64, vcc, s22, v64
	v_cvt_pk_bf16_f32 v69, v74, v75
	s_nop 0
	v_addc_co_u32_e32 v65, vcc, 0, v65, vcc
	global_store_short_d16_hi v[64:65], v69, off
	v_lshl_add_u64 v[64:65], v[170:171], 0, v[166:167]
	global_store_short v[66:67], v69, off
	v_add_co_u32_e32 v66, vcc, s8, v64
	v_cvt_pk_bf16_f32 v68, v76, v77
	s_nop 0
	v_addc_co_u32_e32 v67, vcc, 0, v65, vcc
	global_store_short_d16_hi v[66:67], v68, off
	v_add_co_u32_e32 v66, vcc, s9, v64
	global_store_short v[64:65], v68, off
	s_nop 0
	v_addc_co_u32_e32 v67, vcc, 0, v65, vcc
	v_add_co_u32_e32 v64, vcc, s22, v64
	v_cvt_pk_bf16_f32 v69, v78, v79
	s_nop 0
	v_addc_co_u32_e32 v65, vcc, 0, v65, vcc
	global_store_short_d16_hi v[64:65], v69, off
	v_lshl_add_u64 v[64:65], v[170:171], 0, 64
	global_store_short v[66:67], v69, off
	v_cvt_pk_bf16_f32 v48, v48, v49
	v_cvt_pk_bf16_f32 v49, v50, v51
	global_store_short v[112:113], v48, off offset:64
	global_store_short_d16_hi v[114:115], v48, off offset:64
	global_store_short v[172:173], v49, off offset:64
	global_store_short_d16_hi v[174:175], v49, off offset:64
	v_lshl_add_u64 v[48:49], v[64:65], 0, v[138:139]
	v_add_co_u32_e32 v50, vcc, s8, v48
	v_cvt_pk_bf16_f32 v52, v52, v53
	s_nop 0
	v_addc_co_u32_e32 v51, vcc, 0, v49, vcc
	global_store_short_d16_hi v[50:51], v52, off
	v_add_co_u32_e32 v50, vcc, s9, v48
	global_store_short v[48:49], v52, off
	s_nop 0
	v_addc_co_u32_e32 v51, vcc, 0, v49, vcc
	v_add_co_u32_e32 v48, vcc, s22, v48
	v_cvt_pk_bf16_f32 v53, v54, v55
	s_nop 0
	v_addc_co_u32_e32 v49, vcc, 0, v49, vcc
	global_store_short_d16_hi v[48:49], v53, off
	v_lshl_add_u64 v[48:49], v[64:65], 0, v[140:141]
	global_store_short v[50:51], v53, off
	v_add_co_u32_e32 v50, vcc, s8, v48
	v_cvt_pk_bf16_f32 v52, v56, v57
	s_nop 0
	v_addc_co_u32_e32 v51, vcc, 0, v49, vcc
	global_store_short_d16_hi v[50:51], v52, off
	v_add_co_u32_e32 v50, vcc, s9, v48
	global_store_short v[48:49], v52, off
	s_nop 0
	v_addc_co_u32_e32 v51, vcc, 0, v49, vcc
	v_add_co_u32_e32 v48, vcc, s22, v48
	v_cvt_pk_bf16_f32 v53, v58, v59
	s_nop 0
	v_addc_co_u32_e32 v49, vcc, 0, v49, vcc
	global_store_short_d16_hi v[48:49], v53, off
	v_lshl_add_u64 v[48:49], v[64:65], 0, v[142:143]
	global_store_short v[50:51], v53, off
	v_add_co_u32_e32 v50, vcc, s8, v48
	v_cvt_pk_bf16_f32 v52, v60, v61
	s_nop 0
	v_addc_co_u32_e32 v51, vcc, 0, v49, vcc
	global_store_short_d16_hi v[50:51], v52, off
; DI unsigned pack2(float a, float b) { f32x2_t v = {a, b}; return __builtin_bit_cast(unsigned, __builtin_convertvector(v, bf16x2_t)); }
;     ...
;             for (int g = 0; g < 4; ++g) {
;               const int n = nt * 256 + wn * 128 + ni * 32 + 8 * g + 4 * hh;
;               const float a0 = acc[mi][ni][4 * g], a1 = acc[mi][ni][4 * g + 1], a2 = acc[mi][ni][4 * g + 2], a3 = acc[mi][ni][4 * g + 3];
;               if (MODE == 0) {
;                 uint2 pk; pk.x = pack2(a0, a1); pk.y = pack2(a2, a3);
;                 if (outp != nullptr && nt >= 32) *(uint2*)(outp + m * 2048 + (n - 8192)) = pk;
;                 else if (n < nvalid) *(uint2*)(C + m * ldc + n) = pk;
;               } else if (MODE == 2) {
;                 const unsigned p01 = pack2(a0, a1), p23 = pack2(a2, a3);
;                 bf16_t* dst = ((nt < 8) ? C : outp) + ((size_t)(n & 2047) * 8 + (m >> 12)) * SEQ + (m & 4095);
;                 dst[0] = (bf16_t)(p01 & 0xffffu); dst[(size_t)8 * SEQ] = (bf16_t)(p01 >> 16);
;                 dst[(size_t)16 * SEQ] = (bf16_t)(p23 & 0xffffu); dst[(size_t)24 * SEQ] = (bf16_t)(p23 >> 16);
	v_add_co_u32_e32 v50, vcc, s9, v48
	global_store_short v[48:49], v52, off
	s_nop 0
	v_addc_co_u32_e32 v51, vcc, 0, v49, vcc
	v_add_co_u32_e32 v48, vcc, s22, v48
	v_cvt_pk_bf16_f32 v53, v62, v63
	s_nop 0
	v_addc_co_u32_e32 v49, vcc, 0, v49, vcc
	global_store_short v[50:51], v53, off
	global_store_short_d16_hi v[48:49], v53, off
	v_cvt_pk_bf16_f32 v48, v32, v33
	v_lshl_add_u64 v[32:33], v[64:65], 0, v[144:145]
	v_cvt_pk_bf16_f32 v49, v34, v35
	v_add_co_u32_e32 v34, vcc, s8, v32
	global_store_short v[32:33], v48, off
	s_nop 0
	v_addc_co_u32_e32 v35, vcc, 0, v33, vcc
	global_store_short_d16_hi v[34:35], v48, off
	v_add_co_u32_e32 v34, vcc, s9, v32
	v_cvt_pk_bf16_f32 v36, v36, v37
	s_nop 0
	v_addc_co_u32_e32 v35, vcc, 0, v33, vcc
	v_add_co_u32_e32 v32, vcc, s22, v32
	global_store_short v[34:35], v49, off
	s_nop 0
	v_addc_co_u32_e32 v33, vcc, 0, v33, vcc
	global_store_short_d16_hi v[32:33], v49, off
	v_lshl_add_u64 v[32:33], v[64:65], 0, v[146:147]
	v_add_co_u32_e32 v34, vcc, s8, v32
	global_store_short v[32:33], v36, off
	s_nop 0
	v_addc_co_u32_e32 v35, vcc, 0, v33, vcc
	global_store_short_d16_hi v[34:35], v36, off
	v_add_co_u32_e32 v34, vcc, s9, v32
	v_cvt_pk_bf16_f32 v37, v38, v39
	s_nop 0
	v_addc_co_u32_e32 v35, vcc, 0, v33, vcc
	v_add_co_u32_e32 v32, vcc, s22, v32
	global_store_short v[34:35], v37, off
	s_nop 0
	v_addc_co_u32_e32 v33, vcc, 0, v33, vcc
	global_store_short_d16_hi v[32:33], v37, off
	v_lshl_add_u64 v[32:33], v[64:65], 0, v[148:149]
	v_add_co_u32_e32 v34, vcc, s8, v32
	v_cvt_pk_bf16_f32 v36, v40, v41
	s_nop 0
	v_addc_co_u32_e32 v35, vcc, 0, v33, vcc
	global_store_short_d16_hi v[34:35], v36, off
	v_add_co_u32_e32 v34, vcc, s9, v32
	global_store_short v[32:33], v36, off
	s_nop 0
	v_addc_co_u32_e32 v35, vcc, 0, v33, vcc
	v_add_co_u32_e32 v32, vcc, s22, v32
	v_cvt_pk_bf16_f32 v37, v42, v43
	s_nop 0
	v_addc_co_u32_e32 v33, vcc, 0, v33, vcc
	global_store_short_d16_hi v[32:33], v37, off
	v_lshl_add_u64 v[32:33], v[64:65], 0, v[150:151]
	global_store_short v[34:35], v37, off
	v_add_co_u32_e32 v34, vcc, s8, v32
	v_cvt_pk_bf16_f32 v36, v44, v45
	s_nop 0
	v_addc_co_u32_e32 v35, vcc, 0, v33, vcc
	global_store_short_d16_hi v[34:35], v36, off
	v_add_co_u32_e32 v34, vcc, s9, v32
	global_store_short v[32:33], v36, off
	s_nop 0
	v_addc_co_u32_e32 v35, vcc, 0, v33, vcc
	v_add_co_u32_e32 v32, vcc, s22, v32
	v_cvt_pk_bf16_f32 v37, v46, v47
	s_nop 0
	v_addc_co_u32_e32 v33, vcc, 0, v33, vcc
	global_store_short v[34:35], v37, off
	global_store_short_d16_hi v[32:33], v37, off
	v_cvt_pk_bf16_f32 v32, v16, v17
	v_lshl_add_u64 v[16:17], v[64:65], 0, v[152:153]
	v_cvt_pk_bf16_f32 v33, v18, v19
	v_add_co_u32_e32 v18, vcc, s8, v16
	global_store_short v[16:17], v32, off
	s_nop 0
	v_addc_co_u32_e32 v19, vcc, 0, v17, vcc
	global_store_short_d16_hi v[18:19], v32, off
	v_add_co_u32_e32 v18, vcc, s9, v16
	v_cvt_pk_bf16_f32 v20, v20, v21
	s_nop 0
	v_addc_co_u32_e32 v19, vcc, 0, v17, vcc
	v_add_co_u32_e32 v16, vcc, s22, v16
	global_store_short v[18:19], v33, off
	s_nop 0
	v_addc_co_u32_e32 v17, vcc, 0, v17, vcc
	global_store_short_d16_hi v[16:17], v33, off
	v_lshl_add_u64 v[16:17], v[64:65], 0, v[154:155]
	v_add_co_u32_e32 v18, vcc, s8, v16
	global_store_short v[16:17], v20, off
	s_nop 0
	v_addc_co_u32_e32 v19, vcc, 0, v17, vcc
	global_store_short_d16_hi v[18:19], v20, off
	v_add_co_u32_e32 v18, vcc, s9, v16
	v_cvt_pk_bf16_f32 v21, v22, v23
	s_nop 0
	v_addc_co_u32_e32 v19, vcc, 0, v17, vcc
	v_add_co_u32_e32 v16, vcc, s22, v16
	global_store_short v[18:19], v21, off
	s_nop 0
	v_addc_co_u32_e32 v17, vcc, 0, v17, vcc
	global_store_short_d16_hi v[16:17], v21, off
	v_lshl_add_u64 v[16:17], v[64:65], 0, v[156:157]
	v_add_co_u32_e32 v18, vcc, s8, v16
	v_cvt_pk_bf16_f32 v20, v24, v25
	s_nop 0
	v_addc_co_u32_e32 v19, vcc, 0, v17, vcc
	global_store_short_d16_hi v[18:19], v20, off
	v_add_co_u32_e32 v18, vcc, s9, v16
	global_store_short v[16:17], v20, off
	s_nop 0
	v_addc_co_u32_e32 v19, vcc, 0, v17, vcc
	v_add_co_u32_e32 v16, vcc, s22, v16
	v_cvt_pk_bf16_f32 v21, v26, v27
	s_nop 0
	v_addc_co_u32_e32 v17, vcc, 0, v17, vcc
	global_store_short_d16_hi v[16:17], v21, off
	v_lshl_add_u64 v[16:17], v[64:65], 0, v[158:159]
	global_store_short v[18:19], v21, off
	v_add_co_u32_e32 v18, vcc, s8, v16
	v_cvt_pk_bf16_f32 v20, v28, v29
	s_nop 0
	v_addc_co_u32_e32 v19, vcc, 0, v17, vcc
	global_store_short_d16_hi v[18:19], v20, off
	v_add_co_u32_e32 v18, vcc, s9, v16
	global_store_short v[16:17], v20, off
	s_nop 0
	v_addc_co_u32_e32 v19, vcc, 0, v17, vcc
	v_add_co_u32_e32 v16, vcc, s22, v16
	v_cvt_pk_bf16_f32 v21, v30, v31
	s_nop 0
	v_addc_co_u32_e32 v17, vcc, 0, v17, vcc
	global_store_short v[18:19], v21, off
	global_store_short_d16_hi v[16:17], v21, off
	v_cvt_pk_bf16_f32 v16, v0, v1
	v_lshl_add_u64 v[0:1], v[64:65], 0, v[160:161]
	v_cvt_pk_bf16_f32 v17, v2, v3
	v_add_co_u32_e32 v2, vcc, s8, v0
	global_store_short v[0:1], v16, off
	s_nop 0
; DI unsigned pack2(float a, float b) { f32x2_t v = {a, b}; return __builtin_bit_cast(unsigned, __builtin_convertvector(v, bf16x2_t)); }
; DI f32x16 zero16() { f32x16 z; for (int i = 0; i < 16; ++i) z[i] = 0.f; return z; }
;     ...
;             for (int g = 0; g < 4; ++g) {
;               const int n = nt * 256 + wn * 128 + ni * 32 + 8 * g + 4 * hh;
;               const float a0 = acc[mi][ni][4 * g], a1 = acc[mi][ni][4 * g + 1], a2 = acc[mi][ni][4 * g + 2], a3 = acc[mi][ni][4 * g + 3];
;               if (MODE == 0) {
;                 uint2 pk; pk.x = pack2(a0, a1); pk.y = pack2(a2, a3);
;                 if (outp != nullptr && nt >= 32) *(uint2*)(outp + m * 2048 + (n - 8192)) = pk;
;                 else if (n < nvalid) *(uint2*)(C + m * ldc + n) = pk;
;               } else if (MODE == 2) {
;                 const unsigned p01 = pack2(a0, a1), p23 = pack2(a2, a3);
;                 bf16_t* dst = ((nt < 8) ? C : outp) + ((size_t)(n & 2047) * 8 + (m >> 12)) * SEQ + (m & 4095);
;                 dst[0] = (bf16_t)(p01 & 0xffffu); dst[(size_t)8 * SEQ] = (bf16_t)(p01 >> 16);
;                 dst[(size_t)16 * SEQ] = (bf16_t)(p23 & 0xffffu); dst[(size_t)24 * SEQ] = (bf16_t)(p23 >> 16);
;     ...
; #pragma unroll
;       for (int i = 0; i < 2; ++i)
; #pragma unroll
;         for (int j = 0; j < 4; ++j) acc[i][j] = zero16();
	v_addc_co_u32_e32 v3, vcc, 0, v1, vcc
	global_store_short_d16_hi v[2:3], v16, off
	v_add_co_u32_e32 v2, vcc, s9, v0
	v_cvt_pk_bf16_f32 v4, v4, v5
	s_nop 0
	v_addc_co_u32_e32 v3, vcc, 0, v1, vcc
	v_add_co_u32_e32 v0, vcc, s22, v0
	global_store_short v[2:3], v17, off
	s_nop 0
	v_addc_co_u32_e32 v1, vcc, 0, v1, vcc
	global_store_short_d16_hi v[0:1], v17, off
	v_lshl_add_u64 v[0:1], v[64:65], 0, v[162:163]
	v_add_co_u32_e32 v2, vcc, s8, v0
	global_store_short v[0:1], v4, off
	s_nop 0
	v_addc_co_u32_e32 v3, vcc, 0, v1, vcc
	global_store_short_d16_hi v[2:3], v4, off
	v_add_co_u32_e32 v2, vcc, s9, v0
	v_cvt_pk_bf16_f32 v5, v6, v7
	s_nop 0
	v_addc_co_u32_e32 v3, vcc, 0, v1, vcc
	v_add_co_u32_e32 v0, vcc, s22, v0
	global_store_short v[2:3], v5, off
	s_nop 0
	v_addc_co_u32_e32 v1, vcc, 0, v1, vcc
	global_store_short_d16_hi v[0:1], v5, off
	v_lshl_add_u64 v[0:1], v[64:65], 0, v[164:165]
	v_add_co_u32_e32 v2, vcc, s8, v0
	v_cvt_pk_bf16_f32 v4, v8, v9
	s_nop 0
	v_addc_co_u32_e32 v3, vcc, 0, v1, vcc
	global_store_short_d16_hi v[2:3], v4, off
	v_add_co_u32_e32 v2, vcc, s9, v0
	global_store_short v[0:1], v4, off
	s_nop 0
	v_addc_co_u32_e32 v3, vcc, 0, v1, vcc
	v_add_co_u32_e32 v0, vcc, 0x30000, v0
	v_cvt_pk_bf16_f32 v5, v10, v11
	s_nop 0
	v_addc_co_u32_e32 v1, vcc, 0, v1, vcc
	global_store_short_d16_hi v[0:1], v5, off
	v_lshl_add_u64 v[0:1], v[64:65], 0, v[166:167]
	global_store_short v[2:3], v5, off
	v_add_co_u32_e32 v2, vcc, 0x10000, v0
	v_cvt_pk_bf16_f32 v4, v12, v13
	s_nop 0
	v_addc_co_u32_e32 v3, vcc, 0, v1, vcc
	global_store_short_d16_hi v[2:3], v4, off
	v_add_co_u32_e32 v2, vcc, 0x20000, v0
	global_store_short v[0:1], v4, off
	s_nop 0
	v_addc_co_u32_e32 v3, vcc, 0, v1, vcc
	v_add_co_u32_e32 v0, vcc, 0x30000, v0
	v_cvt_pk_bf16_f32 v5, v14, v15
	s_nop 0
	v_addc_co_u32_e32 v1, vcc, 0, v1, vcc
	global_store_short_d16_hi v[0:1], v5, off
	v_mov_b32_e32 v0, 0
	global_store_short v[2:3], v5, off
	v_mov_b32_e32 v1, v0
	v_mov_b32_e32 v2, v0
	v_mov_b32_e32 v3, v0
	v_mov_b32_e32 v4, v0
	v_mov_b32_e32 v5, v0
	v_mov_b32_e32 v6, v0
	v_mov_b32_e32 v7, v0
	v_mov_b32_e32 v8, v0
	v_mov_b32_e32 v9, v0
	v_mov_b32_e32 v10, v0
	v_mov_b32_e32 v11, v0
	v_mov_b32_e32 v12, v0
	v_mov_b32_e32 v13, v0
	v_mov_b32_e32 v14, v0
	v_mov_b32_e32 v15, v0
	v_mov_b32_e32 v16, v0
	v_mov_b32_e32 v17, v0
	v_mov_b32_e32 v18, v0
	v_mov_b32_e32 v19, v0
	v_mov_b32_e32 v20, v0
	v_mov_b32_e32 v21, v0
	v_mov_b32_e32 v22, v0
	v_mov_b32_e32 v23, v0
	v_mov_b32_e32 v24, v0
	v_mov_b32_e32 v25, v0
	v_mov_b32_e32 v26, v0
	v_mov_b32_e32 v27, v0
	v_mov_b32_e32 v28, v0
	v_mov_b32_e32 v29, v0
	v_mov_b32_e32 v30, v0
	v_mov_b32_e32 v31, v0
	v_mov_b32_e32 v32, v0
	v_mov_b32_e32 v33, v0
	v_mov_b32_e32 v34, v0
	v_mov_b32_e32 v35, v0
	v_mov_b32_e32 v36, v0
	v_mov_b32_e32 v37, v0
	v_mov_b32_e32 v38, v0
	v_mov_b32_e32 v39, v0
	v_mov_b32_e32 v40, v0
	v_mov_b32_e32 v41, v0
	v_mov_b32_e32 v42, v0
	v_mov_b32_e32 v43, v0
	v_mov_b32_e32 v44, v0
	v_mov_b32_e32 v45, v0
	v_mov_b32_e32 v46, v0
	v_mov_b32_e32 v47, v0
	v_mov_b32_e32 v48, v0
	v_mov_b32_e32 v49, v0
	v_mov_b32_e32 v50, v0
	v_mov_b32_e32 v51, v0
	v_mov_b32_e32 v52, v0
	v_mov_b32_e32 v53, v0
	v_mov_b32_e32 v54, v0
	v_mov_b32_e32 v55, v0
	v_mov_b32_e32 v56, v0
	v_mov_b32_e32 v57, v0
	v_mov_b32_e32 v58, v0
	v_mov_b32_e32 v59, v0
	v_mov_b32_e32 v60, v0
	v_mov_b32_e32 v61, v0
	v_mov_b32_e32 v62, v0
	v_mov_b32_e32 v63, v0
	v_mov_b32_e32 v64, v0
	v_mov_b32_e32 v65, v0
	v_mov_b32_e32 v66, v0
	v_mov_b32_e32 v67, v0
	v_mov_b32_e32 v68, v0
	v_mov_b32_e32 v69, v0
	v_mov_b32_e32 v70, v0
	v_mov_b32_e32 v71, v0
	v_mov_b32_e32 v72, v0
	v_mov_b32_e32 v73, v0
	v_mov_b32_e32 v74, v0
	v_mov_b32_e32 v75, v0
	v_mov_b32_e32 v76, v0
	v_mov_b32_e32 v77, v0
	v_mov_b32_e32 v78, v0
	v_mov_b32_e32 v79, v0
	v_mov_b32_e32 v80, v0
	v_mov_b32_e32 v81, v0
	v_mov_b32_e32 v82, v0
	v_mov_b32_e32 v83, v0
	v_mov_b32_e32 v84, v0
	v_mov_b32_e32 v85, v0
	v_mov_b32_e32 v86, v0
	v_mov_b32_e32 v87, v0
	v_mov_b32_e32 v88, v0
	v_mov_b32_e32 v89, v0
	v_mov_b32_e32 v90, v0
	v_mov_b32_e32 v91, v0
	v_mov_b32_e32 v92, v0
	v_mov_b32_e32 v93, v0
	v_mov_b32_e32 v94, v0
	v_mov_b32_e32 v95, v0
	v_mov_b32_e32 v96, v0
	v_mov_b32_e32 v97, v0
	v_mov_b32_e32 v98, v0
	v_mov_b32_e32 v99, v0
	v_mov_b32_e32 v100, v0
	v_mov_b32_e32 v101, v0
	v_mov_b32_e32 v102, v0
	v_mov_b32_e32 v103, v0
	v_mov_b32_e32 v104, v0
	v_mov_b32_e32 v105, v0
	v_mov_b32_e32 v106, v0
	v_mov_b32_e32 v107, v0
	v_mov_b32_e32 v108, v0
	v_mov_b32_e32 v109, v0
	v_mov_b32_e32 v110, v0
	v_mov_b32_e32 v111, v0
	v_mov_b32_e32 v112, v0
	v_mov_b32_e32 v113, v0
	v_mov_b32_e32 v114, v0
	v_mov_b32_e32 v115, v0
	v_mov_b32_e32 v116, v0
	v_mov_b32_e32 v117, v0
	v_mov_b32_e32 v118, v0
	v_mov_b32_e32 v119, v0
	v_mov_b32_e32 v120, v0
	v_mov_b32_e32 v121, v0
	v_mov_b32_e32 v122, v0
	v_mov_b32_e32 v123, v0
	v_mov_b32_e32 v124, v0
	v_mov_b32_e32 v125, v0
	v_mov_b32_e32 v126, v0
	v_mov_b32_e32 v127, v0
	s_branch .LBB0_1107

; #define MFMA(a, b, c) __builtin_amdgcn_mfma_f32_32x32x16_bf16((a), (b), (c), 0, 0, 0)
;     ...
;   for (int s = 0; s < S; ++s) {
;     G_DMA(s + 1, cur ^ BUFB);
;     {
;       const char* Ab = smem + cur + fA;
;       const char* Bb = smem + cur + fB;
;       __builtin_amdgcn_sched_barrier(0);
; #pragma unroll
;       for (int kk = 0; kk < 4; ++kk) {
;         const int ko = (((kk * 2 + hh) ^ fsw) << 4);
;         bf16x8 af[2], wf[4];
;         af[0] = *(const bf16x8*)(Ab + ko); af[1] = *(const bf16x8*)(Ab + 4096 + ko);
; #pragma unroll
;         for (int ni = 0; ni < 4; ++ni) wf[ni] = *(const bf16x8*)(Bb + ni * 4096 + ko);
; #pragma unroll
;         for (int mi = 0; mi < 2; ++mi)
; #pragma unroll
;           for (int ni = 0; ni < 4; ++ni) acc[mi][ni] = MFMA(wf[ni], af[mi], acc[mi][ni]);
;         if (kk == 1) __builtin_amdgcn_sched_barrier(0);
;       }
;       __builtin_amdgcn_sched_barrier(0);
;     }
;     asm volatile("s_waitcnt vmcnt(0)" ::: "memory");
.LBB0_1286:
	s_lshl_b32 s9, s7, 16
	s_and_b32 s9, s9, 0x200000
	s_add_i32 s9, s93, s9
	s_lshl_b32 s9, s9, 1
	s_and_b32 s28, s9, 0x700000
	s_xor_b32 s9, s8, 0x10000
	v_add_u32_e32 v128, s9, v150
	v_lshl_add_u64 v[160:161], v[136:137], 0, s[40:41]
	v_readfirstlane_b32 s22, v128
	v_add_u32_e32 v164, 0x2000, v128
	v_lshl_add_u64 v[162:163], v[160:161], 0, s[24:25]
	s_mov_b32 m0, s22
	v_readfirstlane_b32 s22, v164
	v_add_u32_e32 v164, 0x4000, v128
	global_load_lds_dwordx4 v[162:163], off
	v_add3_u32 v187, s8, v144, v147
	v_add3_u32 v208, s8, v149, v147
	v_add_u32_e32 v182, v208, v148
	v_add_u32_e32 v183, v187, v148
	ds_read_b128 v[192:195], v182 offset:32768
	ds_read_b128 v[216:219], v183
	ds_read_b128 v[196:199], v182 offset:36864
	ds_read_b128 v[200:203], v182 offset:40960
	ds_read_b128 v[204:207], v182 offset:45056
	ds_read_b128 v[220:223], v183 offset:4096
	v_add_u32_e32 v184, v208, v145
	v_add_u32_e32 v185, v187, v145
	ds_read_b128 v[224:227], v184 offset:32768
	ds_read_b128 v[240:243], v185
	ds_read_b128 v[228:231], v184 offset:36864
	ds_read_b128 v[232:235], v184 offset:40960
	ds_read_b128 v[236:239], v184 offset:45056
	ds_read_b128 v[244:247], v185 offset:4096
	s_waitcnt lgkmcnt(10)
	v_mfma_f32_32x32x16_bf16 v[112:127], v[192:195], v[216:219], v[112:127]
	s_waitcnt lgkmcnt(9)
	v_mfma_f32_32x32x16_bf16 v[96:111], v[196:199], v[216:219], v[96:111]
	v_lshl_add_u64 v[162:163], v[160:161], 0, s[42:43]
	s_mov_b32 m0, s22
	v_readfirstlane_b32 s22, v164
	global_load_lds_dwordx4 v[162:163], off
	s_waitcnt lgkmcnt(8)
	v_mfma_f32_32x32x16_bf16 v[80:95], v[200:203], v[216:219], v[80:95]
	s_waitcnt lgkmcnt(7)
	v_mfma_f32_32x32x16_bf16 v[64:79], v[204:207], v[216:219], v[64:79]
	v_lshl_add_u64 v[162:163], v[160:161], 0, s[44:45]
	s_mov_b32 m0, s22
	v_lshl_add_u64 v[158:159], v[138:139], 0, s[28:29]
	global_load_lds_dwordx4 v[162:163], off
	s_waitcnt lgkmcnt(6)
	v_mfma_f32_32x32x16_bf16 v[48:63], v[192:195], v[220:223], v[48:63]
	v_mfma_f32_32x32x16_bf16 v[32:47], v[196:199], v[220:223], v[32:47]
	v_add_u32_e32 v162, 0x6000, v128
	v_lshl_add_u64 v[160:161], v[160:161], 0, s[46:47]
	v_readfirstlane_b32 s22, v162
	v_add_u32_e32 v162, 0x8000, v128
	s_mov_b32 m0, s22
	v_lshl_add_u64 v[158:159], v[158:159], 0, s[40:41]
	v_readfirstlane_b32 s22, v162
	v_add_u32_e32 v162, 0xa000, v128
	global_load_lds_dwordx4 v[160:161], off
	v_mfma_f32_32x32x16_bf16 v[16:31], v[200:203], v[220:223], v[16:31]
	v_mfma_f32_32x32x16_bf16 v[0:15], v[204:207], v[220:223], v[0:15]
	v_lshl_add_u64 v[160:161], v[158:159], 0, s[48:49]
	s_mov_b32 m0, s22
	v_readfirstlane_b32 s22, v162
	v_add_u32_e32 v162, 0xc000, v128
	global_load_lds_dwordx4 v[160:161], off
	v_add_u32_e32 v182, v208, v141
	v_add_u32_e32 v183, v187, v141
	ds_read_b128 v[192:195], v182 offset:32768
	ds_read_b128 v[216:219], v183
	ds_read_b128 v[196:199], v182 offset:36864
	ds_read_b128 v[200:203], v182 offset:40960
	ds_read_b128 v[204:207], v182 offset:45056
	ds_read_b128 v[220:223], v183 offset:4096
	s_waitcnt lgkmcnt(10)
	v_mfma_f32_32x32x16_bf16 v[112:127], v[224:227], v[240:243], v[112:127]
	s_waitcnt lgkmcnt(9)
	v_mfma_f32_32x32x16_bf16 v[96:111], v[228:231], v[240:243], v[96:111]
	v_lshl_add_u64 v[160:161], v[158:159], 0, s[50:51]
	s_mov_b32 m0, s22
	v_readfirstlane_b32 s22, v162
	v_add_u32_e32 v128, 0xe000, v128
	global_load_lds_dwordx4 v[160:161], off
	s_waitcnt lgkmcnt(8)
	v_mfma_f32_32x32x16_bf16 v[80:95], v[232:235], v[240:243], v[80:95]
	s_waitcnt lgkmcnt(7)
	v_mfma_f32_32x32x16_bf16 v[64:79], v[236:239], v[240:243], v[64:79]
	v_lshl_add_u64 v[160:161], v[158:159], 0, s[52:53]
	s_mov_b32 m0, s22
	v_readfirstlane_b32 s22, v128
	global_load_lds_dwordx4 v[160:161], off
	s_waitcnt lgkmcnt(6)
	v_mfma_f32_32x32x16_bf16 v[48:63], v[224:227], v[244:247], v[48:63]
	v_mfma_f32_32x32x16_bf16 v[32:47], v[228:231], v[244:247], v[32:47]
	v_lshl_add_u64 v[158:159], v[158:159], 0, s[56:57]
	s_mov_b32 m0, s22
	s_add_i32 s8, s8, 0
	global_load_lds_dwordx4 v[158:159], off
	v_mfma_f32_32x32x16_bf16 v[16:31], v[232:235], v[244:247], v[16:31]
	v_mfma_f32_32x32x16_bf16 v[0:15], v[236:239], v[244:247], v[0:15]
	v_add_u32_e32 v184, v208, v140
	v_add_u32_e32 v185, v187, v140
	ds_read_b128 v[224:227], v184 offset:32768
	ds_read_b128 v[240:243], v185
	ds_read_b128 v[228:231], v184 offset:36864
	ds_read_b128 v[232:235], v184 offset:40960
	ds_read_b128 v[236:239], v184 offset:45056
	ds_read_b128 v[244:247], v185 offset:4096
	s_waitcnt lgkmcnt(10)
	v_mfma_f32_32x32x16_bf16 v[112:127], v[192:195], v[216:219], v[112:127]
	s_waitcnt lgkmcnt(9)
	v_mfma_f32_32x32x16_bf16 v[96:111], v[196:199], v[216:219], v[96:111]
	s_waitcnt lgkmcnt(8)
	v_mfma_f32_32x32x16_bf16 v[80:95], v[200:203], v[216:219], v[80:95]
	s_waitcnt lgkmcnt(7)
	v_mfma_f32_32x32x16_bf16 v[64:79], v[204:207], v[216:219], v[64:79]
	s_waitcnt lgkmcnt(6)
	v_mfma_f32_32x32x16_bf16 v[48:63], v[192:195], v[220:223], v[48:63]
	v_mfma_f32_32x32x16_bf16 v[32:47], v[196:199], v[220:223], v[32:47]
	v_mfma_f32_32x32x16_bf16 v[16:31], v[200:203], v[220:223], v[16:31]
	v_mfma_f32_32x32x16_bf16 v[0:15], v[204:207], v[220:223], v[0:15]
	s_waitcnt lgkmcnt(4)
	v_mfma_f32_32x32x16_bf16 v[112:127], v[224:227], v[240:243], v[112:127]
	s_waitcnt lgkmcnt(3)
	v_mfma_f32_32x32x16_bf16 v[96:111], v[228:231], v[240:243], v[96:111]
	s_waitcnt lgkmcnt(2)
	v_mfma_f32_32x32x16_bf16 v[80:95], v[232:235], v[240:243], v[80:95]
	s_waitcnt lgkmcnt(1)
	v_mfma_f32_32x32x16_bf16 v[64:79], v[236:239], v[240:243], v[64:79]
	s_waitcnt lgkmcnt(0)
	v_mfma_f32_32x32x16_bf16 v[48:63], v[224:227], v[244:247], v[48:63]
	v_mfma_f32_32x32x16_bf16 v[32:47], v[228:231], v[244:247], v[32:47]
	v_mfma_f32_32x32x16_bf16 v[16:31], v[232:235], v[244:247], v[16:31]
	v_mfma_f32_32x32x16_bf16 v[0:15], v[236:239], v[244:247], v[0:15]
	s_waitcnt vmcnt(0)
	s_waitcnt lgkmcnt(0)
	s_barrier
; #define MFMA(a, b, c) __builtin_amdgcn_mfma_f32_32x32x16_bf16((a), (b), (c), 0, 0, 0)
;     ...
;   for (int s = 0; s < S; ++s) {
;     G_DMA(s + 1, cur ^ BUFB);
;     {
;       const char* Ab = smem + cur + fA;
;       const char* Bb = smem + cur + fB;
;       __builtin_amdgcn_sched_barrier(0);
; #pragma unroll
;       for (int kk = 0; kk < 4; ++kk) {
;         const int ko = (((kk * 2 + hh) ^ fsw) << 4);
;         bf16x8 af[2], wf[4];
;         af[0] = *(const bf16x8*)(Ab + ko); af[1] = *(const bf16x8*)(Ab + 4096 + ko);
; #pragma unroll
;         for (int ni = 0; ni < 4; ++ni) wf[ni] = *(const bf16x8*)(Bb + ni * 4096 + ko);
; #pragma unroll
;         for (int mi = 0; mi < 2; ++mi)
; #pragma unroll
;           for (int ni = 0; ni < 4; ++ni) acc[mi][ni] = MFMA(wf[ni], af[mi], acc[mi][ni]);
;         if (kk == 1) __builtin_amdgcn_sched_barrier(0);
;       }
;       __builtin_amdgcn_sched_barrier(0);
;     }
;     asm volatile("s_waitcnt vmcnt(0)" ::: "memory");
	s_add_u32 s40, s40, 0x80
	s_addc_u32 s41, s41, 0
	s_add_i32 s7, s7, 1
	s_cmpk_eq_i32 s40, 0xf80
	s_mov_b32 s8, s9
	s_cbranch_scc0 .LBB0_1286
	s_mov_b64 s[8:9], 0xf80
	v_readfirstlane_b32 s7, v150
	v_lshl_add_u64 v[136:137], v[132:133], 0, s[8:9]
	s_mov_b32 m0, s7
	s_mov_b64 s[22:23], 0x40f80
	v_readfirstlane_b32 s7, v151
	global_load_lds_dwordx4 v[136:137], off
	v_lshl_add_u64 v[136:137], v[132:133], 0, s[22:23]
	s_mov_b32 m0, s7
	s_mov_b64 s[24:25], 0x80f80
	v_readfirstlane_b32 s7, v152
	global_load_lds_dwordx4 v[136:137], off
	v_lshl_add_u64 v[136:137], v[132:133], 0, s[24:25]
	s_mov_b32 m0, s7
	s_mov_b64 s[40:41], 0xc0f80
	v_readfirstlane_b32 s7, v153
	global_load_lds_dwordx4 v[136:137], off
	v_lshl_add_u64 v[132:133], v[132:133], 0, s[40:41]
	s_mov_b32 m0, s7
	v_readfirstlane_b32 s7, v154
	global_load_lds_dwordx4 v[132:133], off
	v_lshl_add_u64 v[132:133], v[134:135], 0, s[8:9]
	s_mov_b32 m0, s7
	v_readfirstlane_b32 s7, v155
	global_load_lds_dwordx4 v[132:133], off
	v_lshl_add_u64 v[132:133], v[134:135], 0, s[22:23]
	s_mov_b32 m0, s7
	v_readfirstlane_b32 s7, v156
	global_load_lds_dwordx4 v[132:133], off
	v_lshl_add_u64 v[132:133], v[134:135], 0, s[24:25]
	s_mov_b32 m0, s7
	v_readfirstlane_b32 s7, v157
	global_load_lds_dwordx4 v[132:133], off
	v_lshl_add_u64 v[132:133], v[134:135], 0, s[40:41]
	s_mov_b32 m0, s7
	s_add_i32 s28, s6, -1
	global_load_lds_dwordx4 v[132:133], off
	s_lshl_b64 s[8:9], s[28:29], 25
	v_readlane_b32 s22, v253, 39
	v_readlane_b32 s23, v253, 40
	s_add_u32 s40, s22, s8
	v_lshlrev_b32_e32 v132, 6, v146
	s_addc_u32 s41, s23, s9
	v_readlane_b32 s8, v253, 27
	v_ashrrev_i32_e32 v133, 31, v132
	v_readlane_b32 s9, v253, 28
	s_add_i32 s7, 0, 0x10000
	v_lshlrev_b32_e32 v128, 3, v142
	v_lshl_add_u64 v[162:163], v[132:133], 0, s[8:9]
	v_lshlrev_b32_e32 v132, 4, v142
	v_mov_b32_e32 v133, v129
	v_or_b32_e32 v162, v162, v143
	v_lshl_add_u64 v[132:133], s[40:41], 0, v[132:133]
	v_add3_u32 v138, s7, v144, v147
	v_add3_u32 v139, s7, v149, v147
	v_add_u32_e32 v182, v139, v148
	v_add_u32_e32 v183, v138, v148
	ds_read_b128 v[134:137], v182 offset:32768
	ds_read_b128 v[146:149], v183
	ds_read_b128 v[150:153], v182 offset:36864
	ds_read_b128 v[154:157], v182 offset:40960
	ds_read_b128 v[158:161], v182 offset:45056
	ds_read_b128 v[192:195], v183 offset:4096
	v_add_u32_e32 v184, v139, v145
	v_add_u32_e32 v185, v138, v145
	ds_read_b128 v[196:199], v184 offset:32768
	ds_read_b128 v[220:223], v185
	ds_read_b128 v[200:203], v184 offset:36864
	ds_read_b128 v[204:207], v184 offset:40960
	ds_read_b128 v[216:219], v184 offset:45056
	ds_read_b128 v[224:227], v185 offset:4096
	s_waitcnt lgkmcnt(10)
	v_mfma_f32_32x32x16_bf16 v[112:127], v[134:137], v[146:149], v[112:127]
	s_waitcnt lgkmcnt(9)
	v_mfma_f32_32x32x16_bf16 v[96:111], v[150:153], v[146:149], v[96:111]
	s_waitcnt lgkmcnt(8)
	v_mfma_f32_32x32x16_bf16 v[80:95], v[154:157], v[146:149], v[80:95]
	s_waitcnt lgkmcnt(7)
	v_mfma_f32_32x32x16_bf16 v[64:79], v[158:161], v[146:149], v[64:79]
	s_waitcnt lgkmcnt(6)
	v_mfma_f32_32x32x16_bf16 v[48:63], v[134:137], v[192:195], v[48:63]
	v_mfma_f32_32x32x16_bf16 v[32:47], v[150:153], v[192:195], v[32:47]
	v_mfma_f32_32x32x16_bf16 v[16:31], v[154:157], v[192:195], v[16:31]
	v_mfma_f32_32x32x16_bf16 v[0:15], v[158:161], v[192:195], v[0:15]
	v_add_u32_e32 v182, v139, v141
	v_add_u32_e32 v183, v138, v141
	ds_read_b128 v[134:137], v182 offset:32768
	ds_read_b128 v[146:149], v183
	ds_read_b128 v[150:153], v182 offset:36864
	ds_read_b128 v[154:157], v182 offset:40960
	ds_read_b128 v[158:161], v182 offset:45056
	ds_read_b128 v[192:195], v183 offset:4096
	s_waitcnt lgkmcnt(10)
	v_mfma_f32_32x32x16_bf16 v[112:127], v[196:199], v[220:223], v[112:127]
	s_waitcnt lgkmcnt(9)
	v_mfma_f32_32x32x16_bf16 v[96:111], v[200:203], v[220:223], v[96:111]
	s_waitcnt lgkmcnt(8)
	v_mfma_f32_32x32x16_bf16 v[80:95], v[204:207], v[220:223], v[80:95]
	s_waitcnt lgkmcnt(7)
	v_mfma_f32_32x32x16_bf16 v[64:79], v[216:219], v[220:223], v[64:79]
	s_waitcnt lgkmcnt(6)
	v_mfma_f32_32x32x16_bf16 v[48:63], v[196:199], v[224:227], v[48:63]
	v_mfma_f32_32x32x16_bf16 v[32:47], v[200:203], v[224:227], v[32:47]
	v_mfma_f32_32x32x16_bf16 v[16:31], v[204:207], v[224:227], v[16:31]
	v_mfma_f32_32x32x16_bf16 v[0:15], v[216:219], v[224:227], v[0:15]
	v_add_u32_e32 v184, v139, v140
	v_add_u32_e32 v185, v138, v140
	ds_read_b128 v[196:199], v184 offset:32768
	ds_read_b128 v[220:223], v185
	ds_read_b128 v[200:203], v184 offset:36864
	ds_read_b128 v[204:207], v184 offset:40960
	ds_read_b128 v[216:219], v184 offset:45056
	ds_read_b128 v[224:227], v185 offset:4096
	s_waitcnt lgkmcnt(10)
	v_mfma_f32_32x32x16_bf16 v[112:127], v[134:137], v[146:149], v[112:127]
	s_waitcnt lgkmcnt(9)
	v_mfma_f32_32x32x16_bf16 v[96:111], v[150:153], v[146:149], v[96:111]
	s_waitcnt lgkmcnt(8)
	v_mfma_f32_32x32x16_bf16 v[80:95], v[154:157], v[146:149], v[80:95]
	s_waitcnt lgkmcnt(7)
	v_mfma_f32_32x32x16_bf16 v[64:79], v[158:161], v[146:149], v[64:79]
	s_waitcnt lgkmcnt(6)
	v_mfma_f32_32x32x16_bf16 v[48:63], v[134:137], v[192:195], v[48:63]
	v_mfma_f32_32x32x16_bf16 v[32:47], v[150:153], v[192:195], v[32:47]
	v_mfma_f32_32x32x16_bf16 v[16:31], v[154:157], v[192:195], v[16:31]
	v_mfma_f32_32x32x16_bf16 v[0:15], v[158:161], v[192:195], v[0:15]
	s_waitcnt lgkmcnt(4)
	v_mfma_f32_32x32x16_bf16 v[112:127], v[196:199], v[220:223], v[112:127]
	s_waitcnt lgkmcnt(3)
	v_mfma_f32_32x32x16_bf16 v[96:111], v[200:203], v[220:223], v[96:111]
	s_waitcnt lgkmcnt(2)
	v_mfma_f32_32x32x16_bf16 v[80:95], v[204:207], v[220:223], v[80:95]
	s_waitcnt lgkmcnt(1)
	v_mfma_f32_32x32x16_bf16 v[64:79], v[216:219], v[220:223], v[64:79]
	s_waitcnt lgkmcnt(0)
; DI unsigned pack2(float a, float b) { f32x2_t v = {a, b}; return __builtin_bit_cast(unsigned, __builtin_convertvector(v, bf16x2_t)); }
; DI float lo2f(unsigned v) { return __uint_as_float(v << 16); }
; DI float hi2f(unsigned v) { return __uint_as_float(v & 0xffff0000u); }
;     ...
;             } else if (MODE == 1) {
; #pragma unroll
;               for (int gp = 0; gp < 2; ++gp) {
;                 const int g0 = 2 * gp;
;                 const int nb_ = nt * 256 + wn * 128 + ni * 32 + 8 * g0;
;                 const uint2 ra = *(const uint2*)(res + m * 1024 + nb_ + 4 * hh), rb = *(const uint2*)(res + m * 1024 + nb_ + 8 + 4 * hh);
;                 uint2 pa, pb;
;                 pa.x = pack2(alpha * lo2f(ra.x) + acc[mi][ni][4 * g0], alpha * hi2f(ra.x) + acc[mi][ni][4 * g0 + 1]);
;                 pa.y = pack2(alpha * lo2f(ra.y) + acc[mi][ni][4 * g0 + 2], alpha * hi2f(ra.y) + acc[mi][ni][4 * g0 + 3]);
;                 pb.x = pack2(alpha * lo2f(rb.x) + acc[mi][ni][4 * g0 + 4], alpha * hi2f(rb.x) + acc[mi][ni][4 * g0 + 5]);
;                 pb.y = pack2(alpha * lo2f(rb.y) + acc[mi][ni][4 * g0 + 6], alpha * hi2f(rb.y) + acc[mi][ni][4 * g0 + 7]);
;                 { auto rx = __builtin_amdgcn_permlane32_swap(pa.x, pb.x, false, false); pa.x = rx[0]; pb.x = rx[1]; }
;                 { auto ry = __builtin_amdgcn_permlane32_swap(pa.y, pb.y, false, false); pa.y = ry[0]; pb.y = ry[1]; }
;                 *(uint4*)(outp + m * 1024 + nb_ + 8 * hh) = make_uint4(pa.x, pa.y, pb.x, pb.y);
;               }
	v_mfma_f32_32x32x16_bf16 v[48:63], v[196:199], v[224:227], v[48:63]
	v_mfma_f32_32x32x16_bf16 v[32:47], v[200:203], v[224:227], v[32:47]
	v_mfma_f32_32x32x16_bf16 v[16:31], v[204:207], v[224:227], v[16:31]
	v_mfma_f32_32x32x16_bf16 v[0:15], v[216:219], v[224:227], v[0:15]
	s_waitcnt vmcnt(0)
	v_lshlrev_b64 v[136:137], 11, v[162:163]
	v_lshl_add_u64 v[138:139], s[40:41], 0, v[136:137]
	v_lshl_add_u64 v[144:145], v[132:133], 0, v[136:137]
	v_readlane_b32 s7, v251, 32
	s_lshl_b32 s7, s7, 1
	v_mov_b32_e32 v135, v129
	v_lshl_or_b32 v134, v131, 8, s7
	v_lshl_add_u64 v[138:139], v[138:139], 0, v[134:135]
	v_lshl_add_u64 v[138:139], v[138:139], 0, v[128:129]
	global_load_dwordx2 v[140:141], v[138:139], off
	global_load_dwordx2 v[142:143], v[138:139], off offset:16
	s_mov_b32 s8, 0x3fd744fd
	s_waitcnt vmcnt(0)
	v_lshlrev_b32_e32 v146, 16, v140
	v_and_b32_e32 v147, 0xffff0000, v140
	v_pk_fma_f32 v[112:113], v[146:147], s[8:9], v[112:113] op_sel_hi:[1,0,1]
	s_nop 0
	v_cvt_pk_bf16_f32 v140, v112, v113
	v_lshlrev_b32_e32 v112, 16, v141
	v_and_b32_e32 v113, 0xffff0000, v141
	v_pk_fma_f32 v[112:113], v[112:113], s[8:9], v[114:115] op_sel_hi:[1,0,1]
	s_nop 0
	v_cvt_pk_bf16_f32 v141, v112, v113
	v_lshlrev_b32_e32 v112, 16, v142
	v_and_b32_e32 v113, 0xffff0000, v142
	v_pk_fma_f32 v[112:113], v[112:113], s[8:9], v[116:117] op_sel_hi:[1,0,1]
	s_nop 0
	v_cvt_pk_bf16_f32 v142, v112, v113
	v_lshlrev_b32_e32 v112, 16, v143
	v_and_b32_e32 v113, 0xffff0000, v143
	v_pk_fma_f32 v[112:113], v[112:113], s[8:9], v[118:119] op_sel_hi:[1,0,1]
	v_permlane32_swap_b32_e32 v140, v142
	v_cvt_pk_bf16_f32 v143, v112, v113
	s_nop 1
	v_permlane32_swap_b32_e32 v141, v143
	v_lshl_add_u64 v[112:113], v[144:145], 0, v[134:135]
	global_store_dwordx4 v[112:113], v[140:143], off
	global_load_dwordx2 v[114:115], v[138:139], off offset:32
	global_load_dwordx2 v[116:117], v[138:139], off offset:48
	s_waitcnt vmcnt(1)
	v_lshlrev_b32_e32 v118, 16, v114
	v_and_b32_e32 v119, 0xffff0000, v114
	v_pk_fma_f32 v[118:119], v[118:119], s[8:9], v[120:121] op_sel_hi:[1,0,1]
	s_nop 0
	v_cvt_pk_bf16_f32 v114, v118, v119
	v_lshlrev_b32_e32 v118, 16, v115
	v_and_b32_e32 v119, 0xffff0000, v115
	v_pk_fma_f32 v[118:119], v[118:119], s[8:9], v[122:123] op_sel_hi:[1,0,1]
	s_nop 0
	v_cvt_pk_bf16_f32 v115, v118, v119
	s_waitcnt vmcnt(0)
	v_lshlrev_b32_e32 v118, 16, v116
	v_and_b32_e32 v119, 0xffff0000, v116
	v_pk_fma_f32 v[118:119], v[118:119], s[8:9], v[124:125] op_sel_hi:[1,0,1]
	s_nop 0
	v_cvt_pk_bf16_f32 v116, v118, v119
	v_lshlrev_b32_e32 v118, 16, v117
	v_and_b32_e32 v119, 0xffff0000, v117
	v_pk_fma_f32 v[118:119], v[118:119], s[8:9], v[126:127] op_sel_hi:[1,0,1]
	v_permlane32_swap_b32_e32 v114, v116
	v_cvt_pk_bf16_f32 v117, v118, v119
	s_nop 1
	v_permlane32_swap_b32_e32 v115, v117
	global_store_dwordx4 v[112:113], v[114:117], off offset:32
	global_load_dwordx2 v[114:115], v[138:139], off offset:64
	s_nop 0
	global_load_dwordx2 v[116:117], v[138:139], off offset:80
	s_waitcnt vmcnt(1)
	v_lshlrev_b32_e32 v118, 16, v114
	v_and_b32_e32 v119, 0xffff0000, v114
	v_lshlrev_b32_e32 v114, 16, v115
	v_and_b32_e32 v115, 0xffff0000, v115
	v_pk_fma_f32 v[96:97], v[118:119], s[8:9], v[96:97] op_sel_hi:[1,0,1]
	v_pk_fma_f32 v[98:99], v[114:115], s[8:9], v[98:99] op_sel_hi:[1,0,1]
	v_cvt_pk_bf16_f32 v96, v96, v97
	v_cvt_pk_bf16_f32 v97, v98, v99
	s_waitcnt vmcnt(0)
	v_lshlrev_b32_e32 v98, 16, v116
	v_and_b32_e32 v99, 0xffff0000, v116
	v_pk_fma_f32 v[98:99], v[98:99], s[8:9], v[100:101] op_sel_hi:[1,0,1]
	v_lshlrev_b32_e32 v100, 16, v117
	v_and_b32_e32 v101, 0xffff0000, v117
	v_pk_fma_f32 v[100:101], v[100:101], s[8:9], v[102:103] op_sel_hi:[1,0,1]
	v_cvt_pk_bf16_f32 v98, v98, v99
	v_cvt_pk_bf16_f32 v99, v100, v101
	s_nop 0
	v_permlane32_swap_b32_e32 v96, v98
	v_permlane32_swap_b32_e32 v97, v99
	global_store_dwordx4 v[112:113], v[96:99], off offset:64
	global_load_dwordx2 v[96:97], v[138:139], off offset:96
	s_nop 0
	global_load_dwordx2 v[98:99], v[138:139], off offset:112
	s_waitcnt vmcnt(1)
	v_lshlrev_b32_e32 v100, 16, v96
	v_and_b32_e32 v101, 0xffff0000, v96
	v_pk_fma_f32 v[100:101], v[100:101], s[8:9], v[104:105] op_sel_hi:[1,0,1]
	s_nop 0
	v_cvt_pk_bf16_f32 v96, v100, v101
	v_lshlrev_b32_e32 v100, 16, v97
	v_and_b32_e32 v101, 0xffff0000, v97
	v_pk_fma_f32 v[100:101], v[100:101], s[8:9], v[106:107] op_sel_hi:[1,0,1]
	s_nop 0
	v_cvt_pk_bf16_f32 v97, v100, v101
	s_waitcnt vmcnt(0)
	v_lshlrev_b32_e32 v100, 16, v98
	v_and_b32_e32 v101, 0xffff0000, v98
	v_pk_fma_f32 v[100:101], v[100:101], s[8:9], v[108:109] op_sel_hi:[1,0,1]
	s_nop 0
	v_cvt_pk_bf16_f32 v98, v100, v101
	v_lshlrev_b32_e32 v100, 16, v99
	v_and_b32_e32 v101, 0xffff0000, v99
	v_pk_fma_f32 v[100:101], v[100:101], s[8:9], v[110:111] op_sel_hi:[1,0,1]
	v_permlane32_swap_b32_e32 v96, v98
	v_cvt_pk_bf16_f32 v99, v100, v101
	s_nop 1
	v_permlane32_swap_b32_e32 v97, v99
	global_store_dwordx4 v[112:113], v[96:99], off offset:96
	global_load_dwordx2 v[96:97], v[138:139], off offset:128
	s_nop 0
	global_load_dwordx2 v[98:99], v[138:139], off offset:144
	s_waitcnt vmcnt(1)
	v_lshlrev_b32_e32 v100, 16, v96
	v_and_b32_e32 v101, 0xffff0000, v96
	v_lshlrev_b32_e32 v96, 16, v97
	v_and_b32_e32 v97, 0xffff0000, v97
	v_pk_fma_f32 v[80:81], v[100:101], s[8:9], v[80:81] op_sel_hi:[1,0,1]
	v_pk_fma_f32 v[82:83], v[96:97], s[8:9], v[82:83] op_sel_hi:[1,0,1]
	v_cvt_pk_bf16_f32 v80, v80, v81
	v_cvt_pk_bf16_f32 v81, v82, v83
	s_waitcnt vmcnt(0)
; DI unsigned pack2(float a, float b) { f32x2_t v = {a, b}; return __builtin_bit_cast(unsigned, __builtin_convertvector(v, bf16x2_t)); }
; DI float lo2f(unsigned v) { return __uint_as_float(v << 16); }
; DI float hi2f(unsigned v) { return __uint_as_float(v & 0xffff0000u); }
;     ...
;             } else if (MODE == 1) {
; #pragma unroll
;               for (int gp = 0; gp < 2; ++gp) {
;                 const int g0 = 2 * gp;
;                 const int nb_ = nt * 256 + wn * 128 + ni * 32 + 8 * g0;
;                 const uint2 ra = *(const uint2*)(res + m * 1024 + nb_ + 4 * hh), rb = *(const uint2*)(res + m * 1024 + nb_ + 8 + 4 * hh);
;                 uint2 pa, pb;
;                 pa.x = pack2(alpha * lo2f(ra.x) + acc[mi][ni][4 * g0], alpha * hi2f(ra.x) + acc[mi][ni][4 * g0 + 1]);
;                 pa.y = pack2(alpha * lo2f(ra.y) + acc[mi][ni][4 * g0 + 2], alpha * hi2f(ra.y) + acc[mi][ni][4 * g0 + 3]);
;                 pb.x = pack2(alpha * lo2f(rb.x) + acc[mi][ni][4 * g0 + 4], alpha * hi2f(rb.x) + acc[mi][ni][4 * g0 + 5]);
;                 pb.y = pack2(alpha * lo2f(rb.y) + acc[mi][ni][4 * g0 + 6], alpha * hi2f(rb.y) + acc[mi][ni][4 * g0 + 7]);
;                 { auto rx = __builtin_amdgcn_permlane32_swap(pa.x, pb.x, false, false); pa.x = rx[0]; pb.x = rx[1]; }
;                 { auto ry = __builtin_amdgcn_permlane32_swap(pa.y, pb.y, false, false); pa.y = ry[0]; pb.y = ry[1]; }
;                 *(uint4*)(outp + m * 1024 + nb_ + 8 * hh) = make_uint4(pa.x, pa.y, pb.x, pb.y);
;               }
	v_lshlrev_b32_e32 v82, 16, v98
	v_and_b32_e32 v83, 0xffff0000, v98
	v_pk_fma_f32 v[82:83], v[82:83], s[8:9], v[84:85] op_sel_hi:[1,0,1]
	v_lshlrev_b32_e32 v84, 16, v99
	v_and_b32_e32 v85, 0xffff0000, v99
	v_pk_fma_f32 v[84:85], v[84:85], s[8:9], v[86:87] op_sel_hi:[1,0,1]
	v_cvt_pk_bf16_f32 v82, v82, v83
	v_cvt_pk_bf16_f32 v83, v84, v85
	s_nop 0
	v_permlane32_swap_b32_e32 v80, v82
	v_permlane32_swap_b32_e32 v81, v83
	global_store_dwordx4 v[112:113], v[80:83], off offset:128
	global_load_dwordx2 v[80:81], v[138:139], off offset:160
	s_nop 0
	global_load_dwordx2 v[82:83], v[138:139], off offset:176
	s_waitcnt vmcnt(1)
	v_lshlrev_b32_e32 v84, 16, v80
	v_and_b32_e32 v85, 0xffff0000, v80
	v_pk_fma_f32 v[84:85], v[84:85], s[8:9], v[88:89] op_sel_hi:[1,0,1]
	s_nop 0
	v_cvt_pk_bf16_f32 v80, v84, v85
	v_lshlrev_b32_e32 v84, 16, v81
	v_and_b32_e32 v85, 0xffff0000, v81
	v_pk_fma_f32 v[84:85], v[84:85], s[8:9], v[90:91] op_sel_hi:[1,0,1]
	s_nop 0
	v_cvt_pk_bf16_f32 v81, v84, v85
	s_waitcnt vmcnt(0)
	v_lshlrev_b32_e32 v84, 16, v82
	v_and_b32_e32 v85, 0xffff0000, v82
	v_pk_fma_f32 v[84:85], v[84:85], s[8:9], v[92:93] op_sel_hi:[1,0,1]
	s_nop 0
	v_cvt_pk_bf16_f32 v82, v84, v85
	v_lshlrev_b32_e32 v84, 16, v83
	v_and_b32_e32 v85, 0xffff0000, v83
	v_pk_fma_f32 v[84:85], v[84:85], s[8:9], v[94:95] op_sel_hi:[1,0,1]
	v_permlane32_swap_b32_e32 v80, v82
	v_cvt_pk_bf16_f32 v83, v84, v85
	s_nop 1
	v_permlane32_swap_b32_e32 v81, v83
	global_store_dwordx4 v[112:113], v[80:83], off offset:160
	global_load_dwordx2 v[80:81], v[138:139], off offset:192
	s_nop 0
	global_load_dwordx2 v[82:83], v[138:139], off offset:208
	v_or_b32_e32 v136, 0x10000, v136
	s_waitcnt vmcnt(1)
	v_lshlrev_b32_e32 v84, 16, v80
	v_and_b32_e32 v85, 0xffff0000, v80
	v_lshlrev_b32_e32 v80, 16, v81
	v_and_b32_e32 v81, 0xffff0000, v81
	v_pk_fma_f32 v[64:65], v[84:85], s[8:9], v[64:65] op_sel_hi:[1,0,1]
	v_pk_fma_f32 v[66:67], v[80:81], s[8:9], v[66:67] op_sel_hi:[1,0,1]
	v_cvt_pk_bf16_f32 v64, v64, v65
	v_cvt_pk_bf16_f32 v65, v66, v67
	s_waitcnt vmcnt(0)
	v_lshlrev_b32_e32 v66, 16, v82
	v_and_b32_e32 v67, 0xffff0000, v82
	v_pk_fma_f32 v[66:67], v[66:67], s[8:9], v[68:69] op_sel_hi:[1,0,1]
	v_lshlrev_b32_e32 v68, 16, v83
	v_and_b32_e32 v69, 0xffff0000, v83
	v_pk_fma_f32 v[68:69], v[68:69], s[8:9], v[70:71] op_sel_hi:[1,0,1]
	v_cvt_pk_bf16_f32 v66, v66, v67
	v_cvt_pk_bf16_f32 v67, v68, v69
	s_nop 0
	v_permlane32_swap_b32_e32 v64, v66
	v_permlane32_swap_b32_e32 v65, v67
	global_store_dwordx4 v[112:113], v[64:67], off offset:192
	global_load_dwordx2 v[64:65], v[138:139], off offset:224
	s_nop 0
	global_load_dwordx2 v[66:67], v[138:139], off offset:240
	v_lshl_add_u64 v[70:71], v[132:133], 0, v[136:137]
	s_waitcnt vmcnt(1)
	v_lshlrev_b32_e32 v68, 16, v64
	v_and_b32_e32 v69, 0xffff0000, v64
	v_pk_fma_f32 v[68:69], v[68:69], s[8:9], v[72:73] op_sel_hi:[1,0,1]
	s_nop 0
	v_cvt_pk_bf16_f32 v64, v68, v69
	v_lshlrev_b32_e32 v68, 16, v65
	v_and_b32_e32 v69, 0xffff0000, v65
	v_pk_fma_f32 v[68:69], v[68:69], s[8:9], v[74:75] op_sel_hi:[1,0,1]
	s_nop 0
	v_cvt_pk_bf16_f32 v65, v68, v69
	s_waitcnt vmcnt(0)
	v_lshlrev_b32_e32 v68, 16, v66
	v_and_b32_e32 v69, 0xffff0000, v66
	v_pk_fma_f32 v[68:69], v[68:69], s[8:9], v[76:77] op_sel_hi:[1,0,1]
	s_nop 0
	v_cvt_pk_bf16_f32 v66, v68, v69
	v_lshlrev_b32_e32 v68, 16, v67
	v_and_b32_e32 v69, 0xffff0000, v67
	v_pk_fma_f32 v[68:69], v[68:69], s[8:9], v[78:79] op_sel_hi:[1,0,1]
	v_permlane32_swap_b32_e32 v64, v66
	v_cvt_pk_bf16_f32 v67, v68, v69
	s_nop 1
	v_permlane32_swap_b32_e32 v65, v67
	global_store_dwordx4 v[112:113], v[64:67], off offset:224
	s_nop 1
	v_lshl_add_u64 v[64:65], s[40:41], 0, v[136:137]
	v_lshl_add_u64 v[64:65], v[64:65], 0, v[134:135]
	v_lshl_add_u64 v[64:65], v[64:65], 0, v[128:129]
	global_load_dwordx2 v[66:67], v[64:65], off
	global_load_dwordx2 v[68:69], v[64:65], off offset:16
	s_waitcnt vmcnt(1)
	v_lshlrev_b32_e32 v72, 16, v66
	v_and_b32_e32 v73, 0xffff0000, v66
	v_pk_fma_f32 v[48:49], v[72:73], s[8:9], v[48:49] op_sel_hi:[1,0,1]
	s_nop 0
	v_cvt_pk_bf16_f32 v66, v48, v49
	v_lshlrev_b32_e32 v48, 16, v67
	v_and_b32_e32 v49, 0xffff0000, v67
	v_pk_fma_f32 v[48:49], v[48:49], s[8:9], v[50:51] op_sel_hi:[1,0,1]
	s_nop 0
	v_cvt_pk_bf16_f32 v67, v48, v49
	s_waitcnt vmcnt(0)
	v_lshlrev_b32_e32 v48, 16, v68
	v_and_b32_e32 v49, 0xffff0000, v68
	v_pk_fma_f32 v[48:49], v[48:49], s[8:9], v[52:53] op_sel_hi:[1,0,1]
	s_nop 0
	v_cvt_pk_bf16_f32 v68, v48, v49
	v_lshlrev_b32_e32 v48, 16, v69
	v_and_b32_e32 v49, 0xffff0000, v69
	v_pk_fma_f32 v[48:49], v[48:49], s[8:9], v[54:55] op_sel_hi:[1,0,1]
	v_permlane32_swap_b32_e32 v66, v68
	v_cvt_pk_bf16_f32 v69, v48, v49
	s_nop 1
	v_permlane32_swap_b32_e32 v67, v69
	v_lshl_add_u64 v[48:49], v[70:71], 0, v[134:135]
	global_store_dwordx4 v[48:49], v[66:69], off
	global_load_dwordx2 v[50:51], v[64:65], off offset:32
	global_load_dwordx2 v[52:53], v[64:65], off offset:48
	s_waitcnt vmcnt(1)
	v_lshlrev_b32_e32 v54, 16, v50
	v_and_b32_e32 v55, 0xffff0000, v50
	v_pk_fma_f32 v[54:55], v[54:55], s[8:9], v[56:57] op_sel_hi:[1,0,1]
	s_nop 0
	v_cvt_pk_bf16_f32 v50, v54, v55
	v_lshlrev_b32_e32 v54, 16, v51
	v_and_b32_e32 v55, 0xffff0000, v51
	v_pk_fma_f32 v[54:55], v[54:55], s[8:9], v[58:59] op_sel_hi:[1,0,1]
	s_nop 0
	v_cvt_pk_bf16_f32 v51, v54, v55
	s_waitcnt vmcnt(0)
	v_lshlrev_b32_e32 v54, 16, v52
	v_and_b32_e32 v55, 0xffff0000, v52
	v_pk_fma_f32 v[54:55], v[54:55], s[8:9], v[60:61] op_sel_hi:[1,0,1]
	s_nop 0
	v_cvt_pk_bf16_f32 v52, v54, v55
	v_lshlrev_b32_e32 v54, 16, v53
	v_and_b32_e32 v55, 0xffff0000, v53
	v_pk_fma_f32 v[54:55], v[54:55], s[8:9], v[62:63] op_sel_hi:[1,0,1]
	v_permlane32_swap_b32_e32 v50, v52
	v_cvt_pk_bf16_f32 v53, v54, v55
	s_nop 1
	v_permlane32_swap_b32_e32 v51, v53
	global_store_dwordx4 v[48:49], v[50:53], off offset:32
	global_load_dwordx2 v[50:51], v[64:65], off offset:64
	s_nop 0
	global_load_dwordx2 v[52:53], v[64:65], off offset:80
	s_waitcnt vmcnt(1)
; DI unsigned pack2(float a, float b) { f32x2_t v = {a, b}; return __builtin_bit_cast(unsigned, __builtin_convertvector(v, bf16x2_t)); }
; DI float lo2f(unsigned v) { return __uint_as_float(v << 16); }
; DI float hi2f(unsigned v) { return __uint_as_float(v & 0xffff0000u); }
;     ...
;             } else if (MODE == 1) {
; #pragma unroll
;               for (int gp = 0; gp < 2; ++gp) {
;                 const int g0 = 2 * gp;
;                 const int nb_ = nt * 256 + wn * 128 + ni * 32 + 8 * g0;
;                 const uint2 ra = *(const uint2*)(res + m * 1024 + nb_ + 4 * hh), rb = *(const uint2*)(res + m * 1024 + nb_ + 8 + 4 * hh);
;                 uint2 pa, pb;
;                 pa.x = pack2(alpha * lo2f(ra.x) + acc[mi][ni][4 * g0], alpha * hi2f(ra.x) + acc[mi][ni][4 * g0 + 1]);
;                 pa.y = pack2(alpha * lo2f(ra.y) + acc[mi][ni][4 * g0 + 2], alpha * hi2f(ra.y) + acc[mi][ni][4 * g0 + 3]);
;                 pb.x = pack2(alpha * lo2f(rb.x) + acc[mi][ni][4 * g0 + 4], alpha * hi2f(rb.x) + acc[mi][ni][4 * g0 + 5]);
;                 pb.y = pack2(alpha * lo2f(rb.y) + acc[mi][ni][4 * g0 + 6], alpha * hi2f(rb.y) + acc[mi][ni][4 * g0 + 7]);
;                 { auto rx = __builtin_amdgcn_permlane32_swap(pa.x, pb.x, false, false); pa.x = rx[0]; pb.x = rx[1]; }
;                 { auto ry = __builtin_amdgcn_permlane32_swap(pa.y, pb.y, false, false); pa.y = ry[0]; pb.y = ry[1]; }
;                 *(uint4*)(outp + m * 1024 + nb_ + 8 * hh) = make_uint4(pa.x, pa.y, pb.x, pb.y);
;               }
;     ...
;     asm volatile("s_waitcnt lgkmcnt(0)" ::: "memory"); __builtin_amdgcn_s_barrier(); asm volatile("" ::: "memory");
;     cur ^= BUFB;
;   }
;   asm volatile("s_waitcnt vmcnt(0)" ::: "memory");
;   __syncthreads();
	v_lshlrev_b32_e32 v54, 16, v50
	v_and_b32_e32 v55, 0xffff0000, v50
	v_lshlrev_b32_e32 v50, 16, v51
	v_and_b32_e32 v51, 0xffff0000, v51
	v_pk_fma_f32 v[32:33], v[54:55], s[8:9], v[32:33] op_sel_hi:[1,0,1]
	v_pk_fma_f32 v[34:35], v[50:51], s[8:9], v[34:35] op_sel_hi:[1,0,1]
	v_cvt_pk_bf16_f32 v32, v32, v33
	v_cvt_pk_bf16_f32 v33, v34, v35
	s_waitcnt vmcnt(0)
	v_lshlrev_b32_e32 v34, 16, v52
	v_and_b32_e32 v35, 0xffff0000, v52
	v_pk_fma_f32 v[34:35], v[34:35], s[8:9], v[36:37] op_sel_hi:[1,0,1]
	v_lshlrev_b32_e32 v36, 16, v53
	v_and_b32_e32 v37, 0xffff0000, v53
	v_pk_fma_f32 v[36:37], v[36:37], s[8:9], v[38:39] op_sel_hi:[1,0,1]
	v_cvt_pk_bf16_f32 v34, v34, v35
	v_cvt_pk_bf16_f32 v35, v36, v37
	s_nop 0
	v_permlane32_swap_b32_e32 v32, v34
	v_permlane32_swap_b32_e32 v33, v35
	global_store_dwordx4 v[48:49], v[32:35], off offset:64
	global_load_dwordx2 v[32:33], v[64:65], off offset:96
	s_nop 0
	global_load_dwordx2 v[34:35], v[64:65], off offset:112
	s_waitcnt vmcnt(1)
	v_lshlrev_b32_e32 v36, 16, v32
	v_and_b32_e32 v37, 0xffff0000, v32
	v_pk_fma_f32 v[36:37], v[36:37], s[8:9], v[40:41] op_sel_hi:[1,0,1]
	s_nop 0
	v_cvt_pk_bf16_f32 v32, v36, v37
	v_lshlrev_b32_e32 v36, 16, v33
	v_and_b32_e32 v37, 0xffff0000, v33
	v_pk_fma_f32 v[36:37], v[36:37], s[8:9], v[42:43] op_sel_hi:[1,0,1]
	s_nop 0
	v_cvt_pk_bf16_f32 v33, v36, v37
	s_waitcnt vmcnt(0)
	v_lshlrev_b32_e32 v36, 16, v34
	v_and_b32_e32 v37, 0xffff0000, v34
	v_pk_fma_f32 v[36:37], v[36:37], s[8:9], v[44:45] op_sel_hi:[1,0,1]
	s_nop 0
	v_cvt_pk_bf16_f32 v34, v36, v37
	v_lshlrev_b32_e32 v36, 16, v35
	v_and_b32_e32 v37, 0xffff0000, v35
	v_pk_fma_f32 v[36:37], v[36:37], s[8:9], v[46:47] op_sel_hi:[1,0,1]
	v_permlane32_swap_b32_e32 v32, v34
	v_cvt_pk_bf16_f32 v35, v36, v37
	s_nop 1
	v_permlane32_swap_b32_e32 v33, v35
	global_store_dwordx4 v[48:49], v[32:35], off offset:96
	global_load_dwordx2 v[32:33], v[64:65], off offset:128
	s_nop 0
	global_load_dwordx2 v[34:35], v[64:65], off offset:144
	s_waitcnt vmcnt(1)
	v_lshlrev_b32_e32 v36, 16, v32
	v_and_b32_e32 v37, 0xffff0000, v32
	v_lshlrev_b32_e32 v32, 16, v33
	v_and_b32_e32 v33, 0xffff0000, v33
	v_pk_fma_f32 v[16:17], v[36:37], s[8:9], v[16:17] op_sel_hi:[1,0,1]
	v_pk_fma_f32 v[18:19], v[32:33], s[8:9], v[18:19] op_sel_hi:[1,0,1]
	v_cvt_pk_bf16_f32 v16, v16, v17
	v_cvt_pk_bf16_f32 v17, v18, v19
	s_waitcnt vmcnt(0)
	v_lshlrev_b32_e32 v18, 16, v34
	v_and_b32_e32 v19, 0xffff0000, v34
	v_pk_fma_f32 v[18:19], v[18:19], s[8:9], v[20:21] op_sel_hi:[1,0,1]
	v_lshlrev_b32_e32 v20, 16, v35
	v_and_b32_e32 v21, 0xffff0000, v35
	v_pk_fma_f32 v[20:21], v[20:21], s[8:9], v[22:23] op_sel_hi:[1,0,1]
	v_cvt_pk_bf16_f32 v18, v18, v19
	v_cvt_pk_bf16_f32 v19, v20, v21
	s_nop 0
	v_permlane32_swap_b32_e32 v16, v18
	v_permlane32_swap_b32_e32 v17, v19
	global_store_dwordx4 v[48:49], v[16:19], off offset:128
	global_load_dwordx2 v[16:17], v[64:65], off offset:160
	s_nop 0
	global_load_dwordx2 v[18:19], v[64:65], off offset:176
	s_waitcnt vmcnt(1)
	v_lshlrev_b32_e32 v20, 16, v16
	v_and_b32_e32 v21, 0xffff0000, v16
	v_pk_fma_f32 v[20:21], v[20:21], s[8:9], v[24:25] op_sel_hi:[1,0,1]
	s_nop 0
	v_cvt_pk_bf16_f32 v16, v20, v21
	v_lshlrev_b32_e32 v20, 16, v17
	v_and_b32_e32 v21, 0xffff0000, v17
	v_pk_fma_f32 v[20:21], v[20:21], s[8:9], v[26:27] op_sel_hi:[1,0,1]
	s_nop 0
	v_cvt_pk_bf16_f32 v17, v20, v21
	s_waitcnt vmcnt(0)
	v_lshlrev_b32_e32 v20, 16, v18
	v_and_b32_e32 v21, 0xffff0000, v18
	v_pk_fma_f32 v[20:21], v[20:21], s[8:9], v[28:29] op_sel_hi:[1,0,1]
	s_nop 0
	v_cvt_pk_bf16_f32 v18, v20, v21
	v_lshlrev_b32_e32 v20, 16, v19
	v_and_b32_e32 v21, 0xffff0000, v19
	v_pk_fma_f32 v[20:21], v[20:21], s[8:9], v[30:31] op_sel_hi:[1,0,1]
	v_permlane32_swap_b32_e32 v16, v18
	v_cvt_pk_bf16_f32 v19, v20, v21
	s_nop 1
	v_permlane32_swap_b32_e32 v17, v19
	global_store_dwordx4 v[48:49], v[16:19], off offset:160
	global_load_dwordx2 v[16:17], v[64:65], off offset:192
	s_nop 0
	global_load_dwordx2 v[18:19], v[64:65], off offset:208
	s_waitcnt vmcnt(1)
	v_lshlrev_b32_e32 v20, 16, v16
	v_and_b32_e32 v21, 0xffff0000, v16
	v_lshlrev_b32_e32 v16, 16, v17
	v_and_b32_e32 v17, 0xffff0000, v17
	v_pk_fma_f32 v[0:1], v[20:21], s[8:9], v[0:1] op_sel_hi:[1,0,1]
	v_pk_fma_f32 v[2:3], v[16:17], s[8:9], v[2:3] op_sel_hi:[1,0,1]
	v_cvt_pk_bf16_f32 v0, v0, v1
	v_cvt_pk_bf16_f32 v1, v2, v3
	s_waitcnt vmcnt(0)
	v_lshlrev_b32_e32 v2, 16, v18
	v_and_b32_e32 v3, 0xffff0000, v18
	v_pk_fma_f32 v[2:3], v[2:3], s[8:9], v[4:5] op_sel_hi:[1,0,1]
	v_lshlrev_b32_e32 v4, 16, v19
	v_and_b32_e32 v5, 0xffff0000, v19
	v_pk_fma_f32 v[4:5], v[4:5], s[8:9], v[6:7] op_sel_hi:[1,0,1]
	v_cvt_pk_bf16_f32 v2, v2, v3
	v_cvt_pk_bf16_f32 v3, v4, v5
	s_nop 0
	v_permlane32_swap_b32_e32 v0, v2
	v_permlane32_swap_b32_e32 v1, v3
	global_store_dwordx4 v[48:49], v[0:3], off offset:192
	global_load_dwordx2 v[0:1], v[64:65], off offset:224
	s_nop 0
	global_load_dwordx2 v[2:3], v[64:65], off offset:240
	s_waitcnt vmcnt(1)
	v_lshlrev_b32_e32 v4, 16, v0
	v_and_b32_e32 v5, 0xffff0000, v0
	v_pk_fma_f32 v[4:5], v[4:5], s[8:9], v[8:9] op_sel_hi:[1,0,1]
	s_nop 0
	v_cvt_pk_bf16_f32 v0, v4, v5
	v_lshlrev_b32_e32 v4, 16, v1
	v_and_b32_e32 v5, 0xffff0000, v1
	v_pk_fma_f32 v[4:5], v[4:5], s[8:9], v[10:11] op_sel_hi:[1,0,1]
	s_nop 0
	v_cvt_pk_bf16_f32 v1, v4, v5
	s_waitcnt vmcnt(0)
	v_lshlrev_b32_e32 v4, 16, v2
	v_and_b32_e32 v5, 0xffff0000, v2
	v_pk_fma_f32 v[4:5], v[4:5], s[8:9], v[12:13] op_sel_hi:[1,0,1]
	s_nop 0
	v_cvt_pk_bf16_f32 v2, v4, v5
	v_lshlrev_b32_e32 v4, 16, v3
	v_and_b32_e32 v5, 0xffff0000, v3
	v_pk_fma_f32 v[4:5], v[4:5], s[8:9], v[14:15] op_sel_hi:[1,0,1]
	v_permlane32_swap_b32_e32 v0, v2
	v_cvt_pk_bf16_f32 v3, v4, v5
	s_nop 1
	v_permlane32_swap_b32_e32 v1, v3
	global_store_dwordx4 v[48:49], v[0:3], off offset:224
	s_waitcnt lgkmcnt(0)
	s_barrier
	s_waitcnt vmcnt(0)
	s_barrier

; #define MFMA(a, b, c) __builtin_amdgcn_mfma_f32_32x32x16_bf16((a), (b), (c), 0, 0, 0)
;     ...
;   for (int s = 0; s < S; ++s) {
;     G_DMA(s + 1, cur ^ BUFB);
;     {
;       const char* Ab = smem + cur + fA;
;       const char* Bb = smem + cur + fB;
;       __builtin_amdgcn_sched_barrier(0);
; #pragma unroll
;       for (int kk = 0; kk < 4; ++kk) {
;         const int ko = (((kk * 2 + hh) ^ fsw) << 4);
;         bf16x8 af[2], wf[4];
;         af[0] = *(const bf16x8*)(Ab + ko); af[1] = *(const bf16x8*)(Ab + 4096 + ko);
; #pragma unroll
;         for (int ni = 0; ni < 4; ++ni) wf[ni] = *(const bf16x8*)(Bb + ni * 4096 + ko);
; #pragma unroll
;         for (int mi = 0; mi < 2; ++mi)
; #pragma unroll
;           for (int ni = 0; ni < 4; ++ni) acc[mi][ni] = MFMA(wf[ni], af[mi], acc[mi][ni]);
;         if (kk == 1) __builtin_amdgcn_sched_barrier(0);
;       }
;       __builtin_amdgcn_sched_barrier(0);
;     }
;     asm volatile("s_waitcnt vmcnt(0)" ::: "memory");
.LBB0_1293:
	s_add_i32 s44, s8, 1
	s_mov_b32 s9, s23
	s_cmp_lt_u32 s44, s46
	v_readlane_b32 s23, v252, 57
	s_cselect_b32 s23, s44, s23
	s_lshl_b32 s24, s23, 1
	s_andn2_b32 s24, s24, 31
	s_add_i32 s24, s24, s33
	s_lshr_b32 s24, s24, 3
	s_and_b32 s25, s24, 4
	s_or_b32 s25, s25, s47
	s_and_b32 s24, s24, 0xfffff8
	s_or_b32 s28, s24, s74
	s_lshl_b32 s24, s25, 19
	s_add_u32 s24, s7, s24
	s_addc_u32 s25, s22, 0
	s_lshl_b32 s23, s23, 7
	s_and_b32 s45, s23, 0x780
	s_add_u32 s24, s24, s45
	s_addc_u32 s25, s25, 0
	s_lshl_b32 s40, s28, 8
	s_ashr_i32 s41, s40, 31
	s_lshl_b64 s[40:41], s[40:41], 11
	s_add_u32 s28, s72, s40
	s_addc_u32 s40, s73, s41
	s_xor_b32 s23, s9, 0x10000
	v_add_u32_e32 v128, s23, v140
	v_lshl_add_u64 v[136:137], s[24:25], 0, v[132:133]
	v_readfirstlane_b32 s24, v128
	v_add_u32_e32 v148, 0x2000, v128
	s_mov_b32 m0, s24
	s_mov_b64 s[48:49], 0x20000
	v_readfirstlane_b32 s24, v148
	v_add_u32_e32 v148, 0x4000, v128
	global_load_lds_dwordx4 v[136:137], off
	s_add_i32 s9, s9, 0
	v_add3_u32 v187, s9, v131, v138
	v_add3_u32 v208, s9, v139, v138
	v_add_u32_e32 v182, v208, v142
	v_add_u32_e32 v183, v187, v142
	ds_read_b128 v[192:195], v182 offset:32768
	ds_read_b128 v[216:219], v183
	ds_read_b128 v[196:199], v182 offset:36864
	ds_read_b128 v[200:203], v182 offset:40960
	ds_read_b128 v[204:207], v182 offset:45056
	ds_read_b128 v[220:223], v183 offset:4096
	v_add_u32_e32 v184, v208, v143
	v_add_u32_e32 v185, v187, v143
	ds_read_b128 v[224:227], v184 offset:32768
	ds_read_b128 v[240:243], v185
	ds_read_b128 v[228:231], v184 offset:36864
	ds_read_b128 v[232:235], v184 offset:40960
	ds_read_b128 v[236:239], v184 offset:45056
	ds_read_b128 v[244:247], v185 offset:4096
	s_waitcnt lgkmcnt(10)
	v_mfma_f32_32x32x16_bf16 v[112:127], v[192:195], v[216:219], v[112:127]
	s_waitcnt lgkmcnt(9)
	v_mfma_f32_32x32x16_bf16 v[96:111], v[196:199], v[216:219], v[96:111]
	v_lshl_add_u64 v[146:147], v[136:137], 0, s[48:49]
	s_mov_b32 m0, s24
	s_mov_b64 s[50:51], 0x40000
	v_readfirstlane_b32 s24, v148
	global_load_lds_dwordx4 v[146:147], off
	s_waitcnt lgkmcnt(8)
	v_mfma_f32_32x32x16_bf16 v[80:95], v[200:203], v[216:219], v[80:95]
	s_waitcnt lgkmcnt(7)
	v_mfma_f32_32x32x16_bf16 v[64:79], v[204:207], v[216:219], v[64:79]
	v_lshl_add_u64 v[146:147], v[136:137], 0, s[50:51]
	s_mov_b32 m0, s24
	s_mov_b64 s[52:53], 0x60000
	global_load_lds_dwordx4 v[146:147], off
	s_waitcnt lgkmcnt(6)
	v_mfma_f32_32x32x16_bf16 v[48:63], v[192:195], v[220:223], v[48:63]
	v_mfma_f32_32x32x16_bf16 v[32:47], v[196:199], v[220:223], v[32:47]
	v_add_u32_e32 v146, 0x6000, v128
	v_lshl_add_u64 v[136:137], v[136:137], 0, s[52:53]
	v_readfirstlane_b32 s24, v146
	s_mov_b32 m0, s24
	s_add_u32 s24, s28, s45
	s_addc_u32 s25, s40, 0
	v_add_u32_e32 v146, 0x8000, v128
	global_load_lds_dwordx4 v[136:137], off
	v_mfma_f32_32x32x16_bf16 v[16:31], v[200:203], v[220:223], v[16:31]
	v_mfma_f32_32x32x16_bf16 v[0:15], v[204:207], v[220:223], v[0:15]
	v_lshl_add_u64 v[136:137], s[24:25], 0, v[132:133]
	v_readfirstlane_b32 s24, v146
	v_add_u32_e32 v148, 0xa000, v128
	s_mov_b32 m0, s24
	v_readfirstlane_b32 s24, v148
	v_add_u32_e32 v148, 0xc000, v128
	global_load_lds_dwordx4 v[136:137], off
	v_add_u32_e32 v182, v208, v144
	v_add_u32_e32 v183, v187, v144
	ds_read_b128 v[192:195], v182 offset:32768
	ds_read_b128 v[216:219], v183
	ds_read_b128 v[196:199], v182 offset:36864
	ds_read_b128 v[200:203], v182 offset:40960
	ds_read_b128 v[204:207], v182 offset:45056
	ds_read_b128 v[220:223], v183 offset:4096
	s_waitcnt lgkmcnt(10)
	v_mfma_f32_32x32x16_bf16 v[112:127], v[224:227], v[240:243], v[112:127]
	s_waitcnt lgkmcnt(9)
	v_mfma_f32_32x32x16_bf16 v[96:111], v[228:231], v[240:243], v[96:111]
	v_lshl_add_u64 v[146:147], v[136:137], 0, s[48:49]
	s_mov_b32 m0, s24
	v_readfirstlane_b32 s24, v148
	v_add_u32_e32 v128, 0xe000, v128
	global_load_lds_dwordx4 v[146:147], off
	s_waitcnt lgkmcnt(8)
	v_mfma_f32_32x32x16_bf16 v[80:95], v[232:235], v[240:243], v[80:95]
	s_waitcnt lgkmcnt(7)
	v_mfma_f32_32x32x16_bf16 v[64:79], v[236:239], v[240:243], v[64:79]
	v_lshl_add_u64 v[146:147], v[136:137], 0, s[50:51]
	s_mov_b32 m0, s24
	v_readfirstlane_b32 s24, v128
	global_load_lds_dwordx4 v[146:147], off
	s_waitcnt lgkmcnt(6)
	v_mfma_f32_32x32x16_bf16 v[48:63], v[224:227], v[244:247], v[48:63]
	v_mfma_f32_32x32x16_bf16 v[32:47], v[228:231], v[244:247], v[32:47]
	v_lshl_add_u64 v[136:137], v[136:137], 0, s[52:53]
	s_mov_b32 m0, s24
	s_mov_b64 s[48:49], 0x40000
	global_load_lds_dwordx4 v[136:137], off
	v_mfma_f32_32x32x16_bf16 v[16:31], v[232:235], v[244:247], v[16:31]
	v_mfma_f32_32x32x16_bf16 v[0:15], v[236:239], v[244:247], v[0:15]
	v_add_u32_e32 v184, v208, v145
	v_add_u32_e32 v185, v187, v145
	ds_read_b128 v[224:227], v184 offset:32768
	ds_read_b128 v[240:243], v185
	ds_read_b128 v[228:231], v184 offset:36864
	ds_read_b128 v[232:235], v184 offset:40960
	ds_read_b128 v[236:239], v184 offset:45056
	ds_read_b128 v[244:247], v185 offset:4096
	s_waitcnt lgkmcnt(10)
	v_mfma_f32_32x32x16_bf16 v[112:127], v[192:195], v[216:219], v[112:127]
	s_waitcnt lgkmcnt(9)
	v_mfma_f32_32x32x16_bf16 v[96:111], v[196:199], v[216:219], v[96:111]
	s_waitcnt lgkmcnt(8)
	v_mfma_f32_32x32x16_bf16 v[80:95], v[200:203], v[216:219], v[80:95]
	s_waitcnt lgkmcnt(7)
	v_mfma_f32_32x32x16_bf16 v[64:79], v[204:207], v[216:219], v[64:79]
	s_waitcnt lgkmcnt(6)
	v_mfma_f32_32x32x16_bf16 v[48:63], v[192:195], v[220:223], v[48:63]
	v_mfma_f32_32x32x16_bf16 v[32:47], v[196:199], v[220:223], v[32:47]
	v_mfma_f32_32x32x16_bf16 v[16:31], v[200:203], v[220:223], v[16:31]
	v_mfma_f32_32x32x16_bf16 v[0:15], v[204:207], v[220:223], v[0:15]
	s_waitcnt lgkmcnt(4)
	v_mfma_f32_32x32x16_bf16 v[112:127], v[224:227], v[240:243], v[112:127]
	s_waitcnt lgkmcnt(3)
	v_mfma_f32_32x32x16_bf16 v[96:111], v[228:231], v[240:243], v[96:111]
	s_waitcnt lgkmcnt(2)
	v_mfma_f32_32x32x16_bf16 v[80:95], v[232:235], v[240:243], v[80:95]
	s_waitcnt lgkmcnt(1)
	v_mfma_f32_32x32x16_bf16 v[64:79], v[236:239], v[240:243], v[64:79]
	s_waitcnt lgkmcnt(0)
	v_mfma_f32_32x32x16_bf16 v[48:63], v[224:227], v[244:247], v[48:63]
	v_mfma_f32_32x32x16_bf16 v[32:47], v[228:231], v[244:247], v[32:47]
	v_mfma_f32_32x32x16_bf16 v[16:31], v[232:235], v[244:247], v[16:31]
	v_mfma_f32_32x32x16_bf16 v[0:15], v[236:239], v[244:247], v[0:15]
	s_waitcnt vmcnt(0)
	s_and_b32 s9, s8, 15
	s_cmp_lg_u32 s9, 15
	s_cbranch_scc1 .LBB0_1292
; DI unsigned pack2(float a, float b) { f32x2_t v = {a, b}; return __builtin_bit_cast(unsigned, __builtin_convertvector(v, bf16x2_t)); }
; #define G_TILEMAP(q, MT, NT) do { if (sq) { const int grp_ = (q) >> 5, i_ = (q) & 31; \
;       MT = xcd * mpx + (grp_ & (mpx / 4 - 1)) * 4 + (i_ & 3); NT = (grp_ >> (LMPX - 2)) * 8 + (i_ >> 2); } \
;     else { MT = xcd * mpx + ((q) & (mpx - 1)); NT = (q) >> LMPX; } } while (0)
;     ...
;     if ((s & (nk - 1)) == nk - 1) {
;       const int q = slot + (s >> lnk) * nslots;
;       int mt, nt; G_TILEMAP(q, mt, nt);
;       if (dostore) {
; #pragma unroll
;         for (int mi = 0; mi < 2; ++mi) {
;           const size_t m = (size_t)mt * 256 + wm * 64 + mi * 32 + r;
; #pragma unroll
;           for (int ni = 0; ni < 4; ++ni) {
;             __builtin_amdgcn_sched_barrier(0);
;             if (MODE == 0) {
; #pragma unroll
;               for (int gp = 0; gp < 2; ++gp) {
;                 const int g0 = 2 * gp;
;                 uint2 pa, pb;
;                 pa.x = pack2(acc[mi][ni][4 * g0], acc[mi][ni][4 * g0 + 1]); pa.y = pack2(acc[mi][ni][4 * g0 + 2], acc[mi][ni][4 * g0 + 3]);
;                 pb.x = pack2(acc[mi][ni][4 * g0 + 4], acc[mi][ni][4 * g0 + 5]); pb.y = pack2(acc[mi][ni][4 * g0 + 6], acc[mi][ni][4 * g0 + 7]);
;                 { auto rx = __builtin_amdgcn_permlane32_swap(pa.x, pb.x, false, false); pa.x = rx[0]; pb.x = rx[1]; }
;                 { auto ry = __builtin_amdgcn_permlane32_swap(pa.y, pb.y, false, false); pa.y = ry[0]; pb.y = ry[1]; }
;                 const int col = nt * 256 + wn * 128 + ni * 32 + 8 * g0 + 8 * hh;
;                 const uint4 v4 = make_uint4(pa.x, pa.y, pb.x, pb.y);
;                 if (outp != nullptr && nt >= 32) *(uint4*)(outp + m * 2048 + (col - 8192)) = v4;
;                 else if (col < nvalid) *(uint4*)(C + m * ldc + col) = v4;
	s_lshl_b32 s8, s8, 1
	s_and_b32 s8, s8, 0x7fffffe0
	s_add_i32 s8, s8, s33
	s_lshr_b32 s8, s8, 3
	s_and_b32 s9, s8, 4
	s_or_b32 s9, s9, s47
	s_and_b32 s8, s8, 0xfffff8
	s_lshl_b32 s28, s9, 8
	s_or_b32 s8, s8, s74
	v_lshl_add_u64 v[136:137], v[134:135], 0, s[28:29]
	s_lshl_b32 s8, s8, 8
	v_lshlrev_b64 v[136:137], 13, v[136:137]
	v_or_b32_e32 v128, s8, v141
	v_lshl_add_u64 v[136:137], s[58:59], 0, v[136:137]
	v_cvt_pk_bf16_f32 v112, v112, v113
	v_cvt_pk_bf16_f32 v113, v114, v115
	v_cvt_pk_bf16_f32 v114, v116, v117
	v_cvt_pk_bf16_f32 v115, v118, v119
	s_cmp_lt_u32 s8, 2.0
	v_permlane32_swap_b32_e32 v112, v114
	s_cselect_b64 s[24:25], -1, 0
	s_cmp_gt_u32 s8, 0x3fffffff
	v_permlane32_swap_b32_e32 v113, v115
	s_cbranch_scc1 .LBB0_1296
	v_lshl_add_u64 v[116:117], v[128:129], 1, v[136:137]
	global_store_dwordx4 v[116:117], v[112:115], off
